# speedup vs baseline: 1.0035x; 1.0012x over previous
; #define LDA(dst, b, h)                                                                                     \
;   _Pragma("unroll") for (int m = 0; m < 4; ++m) _Pragma("unroll") for (int k = 0; k < 2; ++k) dst[m][k] = \
;       *reinterpret_cast<const bf16x8*>(shmc + aL + (((b) * 2 + (h)) * 16384 + (m * 2 + k) * 1024))
; #define LDB(dst, b, h)                                                                                     \
;   _Pragma("unroll") for (int n = 0; n < 2; ++n) _Pragma("unroll") for (int k = 0; k < 2; ++k) dst[n][k] = \
;       *reinterpret_cast<const bf16x8*>(shmc + bL + (((b) * 2 + (h)) * 16384 + (n * 2 + k) * 1024))
; #define OPAQ asm volatile("" : "+v"(aL), "+v"(bL))
; #define WAIT_V(n) asm volatile("s_waitcnt vmcnt(" #n ")" ::: "memory")
; #define WAIT_L(n) asm volatile("s_waitcnt lgkmcnt(" #n ")" ::: "memory")
; #define BAR __builtin_amdgcn_s_barrier()
; #define SCHED __builtin_amdgcn_sched_barrier(0)
; template <int EPI>
; __device__ __forceinline__ void phase_gemm(const Params& p, const GemmDesc& d, char* shmc) {
;     ...
;     for (int t = 0; t < nt - 2; t += 2) {
;       OPAQ;
;       LDB(B0, 0, 0); SCHED; LDA(At, 0, 0); STAGE_A(SA(1, 1), 1, t + 1);
;       WAIT_L(8); BAR; WAIT_L(0); MMA(0, 0, At, B0); BAR; SCHED;
;       LDB(B1, 0, 1); STAGE_B(SB(0, 0), 0, t + 2);
;       BAR; WAIT_L(0); MMA(0, 1, At, B1); BAR;
;       LDA(At, 0, 1); STAGE_A(SA(0, 0), 0, t + 2);
;       BAR; WAIT_L(0); MMA(1, 0, At, B0); BAR; SCHED;
;       STAGE_B(SB(0, 1), 1, t + 2);
;       WAIT_V(6); BAR; MMA(1, 1, At, B1); BAR;
;       LDB(B0, 1, 0); SCHED; LDA(At, 1, 0); STAGE_A(SA(0, 1), 1, t + 2);
;       WAIT_L(8); BAR; WAIT_L(0); MMA(0, 0, At, B0); BAR; SCHED;
;       LDB(B1, 1, 1); STAGE_B(SB(1, 0), 0, t + 3);
;       BAR; WAIT_L(0); MMA(0, 1, At, B1); BAR;
;       LDA(At, 1, 1); STAGE_A(SA(1, 0), 0, t + 3);
;       BAR; WAIT_L(0); MMA(1, 0, At, B0); BAR; SCHED;
;       STAGE_B(SB(1, 1), 1, t + 3);
;       WAIT_V(6); BAR; MMA(1, 1, At, B1); BAR;
;     }
.LBB0_296:
	s_nop 0
	v_add_u32_e32 v162, 0, v205
	v_add_u32_e32 v175, 0, v204
	s_setprio 0
	ds_read_b128 v[138:141], v162
	ds_read_b128 v[142:145], v162 offset:1024
	ds_read_b128 v[146:149], v162 offset:2048
	ds_read_b128 v[150:153], v162 offset:3072
	ds_read_b128 v[208:211], v162 offset:16384
	ds_read_b128 v[212:215], v162 offset:17408
	ds_read_b128 v[216:219], v162 offset:18432
	ds_read_b128 v[220:223], v162 offset:19456
	ds_read_b128 v[154:157], v175
	ds_read_b128 v[158:161], v175 offset:1024
	ds_read_b128 v[178:181], v175 offset:2048
	ds_read_b128 v[182:185], v175 offset:3072
	ds_read_b128 v[186:189], v175 offset:4096
	ds_read_b128 v[190:193], v175 offset:5120
	ds_read_b128 v[194:197], v175 offset:6144
	ds_read_b128 v[198:201], v175 offset:7168
	s_mov_b32 m0, s93
	s_nop 0
	global_load_lds_dwordx4 v202, s[98:99]
	s_mov_b32 m0, s94
	s_nop 0
	global_load_lds_dwordx4 v203, s[98:99]
	s_waitcnt vmcnt(8)
	s_waitcnt lgkmcnt(0)
	s_setprio 1
	s_barrier
	v_mfma_f32_16x16x32_bf16 v[2:5], v[154:157], v[138:141], v[2:5]
	v_mfma_f32_16x16x32_bf16 v[6:9], v[154:157], v[146:149], v[6:9]
	v_mfma_f32_16x16x32_bf16 v[18:21], v[178:181], v[146:149], v[18:21]
	v_mfma_f32_16x16x32_bf16 v[10:13], v[178:181], v[138:141], v[10:13]
	v_mfma_f32_16x16x32_bf16 v[30:33], v[186:189], v[138:141], v[30:33]
	v_mfma_f32_16x16x32_bf16 v[42:45], v[186:189], v[146:149], v[42:45]
	v_mfma_f32_16x16x32_bf16 v[66:69], v[194:197], v[146:149], v[66:69]
	v_mfma_f32_16x16x32_bf16 v[54:57], v[194:197], v[138:141], v[54:57]
	v_mfma_f32_16x16x32_bf16 v[2:5], v[158:161], v[142:145], v[2:5]
	v_mfma_f32_16x16x32_bf16 v[6:9], v[158:161], v[150:153], v[6:9]
	v_mfma_f32_16x16x32_bf16 v[18:21], v[182:185], v[150:153], v[18:21]
	v_mfma_f32_16x16x32_bf16 v[10:13], v[182:185], v[142:145], v[10:13]
	v_mfma_f32_16x16x32_bf16 v[30:33], v[190:193], v[142:145], v[30:33]
	v_mfma_f32_16x16x32_bf16 v[42:45], v[190:193], v[150:153], v[42:45]
	v_mfma_f32_16x16x32_bf16 v[66:69], v[198:201], v[150:153], v[66:69]
	v_mfma_f32_16x16x32_bf16 v[54:57], v[198:201], v[142:145], v[54:57]
	v_mfma_f32_16x16x32_bf16 v[14:17], v[154:157], v[208:211], v[14:17]
	v_mfma_f32_16x16x32_bf16 v[22:25], v[154:157], v[216:219], v[22:25]
	v_mfma_f32_16x16x32_bf16 v[46:49], v[178:181], v[216:219], v[46:49]
	v_mfma_f32_16x16x32_bf16 v[34:37], v[178:181], v[208:211], v[34:37]
	v_mfma_f32_16x16x32_bf16 v[58:61], v[186:189], v[208:211], v[58:61]
	v_mfma_f32_16x16x32_bf16 v[70:73], v[186:189], v[216:219], v[70:73]
	v_mfma_f32_16x16x32_bf16 v[86:89], v[194:197], v[216:219], v[86:89]
	v_mfma_f32_16x16x32_bf16 v[78:81], v[194:197], v[208:211], v[78:81]
	v_mfma_f32_16x16x32_bf16 v[14:17], v[158:161], v[212:215], v[14:17]
	v_mfma_f32_16x16x32_bf16 v[22:25], v[158:161], v[220:223], v[22:25]
	v_mfma_f32_16x16x32_bf16 v[46:49], v[182:185], v[220:223], v[46:49]
	v_mfma_f32_16x16x32_bf16 v[34:37], v[182:185], v[212:215], v[34:37]
	v_mfma_f32_16x16x32_bf16 v[58:61], v[190:193], v[212:215], v[58:61]
	v_mfma_f32_16x16x32_bf16 v[70:73], v[190:193], v[220:223], v[70:73]
	v_mfma_f32_16x16x32_bf16 v[86:89], v[198:201], v[220:223], v[86:89]
	v_mfma_f32_16x16x32_bf16 v[78:81], v[198:201], v[212:215], v[78:81]
	s_barrier
	s_setprio 0
	ds_read_b128 v[154:157], v175 offset:16384
	ds_read_b128 v[158:161], v175 offset:17408
	ds_read_b128 v[178:181], v175 offset:18432
	ds_read_b128 v[182:185], v175 offset:19456
	ds_read_b128 v[186:189], v175 offset:20480
	ds_read_b128 v[190:193], v175 offset:21504
	ds_read_b128 v[194:197], v175 offset:22528
	ds_read_b128 v[198:201], v175 offset:23552
	s_mov_b32 m0, s80
	s_nop 0
	global_load_lds_dwordx4 v224, s[100:101]
	s_mov_b32 m0, s81
	s_nop 0
	global_load_lds_dwordx4 v225, s[100:101]
	s_mov_b32 m0, s77
	s_nop 0
	global_load_lds_dwordx4 v226, s[98:99]
	s_mov_b32 m0, s82
	s_nop 0
	global_load_lds_dwordx4 v227, s[98:99]
	s_mov_b32 m0, s83
	s_nop 0
	global_load_lds_dwordx4 v228, s[100:101]
	s_mov_b32 m0, s84
	s_nop 0
	global_load_lds_dwordx4 v229, s[100:101]
	s_waitcnt vmcnt(8)
	s_waitcnt lgkmcnt(0)
	s_setprio 1
	s_barrier
	v_mfma_f32_16x16x32_bf16 v[26:29], v[154:157], v[138:141], v[26:29]
	v_mfma_f32_16x16x32_bf16 v[38:41], v[154:157], v[146:149], v[38:41]
	v_mfma_f32_16x16x32_bf16 v[62:65], v[178:181], v[146:149], v[62:65]
	v_mfma_f32_16x16x32_bf16 v[50:53], v[178:181], v[138:141], v[50:53]
	v_mfma_f32_16x16x32_bf16 v[74:77], v[186:189], v[138:141], v[74:77]
	v_mfma_f32_16x16x32_bf16 v[82:85], v[186:189], v[146:149], v[82:85]
	v_mfma_f32_16x16x32_bf16 v[94:97], v[194:197], v[146:149], v[94:97]
	v_mfma_f32_16x16x32_bf16 v[90:93], v[194:197], v[138:141], v[90:93]
	v_mfma_f32_16x16x32_bf16 v[26:29], v[158:161], v[142:145], v[26:29]
	v_mfma_f32_16x16x32_bf16 v[38:41], v[158:161], v[150:153], v[38:41]
	v_mfma_f32_16x16x32_bf16 v[62:65], v[182:185], v[150:153], v[62:65]
	v_mfma_f32_16x16x32_bf16 v[50:53], v[182:185], v[142:145], v[50:53]
	v_mfma_f32_16x16x32_bf16 v[74:77], v[190:193], v[142:145], v[74:77]
	v_mfma_f32_16x16x32_bf16 v[82:85], v[190:193], v[150:153], v[82:85]
	v_mfma_f32_16x16x32_bf16 v[94:97], v[198:201], v[150:153], v[94:97]
	v_mfma_f32_16x16x32_bf16 v[90:93], v[198:201], v[142:145], v[90:93]
	v_mfma_f32_16x16x32_bf16 v[98:101], v[154:157], v[208:211], v[98:101]
	v_mfma_f32_16x16x32_bf16 v[102:105], v[154:157], v[216:219], v[102:105]
	v_mfma_f32_16x16x32_bf16 v[110:113], v[178:181], v[216:219], v[110:113]
	v_mfma_f32_16x16x32_bf16 v[106:109], v[178:181], v[208:211], v[106:109]
	v_mfma_f32_16x16x32_bf16 v[114:117], v[186:189], v[208:211], v[114:117]
	v_mfma_f32_16x16x32_bf16 v[118:121], v[186:189], v[216:219], v[118:121]
	v_mfma_f32_16x16x32_bf16 v[126:129], v[194:197], v[216:219], v[126:129]
	v_mfma_f32_16x16x32_bf16 v[122:125], v[194:197], v[208:211], v[122:125]
	v_mfma_f32_16x16x32_bf16 v[98:101], v[158:161], v[212:215], v[98:101]
	v_mfma_f32_16x16x32_bf16 v[102:105], v[158:161], v[220:223], v[102:105]
	v_mfma_f32_16x16x32_bf16 v[110:113], v[182:185], v[220:223], v[110:113]
	v_mfma_f32_16x16x32_bf16 v[106:109], v[182:185], v[212:215], v[106:109]
	v_mfma_f32_16x16x32_bf16 v[114:117], v[190:193], v[212:215], v[114:117]
	v_mfma_f32_16x16x32_bf16 v[118:121], v[190:193], v[220:223], v[118:121]
	v_mfma_f32_16x16x32_bf16 v[126:129], v[198:201], v[220:223], v[126:129]
	v_mfma_f32_16x16x32_bf16 v[122:125], v[198:201], v[212:215], v[122:125]
	s_barrier
; #define LDA(dst, b, h)                                                                                     \
;   _Pragma("unroll") for (int m = 0; m < 4; ++m) _Pragma("unroll") for (int k = 0; k < 2; ++k) dst[m][k] = \
;       *reinterpret_cast<const bf16x8*>(shmc + aL + (((b) * 2 + (h)) * 16384 + (m * 2 + k) * 1024))
; #define LDB(dst, b, h)                                                                                     \
;   _Pragma("unroll") for (int n = 0; n < 2; ++n) _Pragma("unroll") for (int k = 0; k < 2; ++k) dst[n][k] = \
;       *reinterpret_cast<const bf16x8*>(shmc + bL + (((b) * 2 + (h)) * 16384 + (n * 2 + k) * 1024))
; #define OPAQ asm volatile("" : "+v"(aL), "+v"(bL))
; #define WAIT_V(n) asm volatile("s_waitcnt vmcnt(" #n ")" ::: "memory")
; #define WAIT_L(n) asm volatile("s_waitcnt lgkmcnt(" #n ")" ::: "memory")
; #define BAR __builtin_amdgcn_s_barrier()
; #define SCHED __builtin_amdgcn_sched_barrier(0)
; template <int EPI>
; __device__ __forceinline__ void phase_gemm(const Params& p, const GemmDesc& d, char* shmc) {
;     ...
;     for (int t = 0; t < nt - 2; t += 2) {
;       OPAQ;
;       LDB(B0, 0, 0); SCHED; LDA(At, 0, 0); STAGE_A(SA(1, 1), 1, t + 1);
;       WAIT_L(8); BAR; WAIT_L(0); MMA(0, 0, At, B0); BAR; SCHED;
;       LDB(B1, 0, 1); STAGE_B(SB(0, 0), 0, t + 2);
;       BAR; WAIT_L(0); MMA(0, 1, At, B1); BAR;
;       LDA(At, 0, 1); STAGE_A(SA(0, 0), 0, t + 2);
;       BAR; WAIT_L(0); MMA(1, 0, At, B0); BAR; SCHED;
;       STAGE_B(SB(0, 1), 1, t + 2);
;       WAIT_V(6); BAR; MMA(1, 1, At, B1); BAR;
;       LDB(B0, 1, 0); SCHED; LDA(At, 1, 0); STAGE_A(SA(0, 1), 1, t + 2);
;       WAIT_L(8); BAR; WAIT_L(0); MMA(0, 0, At, B0); BAR; SCHED;
;       LDB(B1, 1, 1); STAGE_B(SB(1, 0), 0, t + 3);
;       BAR; WAIT_L(0); MMA(0, 1, At, B1); BAR;
;       LDA(At, 1, 1); STAGE_A(SA(1, 0), 0, t + 3);
;       BAR; WAIT_L(0); MMA(1, 0, At, B0); BAR; SCHED;
;       STAGE_B(SB(1, 1), 1, t + 3);
;       WAIT_V(6); BAR; MMA(1, 1, At, B1); BAR;
;     }
	s_setprio 0
	ds_read_b128 v[138:141], v162 offset:32768
	ds_read_b128 v[142:145], v162 offset:33792
	ds_read_b128 v[146:149], v162 offset:34816
	ds_read_b128 v[150:153], v162 offset:35840
	ds_read_b128 v[208:211], v162 offset:49152
	ds_read_b128 v[212:215], v162 offset:50176
	ds_read_b128 v[216:219], v162 offset:51200
	ds_read_b128 v[220:223], v162 offset:52224
	ds_read_b128 v[154:157], v175 offset:32768
	ds_read_b128 v[158:161], v175 offset:33792
	ds_read_b128 v[178:181], v175 offset:34816
	ds_read_b128 v[182:185], v175 offset:35840
	ds_read_b128 v[186:189], v175 offset:36864
	ds_read_b128 v[190:193], v175 offset:37888
	ds_read_b128 v[194:197], v175 offset:38912
	ds_read_b128 v[198:201], v175 offset:39936
	s_mov_b32 m0, s85
	s_nop 0
	global_load_lds_dwordx4 v230, s[98:99]
	s_mov_b32 m0, s86
	s_nop 0
	global_load_lds_dwordx4 v231, s[98:99]
	s_waitcnt vmcnt(8)
	s_waitcnt lgkmcnt(0)
	s_setprio 1
	s_barrier
	v_mfma_f32_16x16x32_bf16 v[2:5], v[154:157], v[138:141], v[2:5]
	v_mfma_f32_16x16x32_bf16 v[6:9], v[154:157], v[146:149], v[6:9]
	v_mfma_f32_16x16x32_bf16 v[18:21], v[178:181], v[146:149], v[18:21]
	v_mfma_f32_16x16x32_bf16 v[10:13], v[178:181], v[138:141], v[10:13]
	v_mfma_f32_16x16x32_bf16 v[30:33], v[186:189], v[138:141], v[30:33]
	v_mfma_f32_16x16x32_bf16 v[42:45], v[186:189], v[146:149], v[42:45]
	v_mfma_f32_16x16x32_bf16 v[66:69], v[194:197], v[146:149], v[66:69]
	v_mfma_f32_16x16x32_bf16 v[54:57], v[194:197], v[138:141], v[54:57]
	v_mfma_f32_16x16x32_bf16 v[2:5], v[158:161], v[142:145], v[2:5]
	v_mfma_f32_16x16x32_bf16 v[6:9], v[158:161], v[150:153], v[6:9]
	v_mfma_f32_16x16x32_bf16 v[18:21], v[182:185], v[150:153], v[18:21]
	v_mfma_f32_16x16x32_bf16 v[10:13], v[182:185], v[142:145], v[10:13]
	v_mfma_f32_16x16x32_bf16 v[30:33], v[190:193], v[142:145], v[30:33]
	v_mfma_f32_16x16x32_bf16 v[42:45], v[190:193], v[150:153], v[42:45]
	v_mfma_f32_16x16x32_bf16 v[66:69], v[198:201], v[150:153], v[66:69]
	v_mfma_f32_16x16x32_bf16 v[54:57], v[198:201], v[142:145], v[54:57]
	v_mfma_f32_16x16x32_bf16 v[14:17], v[154:157], v[208:211], v[14:17]
	v_mfma_f32_16x16x32_bf16 v[22:25], v[154:157], v[216:219], v[22:25]
	v_mfma_f32_16x16x32_bf16 v[46:49], v[178:181], v[216:219], v[46:49]
	v_mfma_f32_16x16x32_bf16 v[34:37], v[178:181], v[208:211], v[34:37]
	v_mfma_f32_16x16x32_bf16 v[58:61], v[186:189], v[208:211], v[58:61]
	v_mfma_f32_16x16x32_bf16 v[70:73], v[186:189], v[216:219], v[70:73]
	v_mfma_f32_16x16x32_bf16 v[86:89], v[194:197], v[216:219], v[86:89]
	v_mfma_f32_16x16x32_bf16 v[78:81], v[194:197], v[208:211], v[78:81]
	v_mfma_f32_16x16x32_bf16 v[14:17], v[158:161], v[212:215], v[14:17]
	v_mfma_f32_16x16x32_bf16 v[22:25], v[158:161], v[220:223], v[22:25]
	v_mfma_f32_16x16x32_bf16 v[46:49], v[182:185], v[220:223], v[46:49]
	v_mfma_f32_16x16x32_bf16 v[34:37], v[182:185], v[212:215], v[34:37]
	v_mfma_f32_16x16x32_bf16 v[58:61], v[190:193], v[212:215], v[58:61]
	v_mfma_f32_16x16x32_bf16 v[70:73], v[190:193], v[220:223], v[70:73]
	v_mfma_f32_16x16x32_bf16 v[86:89], v[198:201], v[220:223], v[86:89]
	v_mfma_f32_16x16x32_bf16 v[78:81], v[198:201], v[212:215], v[78:81]
	s_barrier
	s_setprio 0
	ds_read_b128 v[154:157], v175 offset:49152
	ds_read_b128 v[158:161], v175 offset:50176
	ds_read_b128 v[178:181], v175 offset:51200
	ds_read_b128 v[182:185], v175 offset:52224
	ds_read_b128 v[186:189], v175 offset:53248
	ds_read_b128 v[190:193], v175 offset:54272
	ds_read_b128 v[194:197], v175 offset:55296
	ds_read_b128 v[198:201], v175 offset:56320
	s_mov_b32 m0, s87
	s_nop 0
	global_load_lds_dwordx4 v232, s[100:101]
	s_mov_b32 m0, s88
	s_nop 0
	global_load_lds_dwordx4 v233, s[100:101]
	s_mov_b32 m0, s89
	s_nop 0
	global_load_lds_dwordx4 v234, s[98:99]
	s_mov_b32 m0, s90
	s_nop 0
	global_load_lds_dwordx4 v235, s[98:99]
	s_mov_b32 m0, s91
	s_nop 0
	global_load_lds_dwordx4 v236, s[100:101]
	s_mov_b32 m0, s92
	s_nop 0
	global_load_lds_dwordx4 v237, s[100:101]
	s_add_i32 s35, s35, 2
	s_add_u32 s10, s10, 0x100
	s_addc_u32 s11, s11, 0
	s_add_u32 s98, s98, 0x100
	s_addc_u32 s99, s99, 0
	s_add_u32 s100, s100, 0x100
	s_addc_u32 s101, s101, 0
	s_cmp_gt_u32 s35, 27
	s_waitcnt vmcnt(8)
	s_waitcnt lgkmcnt(0)
	s_setprio 1
	s_barrier
	v_mfma_f32_16x16x32_bf16 v[26:29], v[154:157], v[138:141], v[26:29]
	v_mfma_f32_16x16x32_bf16 v[38:41], v[154:157], v[146:149], v[38:41]
	v_mfma_f32_16x16x32_bf16 v[62:65], v[178:181], v[146:149], v[62:65]
	v_mfma_f32_16x16x32_bf16 v[50:53], v[178:181], v[138:141], v[50:53]
	v_mfma_f32_16x16x32_bf16 v[74:77], v[186:189], v[138:141], v[74:77]
	v_mfma_f32_16x16x32_bf16 v[82:85], v[186:189], v[146:149], v[82:85]
	v_mfma_f32_16x16x32_bf16 v[94:97], v[194:197], v[146:149], v[94:97]
	v_mfma_f32_16x16x32_bf16 v[90:93], v[194:197], v[138:141], v[90:93]
	v_mfma_f32_16x16x32_bf16 v[26:29], v[158:161], v[142:145], v[26:29]
	v_mfma_f32_16x16x32_bf16 v[38:41], v[158:161], v[150:153], v[38:41]
	v_mfma_f32_16x16x32_bf16 v[62:65], v[182:185], v[150:153], v[62:65]
	v_mfma_f32_16x16x32_bf16 v[50:53], v[182:185], v[142:145], v[50:53]
	v_mfma_f32_16x16x32_bf16 v[74:77], v[190:193], v[142:145], v[74:77]
	v_mfma_f32_16x16x32_bf16 v[82:85], v[190:193], v[150:153], v[82:85]
	v_mfma_f32_16x16x32_bf16 v[94:97], v[198:201], v[150:153], v[94:97]
	v_mfma_f32_16x16x32_bf16 v[90:93], v[198:201], v[142:145], v[90:93]
	v_mfma_f32_16x16x32_bf16 v[98:101], v[154:157], v[208:211], v[98:101]
	v_mfma_f32_16x16x32_bf16 v[102:105], v[154:157], v[216:219], v[102:105]
	v_mfma_f32_16x16x32_bf16 v[110:113], v[178:181], v[216:219], v[110:113]
	v_mfma_f32_16x16x32_bf16 v[106:109], v[178:181], v[208:211], v[106:109]
	v_mfma_f32_16x16x32_bf16 v[114:117], v[186:189], v[208:211], v[114:117]
	v_mfma_f32_16x16x32_bf16 v[118:121], v[186:189], v[216:219], v[118:121]
	v_mfma_f32_16x16x32_bf16 v[126:129], v[194:197], v[216:219], v[126:129]
	v_mfma_f32_16x16x32_bf16 v[122:125], v[194:197], v[208:211], v[122:125]
	v_mfma_f32_16x16x32_bf16 v[98:101], v[158:161], v[212:215], v[98:101]
	v_mfma_f32_16x16x32_bf16 v[102:105], v[158:161], v[220:223], v[102:105]
	v_mfma_f32_16x16x32_bf16 v[110:113], v[182:185], v[220:223], v[110:113]
	v_mfma_f32_16x16x32_bf16 v[106:109], v[182:185], v[212:215], v[106:109]
	v_mfma_f32_16x16x32_bf16 v[114:117], v[190:193], v[212:215], v[114:117]
	v_mfma_f32_16x16x32_bf16 v[118:121], v[190:193], v[220:223], v[118:121]
	v_mfma_f32_16x16x32_bf16 v[126:129], v[198:201], v[220:223], v[126:129]
	v_mfma_f32_16x16x32_bf16 v[122:125], v[198:201], v[212:215], v[122:125]
	s_barrier
; #define LDA(dst, b, h)                                                                                     \
;   _Pragma("unroll") for (int m = 0; m < 4; ++m) _Pragma("unroll") for (int k = 0; k < 2; ++k) dst[m][k] = \
;       *reinterpret_cast<const bf16x8*>(shmc + aL + (((b) * 2 + (h)) * 16384 + (m * 2 + k) * 1024))
; #define LDB(dst, b, h)                                                                                     \
;   _Pragma("unroll") for (int n = 0; n < 2; ++n) _Pragma("unroll") for (int k = 0; k < 2; ++k) dst[n][k] = \
;       *reinterpret_cast<const bf16x8*>(shmc + bL + (((b) * 2 + (h)) * 16384 + (n * 2 + k) * 1024))
; #define OPAQ asm volatile("" : "+v"(aL), "+v"(bL))
; #define WAIT_V(n) asm volatile("s_waitcnt vmcnt(" #n ")" ::: "memory")
; #define WAIT_L(n) asm volatile("s_waitcnt lgkmcnt(" #n ")" ::: "memory")
; #define BAR __builtin_amdgcn_s_barrier()
; #define SCHED __builtin_amdgcn_sched_barrier(0)
; template <int EPI>
; __device__ __forceinline__ void phase_gemm(const Params& p, const GemmDesc& d, char* shmc) {
;     ...
;     for (int t = 0; t < nt - 2; t += 2) {
;       OPAQ;
;       LDB(B0, 0, 0); SCHED; LDA(At, 0, 0); STAGE_A(SA(1, 1), 1, t + 1);
;       WAIT_L(8); BAR; WAIT_L(0); MMA(0, 0, At, B0); BAR; SCHED;
;       LDB(B1, 0, 1); STAGE_B(SB(0, 0), 0, t + 2);
;       BAR; WAIT_L(0); MMA(0, 1, At, B1); BAR;
;       LDA(At, 0, 1); STAGE_A(SA(0, 0), 0, t + 2);
;       BAR; WAIT_L(0); MMA(1, 0, At, B0); BAR; SCHED;
;       STAGE_B(SB(0, 1), 1, t + 2);
;       WAIT_V(6); BAR; MMA(1, 1, At, B1); BAR;
;       LDB(B0, 1, 0); SCHED; LDA(At, 1, 0); STAGE_A(SA(0, 1), 1, t + 2);
;       WAIT_L(8); BAR; WAIT_L(0); MMA(0, 0, At, B0); BAR; SCHED;
;       LDB(B1, 1, 1); STAGE_B(SB(1, 0), 0, t + 3);
;       BAR; WAIT_L(0); MMA(0, 1, At, B1); BAR;
;       LDA(At, 1, 1); STAGE_A(SA(1, 0), 0, t + 3);
;       BAR; WAIT_L(0); MMA(1, 0, At, B0); BAR; SCHED;
;       STAGE_B(SB(1, 1), 1, t + 3);
;       WAIT_V(6); BAR; MMA(1, 1, At, B1); BAR;
;     }
;     {
;       OPAQ;
;       LDB(B0, 0, 0); LDA(At, 0, 0); STAGE_A(SA(1, 1), 1, nt - 1);
;       BAR; WAIT_L(0); MMA(0, 0, At, B0); BAR;
;       LDB(B1, 0, 1); BAR; WAIT_L(0); MMA(0, 1, At, B1); BAR;
;       LDA(At, 0, 1); WAIT_V(4); BAR; WAIT_L(0); MMA(1, 0, At, B0); MMA(1, 1, At, B1); BAR;
	s_cbranch_scc0 .LBB0_296
	s_setprio 0
	s_add_u32 s8, s8, 0x80f80
	s_addc_u32 s9, s9, 0
	v_add_u32_e32 v162, 0, v205
	v_add_u32_e32 v175, 0, v204
	s_mov_b32 m0, s93
	ds_read_b128 v[130:133], v162
	ds_read_b128 v[134:137], v162 offset:1024
	ds_read_b128 v[138:141], v162 offset:2048
	ds_read_b128 v[142:145], v162 offset:3072
	ds_read_b128 v[146:149], v175
	ds_read_b128 v[150:153], v175 offset:1024
	ds_read_b128 v[154:157], v175 offset:2048
	ds_read_b128 v[158:161], v175 offset:3072
	ds_read_b128 v[178:181], v175 offset:4096
	ds_read_b128 v[182:185], v175 offset:5120
	ds_read_b128 v[186:189], v175 offset:6144
	ds_read_b128 v[190:193], v175 offset:7168
	global_load_lds_dwordx4 v174, s[8:9]
	s_mov_b32 m0, s94
	s_nop 0
	global_load_lds_dwordx4 v176, s[8:9]
	s_waitcnt vmcnt(8)
	s_barrier
	s_waitcnt lgkmcnt(0)
	s_setprio 1
	s_waitcnt lgkmcnt(0)
	v_mfma_f32_16x16x32_bf16 v[2:5], v[146:149], v[130:133], v[2:5]
	v_mfma_f32_16x16x32_bf16 v[6:9], v[146:149], v[138:141], v[6:9]
	v_mfma_f32_16x16x32_bf16 v[10:13], v[154:157], v[130:133], v[10:13]
	v_mfma_f32_16x16x32_bf16 v[18:21], v[154:157], v[138:141], v[18:21]
	v_mfma_f32_16x16x32_bf16 v[66:69], v[186:189], v[138:141], v[66:69]
	v_mfma_f32_16x16x32_bf16 v[2:5], v[150:153], v[134:137], v[2:5]
	v_mfma_f32_16x16x32_bf16 v[6:9], v[150:153], v[142:145], v[6:9]
	v_mfma_f32_16x16x32_bf16 v[10:13], v[158:161], v[134:137], v[10:13]
	v_mfma_f32_16x16x32_bf16 v[18:21], v[158:161], v[142:145], v[18:21]
	v_mfma_f32_16x16x32_bf16 v[30:33], v[178:181], v[130:133], v[30:33]
	v_mfma_f32_16x16x32_bf16 v[42:45], v[178:181], v[138:141], v[42:45]
	v_mfma_f32_16x16x32_bf16 v[54:57], v[186:189], v[130:133], v[54:57]
	v_mfma_f32_16x16x32_bf16 v[66:69], v[190:193], v[142:145], v[66:69]
	v_mfma_f32_16x16x32_bf16 v[30:33], v[182:185], v[134:137], v[30:33]
	v_mfma_f32_16x16x32_bf16 v[42:45], v[182:185], v[142:145], v[42:45]
	v_mfma_f32_16x16x32_bf16 v[54:57], v[190:193], v[134:137], v[54:57]
	s_setprio 0
	s_barrier
	ds_read_b128 v[194:197], v162 offset:16384
	ds_read_b128 v[198:201], v162 offset:17408
	ds_read_b128 v[208:211], v162 offset:18432
	ds_read_b128 v[212:215], v162 offset:19456
	s_barrier
	s_waitcnt lgkmcnt(0)
	s_setprio 1
	s_waitcnt lgkmcnt(0)
	v_mfma_f32_16x16x32_bf16 v[14:17], v[146:149], v[194:197], v[14:17]
	v_mfma_f32_16x16x32_bf16 v[22:25], v[146:149], v[208:211], v[22:25]
	v_mfma_f32_16x16x32_bf16 v[58:61], v[178:181], v[194:197], v[58:61]
	v_mfma_f32_16x16x32_bf16 v[14:17], v[150:153], v[198:201], v[14:17]
	v_mfma_f32_16x16x32_bf16 v[22:25], v[150:153], v[212:215], v[22:25]
	v_mfma_f32_16x16x32_bf16 v[150:153], v[182:185], v[198:201], v[58:61]
	v_mfma_f32_16x16x32_bf16 v[58:61], v[178:181], v[208:211], v[70:73]
	v_mfma_f32_16x16x32_bf16 v[34:37], v[154:157], v[194:197], v[34:37]
	v_mfma_f32_16x16x32_bf16 v[46:49], v[154:157], v[208:211], v[46:49]
	v_mfma_f32_16x16x32_bf16 v[154:157], v[182:185], v[212:215], v[58:61]
	v_mfma_f32_16x16x32_bf16 v[58:61], v[186:189], v[194:197], v[78:81]
	v_mfma_f32_16x16x32_bf16 v[78:81], v[190:193], v[198:201], v[58:61]
	v_mfma_f32_16x16x32_bf16 v[58:61], v[186:189], v[208:211], v[86:89]
	v_mfma_f32_16x16x32_bf16 v[86:89], v[190:193], v[212:215], v[58:61]
	v_mfma_f32_16x16x32_bf16 v[34:37], v[158:161], v[198:201], v[34:37]
	v_mfma_f32_16x16x32_bf16 v[46:49], v[158:161], v[212:215], v[46:49]
	s_setprio 0
	s_barrier
	s_nop 2
	ds_read_b128 v[58:61], v175 offset:16384
	ds_read_b128 v[70:73], v175 offset:17408
	ds_read_b128 v[146:149], v175 offset:18432
	ds_read_b128 v[158:161], v175 offset:19456
	ds_read_b128 v[178:181], v175 offset:20480
	ds_read_b128 v[182:185], v175 offset:21504
	ds_read_b128 v[186:189], v175 offset:22528
	ds_read_b128 v[190:193], v175 offset:23552
	s_waitcnt vmcnt(4)
	s_barrier
	s_waitcnt lgkmcnt(0)
	s_setprio 1
	s_waitcnt lgkmcnt(0)
	v_mfma_f32_16x16x32_bf16 v[74:77], v[178:181], v[130:133], v[74:77]
	v_mfma_f32_16x16x32_bf16 v[216:219], v[182:185], v[134:137], v[74:77]
	v_mfma_f32_16x16x32_bf16 v[74:77], v[178:181], v[138:141], v[82:85]
	v_mfma_f32_16x16x32_bf16 v[26:29], v[58:61], v[130:133], v[26:29]
	v_mfma_f32_16x16x32_bf16 v[82:85], v[182:185], v[142:145], v[74:77]
	v_mfma_f32_16x16x32_bf16 v[74:77], v[186:189], v[130:133], v[90:93]
	v_mfma_f32_16x16x32_bf16 v[26:29], v[70:73], v[134:137], v[26:29]
	v_mfma_f32_16x16x32_bf16 v[38:41], v[58:61], v[138:141], v[38:41]
	v_mfma_f32_16x16x32_bf16 v[50:53], v[146:149], v[130:133], v[50:53]
	v_mfma_f32_16x16x32_bf16 v[62:65], v[146:149], v[138:141], v[62:65]
	v_mfma_f32_16x16x32_bf16 v[90:93], v[190:193], v[134:137], v[74:77]
	v_mfma_f32_16x16x32_bf16 v[74:77], v[186:189], v[138:141], v[94:97]
	v_mfma_f32_16x16x32_bf16 v[38:41], v[70:73], v[142:145], v[38:41]
	v_mfma_f32_16x16x32_bf16 v[50:53], v[158:161], v[134:137], v[50:53]
	v_mfma_f32_16x16x32_bf16 v[62:65], v[158:161], v[142:145], v[62:65]
	v_mfma_f32_16x16x32_bf16 v[220:223], v[190:193], v[142:145], v[74:77]
	s_setprio 0
	s_setprio 1
	v_mfma_f32_16x16x32_bf16 v[74:77], v[58:61], v[194:197], v[98:101]
	v_mfma_f32_16x16x32_bf16 v[58:61], v[58:61], v[208:211], v[102:105]
	v_mfma_f32_16x16x32_bf16 v[228:231], v[70:73], v[212:215], v[58:61]
	v_mfma_f32_16x16x32_bf16 v[58:61], v[146:149], v[194:197], v[106:109]
	v_mfma_f32_16x16x32_bf16 v[232:235], v[158:161], v[198:201], v[58:61]
	v_mfma_f32_16x16x32_bf16 v[58:61], v[146:149], v[208:211], v[110:113]
	v_mfma_f32_16x16x32_bf16 v[236:239], v[158:161], v[212:215], v[58:61]
	v_mfma_f32_16x16x32_bf16 v[58:61], v[178:181], v[194:197], v[114:117]
	v_mfma_f32_16x16x32_bf16 v[240:243], v[182:185], v[198:201], v[58:61]
	v_mfma_f32_16x16x32_bf16 v[58:61], v[178:181], v[208:211], v[118:121]
	v_mfma_f32_16x16x32_bf16 v[178:181], v[182:185], v[212:215], v[58:61]
	v_mfma_f32_16x16x32_bf16 v[58:61], v[186:189], v[194:197], v[122:125]
	v_mfma_f32_16x16x32_bf16 v[182:185], v[190:193], v[198:201], v[58:61]
	v_mfma_f32_16x16x32_bf16 v[58:61], v[186:189], v[208:211], v[126:129]
	v_mfma_f32_16x16x32_bf16 v[224:227], v[70:73], v[198:201], v[74:77]
	v_mfma_f32_16x16x32_bf16 v[186:189], v[190:193], v[212:215], v[58:61]
	s_setprio 0
	s_barrier
; #define LDA(dst, b, h)                                                                                     \
;   _Pragma("unroll") for (int m = 0; m < 4; ++m) _Pragma("unroll") for (int k = 0; k < 2; ++k) dst[m][k] = \
;       *reinterpret_cast<const bf16x8*>(shmc + aL + (((b) * 2 + (h)) * 16384 + (m * 2 + k) * 1024))
; #define LDB(dst, b, h)                                                                                     \
;   _Pragma("unroll") for (int n = 0; n < 2; ++n) _Pragma("unroll") for (int k = 0; k < 2; ++k) dst[n][k] = \
;       *reinterpret_cast<const bf16x8*>(shmc + bL + (((b) * 2 + (h)) * 16384 + (n * 2 + k) * 1024))
; #define WAIT_V(n) asm volatile("s_waitcnt vmcnt(" #n ")" ::: "memory")
; #define WAIT_L(n) asm volatile("s_waitcnt lgkmcnt(" #n ")" ::: "memory")
; #define BAR __builtin_amdgcn_s_barrier()
; template <int EPI>
; __device__ __forceinline__ void phase_gemm(const Params& p, const GemmDesc& d, char* shmc) {
;     ...
;     {
;       LDB(B0, 1, 0); LDA(At, 1, 0); WAIT_V(2); BAR; WAIT_L(0); MMA(0, 0, At, B0); BAR;
;       LDB(B1, 1, 1); WAIT_V(0); BAR; WAIT_L(0); MMA(0, 1, At, B1); BAR;
;       LDA(At, 1, 1); BAR; WAIT_L(0); MMA(1, 0, At, B0); MMA(1, 1, At, B1); BAR;
;     }
;     if (wr == 0) BAR;
	ds_read_b128 v[98:101], v162 offset:32768
	ds_read_b128 v[106:109], v162 offset:33792
	ds_read_b128 v[190:193], v162 offset:34816
	ds_read_b128 v[194:197], v162 offset:35840
	ds_read_b128 v[58:61], v175 offset:32768
	ds_read_b128 v[70:73], v175 offset:33792
	ds_read_b128 v[114:117], v175 offset:34816
	ds_read_b128 v[122:125], v175 offset:35840
	ds_read_b128 v[130:133], v175 offset:36864
	ds_read_b128 v[138:141], v175 offset:37888
	ds_read_b128 v[198:201], v175 offset:38912
	ds_read_b128 v[208:211], v175 offset:39936
	s_waitcnt vmcnt(2)
	s_barrier
	s_waitcnt lgkmcnt(0)
	s_setprio 1
	s_waitcnt lgkmcnt(0)
	v_mfma_f32_16x16x32_bf16 v[2:5], v[58:61], v[98:101], v[2:5]
	v_mfma_f32_16x16x32_bf16 v[158:161], v[70:73], v[106:109], v[2:5]
	v_mfma_f32_16x16x32_bf16 v[2:5], v[58:61], v[190:193], v[6:9]
	v_mfma_f32_16x16x32_bf16 v[146:149], v[70:73], v[194:197], v[2:5]
	v_mfma_f32_16x16x32_bf16 v[2:5], v[114:117], v[98:101], v[10:13]
	v_mfma_f32_16x16x32_bf16 v[142:145], v[122:125], v[106:109], v[2:5]
	v_mfma_f32_16x16x32_bf16 v[2:5], v[114:117], v[190:193], v[18:21]
	v_mfma_f32_16x16x32_bf16 v[134:137], v[122:125], v[194:197], v[2:5]
	v_mfma_f32_16x16x32_bf16 v[2:5], v[130:133], v[98:101], v[30:33]
	v_mfma_f32_16x16x32_bf16 v[126:129], v[138:141], v[106:109], v[2:5]
	v_mfma_f32_16x16x32_bf16 v[2:5], v[130:133], v[190:193], v[42:45]
	v_mfma_f32_16x16x32_bf16 v[118:121], v[138:141], v[194:197], v[2:5]
	v_mfma_f32_16x16x32_bf16 v[2:5], v[198:201], v[98:101], v[54:57]
	v_mfma_f32_16x16x32_bf16 v[110:113], v[208:211], v[106:109], v[2:5]
	v_mfma_f32_16x16x32_bf16 v[2:5], v[198:201], v[190:193], v[66:69]
	v_mfma_f32_16x16x32_bf16 v[102:105], v[208:211], v[194:197], v[2:5]
	s_setprio 0
	s_barrier
	ds_read_b128 v[30:33], v162 offset:49152
	ds_read_b128 v[42:45], v162 offset:50176
	ds_read_b128 v[54:57], v162 offset:51200
	ds_read_b128 v[212:215], v162 offset:52224
	s_waitcnt vmcnt(0)
	s_barrier
	s_waitcnt lgkmcnt(0)
	s_setprio 1
	s_waitcnt lgkmcnt(0)
	v_mfma_f32_16x16x32_bf16 v[2:5], v[58:61], v[30:33], v[14:17]
	v_mfma_f32_16x16x32_bf16 v[94:97], v[70:73], v[42:45], v[2:5]
	v_mfma_f32_16x16x32_bf16 v[2:5], v[58:61], v[54:57], v[22:25]
	v_mfma_f32_16x16x32_bf16 v[58:61], v[70:73], v[212:215], v[2:5]
	v_mfma_f32_16x16x32_bf16 v[2:5], v[114:117], v[30:33], v[34:37]
	v_mfma_f32_16x16x32_bf16 v[74:77], v[122:125], v[42:45], v[2:5]
	v_mfma_f32_16x16x32_bf16 v[2:5], v[114:117], v[54:57], v[46:49]
	v_mfma_f32_16x16x32_bf16 v[10:13], v[122:125], v[212:215], v[2:5]
	v_mfma_f32_16x16x32_bf16 v[2:5], v[130:133], v[30:33], v[150:153]
	v_mfma_f32_16x16x32_bf16 v[70:73], v[138:141], v[42:45], v[2:5]
	v_mfma_f32_16x16x32_bf16 v[2:5], v[130:133], v[54:57], v[154:157]
	v_mfma_f32_16x16x32_bf16 v[6:9], v[138:141], v[212:215], v[2:5]
	v_mfma_f32_16x16x32_bf16 v[2:5], v[198:201], v[30:33], v[78:81]
	v_mfma_f32_16x16x32_bf16 v[66:69], v[208:211], v[42:45], v[2:5]
	v_mfma_f32_16x16x32_bf16 v[2:5], v[198:201], v[54:57], v[86:89]
	v_mfma_f32_16x16x32_bf16 v[2:5], v[208:211], v[212:215], v[2:5]
	s_setprio 0
	s_barrier
	ds_read_b128 v[14:17], v175 offset:49152
	ds_read_b128 v[18:21], v175 offset:50176
	ds_read_b128 v[22:25], v175 offset:51200
	ds_read_b128 v[34:37], v175 offset:52224
	ds_read_b128 v[46:49], v175 offset:53248
	ds_read_b128 v[78:81], v175 offset:54272
	ds_read_b128 v[198:201], v175 offset:55296
	ds_read_b128 v[208:211], v175 offset:56320
	s_barrier
	s_waitcnt lgkmcnt(0)
	s_setprio 1
	s_waitcnt lgkmcnt(0)
	v_mfma_f32_16x16x32_bf16 v[26:29], v[14:17], v[98:101], v[26:29]
	v_mfma_f32_16x16x32_bf16 v[154:157], v[18:21], v[106:109], v[26:29]
	v_mfma_f32_16x16x32_bf16 v[26:29], v[14:17], v[190:193], v[38:41]
	v_mfma_f32_16x16x32_bf16 v[150:153], v[18:21], v[194:197], v[26:29]
	v_mfma_f32_16x16x32_bf16 v[26:29], v[22:25], v[98:101], v[50:53]
	v_mfma_f32_16x16x32_bf16 v[138:141], v[34:37], v[106:109], v[26:29]
	v_mfma_f32_16x16x32_bf16 v[26:29], v[22:25], v[190:193], v[62:65]
	v_mfma_f32_16x16x32_bf16 v[130:133], v[34:37], v[194:197], v[26:29]
	v_mfma_f32_16x16x32_bf16 v[26:29], v[46:49], v[98:101], v[216:219]
	v_mfma_f32_16x16x32_bf16 v[122:125], v[78:81], v[106:109], v[26:29]
	v_mfma_f32_16x16x32_bf16 v[26:29], v[46:49], v[190:193], v[82:85]
	v_mfma_f32_16x16x32_bf16 v[114:117], v[78:81], v[194:197], v[26:29]
	v_mfma_f32_16x16x32_bf16 v[26:29], v[198:201], v[98:101], v[90:93]
	v_mfma_f32_16x16x32_bf16 v[106:109], v[208:211], v[106:109], v[26:29]
	v_mfma_f32_16x16x32_bf16 v[26:29], v[198:201], v[190:193], v[220:223]
	v_mfma_f32_16x16x32_bf16 v[98:101], v[208:211], v[194:197], v[26:29]
	s_setprio 0
	s_setprio 1
	v_mfma_f32_16x16x32_bf16 v[26:29], v[14:17], v[30:33], v[224:227]
	v_mfma_f32_16x16x32_bf16 v[14:17], v[14:17], v[54:57], v[228:231]
	v_mfma_f32_16x16x32_bf16 v[90:93], v[18:21], v[42:45], v[26:29]
	v_mfma_f32_16x16x32_bf16 v[26:29], v[18:21], v[212:215], v[14:17]
	v_mfma_f32_16x16x32_bf16 v[14:17], v[22:25], v[30:33], v[232:235]
	v_mfma_f32_16x16x32_bf16 v[86:89], v[34:37], v[42:45], v[14:17]
	v_mfma_f32_16x16x32_bf16 v[14:17], v[22:25], v[54:57], v[236:239]
	v_mfma_f32_16x16x32_bf16 v[22:25], v[34:37], v[212:215], v[14:17]
	v_mfma_f32_16x16x32_bf16 v[14:17], v[46:49], v[30:33], v[240:243]
	v_mfma_f32_16x16x32_bf16 v[82:85], v[78:81], v[42:45], v[14:17]
	v_mfma_f32_16x16x32_bf16 v[14:17], v[46:49], v[54:57], v[178:181]
	v_mfma_f32_16x16x32_bf16 v[18:21], v[78:81], v[212:215], v[14:17]
	v_mfma_f32_16x16x32_bf16 v[14:17], v[198:201], v[30:33], v[182:185]
	v_mfma_f32_16x16x32_bf16 v[78:81], v[208:211], v[42:45], v[14:17]
	v_mfma_f32_16x16x32_bf16 v[14:17], v[198:201], v[54:57], v[186:189]
	v_mfma_f32_16x16x32_bf16 v[14:17], v[208:211], v[212:215], v[14:17]
	s_setprio 0
	s_barrier
	s_and_saveexec_b64 s[8:9], s[6:7]
	s_cbranch_execz .LBB0_299
	s_barrier

; #define LDA(dst, b, h)                                                                                     \
;   _Pragma("unroll") for (int m = 0; m < 4; ++m) _Pragma("unroll") for (int k = 0; k < 2; ++k) dst[m][k] = \
;       *reinterpret_cast<const bf16x8*>(shmc + aL + (((b) * 2 + (h)) * 16384 + (m * 2 + k) * 1024))
; #define LDB(dst, b, h)                                                                                     \
;   _Pragma("unroll") for (int n = 0; n < 2; ++n) _Pragma("unroll") for (int k = 0; k < 2; ++k) dst[n][k] = \
;       *reinterpret_cast<const bf16x8*>(shmc + bL + (((b) * 2 + (h)) * 16384 + (n * 2 + k) * 1024))
; #define OPAQ asm volatile("" : "+v"(aL), "+v"(bL))
; #define WAIT_V(n) asm volatile("s_waitcnt vmcnt(" #n ")" ::: "memory")
; #define WAIT_L(n) asm volatile("s_waitcnt lgkmcnt(" #n ")" ::: "memory")
; #define BAR __builtin_amdgcn_s_barrier()
; #define SCHED __builtin_amdgcn_sched_barrier(0)
; template <int EPI>
; __device__ __forceinline__ void phase_gemm(const Params& p, const GemmDesc& d, char* shmc) {
;     ...
;     for (int t = 0; t < nt - 2; t += 2) {
;       OPAQ;
;       LDB(B0, 0, 0); SCHED; LDA(At, 0, 0); STAGE_A(SA(1, 1), 1, t + 1);
;       WAIT_L(8); BAR; WAIT_L(0); MMA(0, 0, At, B0); BAR; SCHED;
;       LDB(B1, 0, 1); STAGE_B(SB(0, 0), 0, t + 2);
;       BAR; WAIT_L(0); MMA(0, 1, At, B1); BAR;
;       LDA(At, 0, 1); STAGE_A(SA(0, 0), 0, t + 2);
;       BAR; WAIT_L(0); MMA(1, 0, At, B0); BAR; SCHED;
;       STAGE_B(SB(0, 1), 1, t + 2);
;       WAIT_V(6); BAR; MMA(1, 1, At, B1); BAR;
.LBB0_455:
	s_nop 0
	v_add_u32_e32 v130, 0, v153
	v_add_u32_e32 v141, 0, v152
	s_setprio 0
	ds_read_b128 v[156:159], v130
	ds_read_b128 v[160:163], v130 offset:1024
	ds_read_b128 v[164:167], v130 offset:2048
	ds_read_b128 v[168:171], v130 offset:3072
	ds_read_b128 v[204:207], v130 offset:16384
	ds_read_b128 v[208:211], v130 offset:17408
	ds_read_b128 v[212:215], v130 offset:18432
	ds_read_b128 v[216:219], v130 offset:19456
	ds_read_b128 v[172:175], v141
	ds_read_b128 v[176:179], v141 offset:1024
	ds_read_b128 v[180:183], v141 offset:2048
	ds_read_b128 v[184:187], v141 offset:3072
	ds_read_b128 v[188:191], v141 offset:4096
	ds_read_b128 v[192:195], v141 offset:5120
	ds_read_b128 v[196:199], v141 offset:6144
	ds_read_b128 v[200:203], v141 offset:7168
	s_mov_b32 m0, s70
	s_nop 0
	global_load_lds_dwordx4 v220, s[98:99]
	s_mov_b32 m0, s71
	s_nop 0
	global_load_lds_dwordx4 v221, s[98:99]
	s_waitcnt vmcnt(8)
	s_waitcnt lgkmcnt(0)
	s_setprio 1
	s_barrier
	v_mfma_f32_16x16x32_bf16 v[126:129], v[156:159], v[172:175], v[126:129]
	v_mfma_f32_16x16x32_bf16 v[122:125], v[164:167], v[172:175], v[122:125]
	v_mfma_f32_16x16x32_bf16 v[114:117], v[164:167], v[180:183], v[114:117]
	v_mfma_f32_16x16x32_bf16 v[118:121], v[156:159], v[180:183], v[118:121]
	v_mfma_f32_16x16x32_bf16 v[110:113], v[156:159], v[188:191], v[110:113]
	v_mfma_f32_16x16x32_bf16 v[106:109], v[164:167], v[188:191], v[106:109]
	v_mfma_f32_16x16x32_bf16 v[98:101], v[164:167], v[196:199], v[98:101]
	v_mfma_f32_16x16x32_bf16 v[102:105], v[156:159], v[196:199], v[102:105]
	v_mfma_f32_16x16x32_bf16 v[126:129], v[160:163], v[176:179], v[126:129]
	v_mfma_f32_16x16x32_bf16 v[122:125], v[168:171], v[176:179], v[122:125]
	v_mfma_f32_16x16x32_bf16 v[114:117], v[168:171], v[184:187], v[114:117]
	v_mfma_f32_16x16x32_bf16 v[118:121], v[160:163], v[184:187], v[118:121]
	v_mfma_f32_16x16x32_bf16 v[110:113], v[160:163], v[192:195], v[110:113]
	v_mfma_f32_16x16x32_bf16 v[106:109], v[168:171], v[192:195], v[106:109]
	v_mfma_f32_16x16x32_bf16 v[98:101], v[168:171], v[200:203], v[98:101]
	v_mfma_f32_16x16x32_bf16 v[102:105], v[160:163], v[200:203], v[102:105]
	v_mfma_f32_16x16x32_bf16 v[86:89], v[204:207], v[172:175], v[86:89]
	v_mfma_f32_16x16x32_bf16 v[70:73], v[212:215], v[172:175], v[70:73]
	v_mfma_f32_16x16x32_bf16 v[50:53], v[212:215], v[180:183], v[50:53]
	v_mfma_f32_16x16x32_bf16 v[54:57], v[204:207], v[180:183], v[54:57]
	v_mfma_f32_16x16x32_bf16 v[46:49], v[204:207], v[188:191], v[46:49]
	v_mfma_f32_16x16x32_bf16 v[42:45], v[212:215], v[188:191], v[42:45]
	v_mfma_f32_16x16x32_bf16 v[34:37], v[212:215], v[196:199], v[34:37]
	v_mfma_f32_16x16x32_bf16 v[38:41], v[204:207], v[196:199], v[38:41]
	v_mfma_f32_16x16x32_bf16 v[86:89], v[208:211], v[176:179], v[86:89]
	v_mfma_f32_16x16x32_bf16 v[70:73], v[216:219], v[176:179], v[70:73]
	v_mfma_f32_16x16x32_bf16 v[50:53], v[216:219], v[184:187], v[50:53]
	v_mfma_f32_16x16x32_bf16 v[54:57], v[208:211], v[184:187], v[54:57]
	v_mfma_f32_16x16x32_bf16 v[46:49], v[208:211], v[192:195], v[46:49]
	v_mfma_f32_16x16x32_bf16 v[42:45], v[216:219], v[192:195], v[42:45]
	v_mfma_f32_16x16x32_bf16 v[34:37], v[216:219], v[200:203], v[34:37]
	v_mfma_f32_16x16x32_bf16 v[38:41], v[208:211], v[200:203], v[38:41]
	s_barrier
	s_setprio 0
	ds_read_b128 v[172:175], v141 offset:16384
	ds_read_b128 v[176:179], v141 offset:17408
	ds_read_b128 v[180:183], v141 offset:18432
	ds_read_b128 v[184:187], v141 offset:19456
	ds_read_b128 v[188:191], v141 offset:20480
	ds_read_b128 v[192:195], v141 offset:21504
	ds_read_b128 v[196:199], v141 offset:22528
	ds_read_b128 v[200:203], v141 offset:23552
	s_mov_b32 m0, s33
	s_nop 0
	global_load_lds_dwordx4 v222, s[100:101]
	s_mov_b32 m0, s34
	s_nop 0
	global_load_lds_dwordx4 v223, s[100:101]
	s_mov_b32 m0, s14
	s_nop 0
	global_load_lds_dwordx4 v224, s[98:99]
	s_mov_b32 m0, s35
	s_nop 0
	global_load_lds_dwordx4 v225, s[98:99]
	s_mov_b32 m0, s58
	s_nop 0
	global_load_lds_dwordx4 v226, s[100:101]
	s_mov_b32 m0, s59
	s_nop 0
	global_load_lds_dwordx4 v227, s[100:101]
	s_waitcnt vmcnt(8)
	s_waitcnt lgkmcnt(0)
	s_setprio 1
	s_barrier
	v_mfma_f32_16x16x32_bf16 v[30:33], v[156:159], v[172:175], v[30:33]
	v_mfma_f32_16x16x32_bf16 v[26:29], v[164:167], v[172:175], v[26:29]
	v_mfma_f32_16x16x32_bf16 v[18:21], v[164:167], v[180:183], v[18:21]
	v_mfma_f32_16x16x32_bf16 v[22:25], v[156:159], v[180:183], v[22:25]
	v_mfma_f32_16x16x32_bf16 v[14:17], v[156:159], v[188:191], v[14:17]
	v_mfma_f32_16x16x32_bf16 v[10:13], v[164:167], v[188:191], v[10:13]
	v_mfma_f32_16x16x32_bf16 v[2:5], v[164:167], v[196:199], v[2:5]
	v_mfma_f32_16x16x32_bf16 v[6:9], v[156:159], v[196:199], v[6:9]
	v_mfma_f32_16x16x32_bf16 v[30:33], v[160:163], v[176:179], v[30:33]
	v_mfma_f32_16x16x32_bf16 v[26:29], v[168:171], v[176:179], v[26:29]
	v_mfma_f32_16x16x32_bf16 v[18:21], v[168:171], v[184:187], v[18:21]
	v_mfma_f32_16x16x32_bf16 v[22:25], v[160:163], v[184:187], v[22:25]
	v_mfma_f32_16x16x32_bf16 v[14:17], v[160:163], v[192:195], v[14:17]
	v_mfma_f32_16x16x32_bf16 v[10:13], v[168:171], v[192:195], v[10:13]
	v_mfma_f32_16x16x32_bf16 v[2:5], v[168:171], v[200:203], v[2:5]
	v_mfma_f32_16x16x32_bf16 v[6:9], v[160:163], v[200:203], v[6:9]
	v_mfma_f32_16x16x32_bf16 v[58:61], v[204:207], v[172:175], v[58:61]
	v_mfma_f32_16x16x32_bf16 v[62:65], v[212:215], v[172:175], v[62:65]
	v_mfma_f32_16x16x32_bf16 v[74:77], v[212:215], v[180:183], v[74:77]
	v_mfma_f32_16x16x32_bf16 v[66:69], v[204:207], v[180:183], v[66:69]
	v_mfma_f32_16x16x32_bf16 v[78:81], v[204:207], v[188:191], v[78:81]
	v_mfma_f32_16x16x32_bf16 v[82:85], v[212:215], v[188:191], v[82:85]
	v_mfma_f32_16x16x32_bf16 v[94:97], v[212:215], v[196:199], v[94:97]
	v_mfma_f32_16x16x32_bf16 v[90:93], v[204:207], v[196:199], v[90:93]
	v_mfma_f32_16x16x32_bf16 v[58:61], v[208:211], v[176:179], v[58:61]
	v_mfma_f32_16x16x32_bf16 v[62:65], v[216:219], v[176:179], v[62:65]
	v_mfma_f32_16x16x32_bf16 v[74:77], v[216:219], v[184:187], v[74:77]
	v_mfma_f32_16x16x32_bf16 v[66:69], v[208:211], v[184:187], v[66:69]
	v_mfma_f32_16x16x32_bf16 v[78:81], v[208:211], v[192:195], v[78:81]
	v_mfma_f32_16x16x32_bf16 v[82:85], v[216:219], v[192:195], v[82:85]
	v_mfma_f32_16x16x32_bf16 v[94:97], v[216:219], v[200:203], v[94:97]
	v_mfma_f32_16x16x32_bf16 v[90:93], v[208:211], v[200:203], v[90:93]
	s_barrier
; #define LDA(dst, b, h)                                                                                     \
;   _Pragma("unroll") for (int m = 0; m < 4; ++m) _Pragma("unroll") for (int k = 0; k < 2; ++k) dst[m][k] = \
;       *reinterpret_cast<const bf16x8*>(shmc + aL + (((b) * 2 + (h)) * 16384 + (m * 2 + k) * 1024))
; #define LDB(dst, b, h)                                                                                     \
;   _Pragma("unroll") for (int n = 0; n < 2; ++n) _Pragma("unroll") for (int k = 0; k < 2; ++k) dst[n][k] = \
;       *reinterpret_cast<const bf16x8*>(shmc + bL + (((b) * 2 + (h)) * 16384 + (n * 2 + k) * 1024))
; #define WAIT_V(n) asm volatile("s_waitcnt vmcnt(" #n ")" ::: "memory")
; #define WAIT_L(n) asm volatile("s_waitcnt lgkmcnt(" #n ")" ::: "memory")
; #define BAR __builtin_amdgcn_s_barrier()
; #define SCHED __builtin_amdgcn_sched_barrier(0)
; template <int EPI>
; __device__ __forceinline__ void phase_gemm(const Params& p, const GemmDesc& d, char* shmc) {
;     ...
;       LDB(B0, 1, 0); SCHED; LDA(At, 1, 0); STAGE_A(SA(0, 1), 1, t + 2);
;       WAIT_L(8); BAR; WAIT_L(0); MMA(0, 0, At, B0); BAR; SCHED;
;       LDB(B1, 1, 1); STAGE_B(SB(1, 0), 0, t + 3);
;       BAR; WAIT_L(0); MMA(0, 1, At, B1); BAR;
;       LDA(At, 1, 1); STAGE_A(SA(1, 0), 0, t + 3);
;       BAR; WAIT_L(0); MMA(1, 0, At, B0); BAR; SCHED;
;       STAGE_B(SB(1, 1), 1, t + 3);
;       WAIT_V(6); BAR; MMA(1, 1, At, B1); BAR;
;     }
	s_setprio 0
	ds_read_b128 v[156:159], v130 offset:32768
	ds_read_b128 v[160:163], v130 offset:33792
	ds_read_b128 v[164:167], v130 offset:34816
	ds_read_b128 v[168:171], v130 offset:35840
	ds_read_b128 v[204:207], v130 offset:49152
	ds_read_b128 v[208:211], v130 offset:50176
	ds_read_b128 v[212:215], v130 offset:51200
	ds_read_b128 v[216:219], v130 offset:52224
	ds_read_b128 v[172:175], v141 offset:32768
	ds_read_b128 v[176:179], v141 offset:33792
	ds_read_b128 v[180:183], v141 offset:34816
	ds_read_b128 v[184:187], v141 offset:35840
	ds_read_b128 v[188:191], v141 offset:36864
	ds_read_b128 v[192:195], v141 offset:37888
	ds_read_b128 v[196:199], v141 offset:38912
	ds_read_b128 v[200:203], v141 offset:39936
	s_mov_b32 m0, s60
	s_nop 0
	global_load_lds_dwordx4 v228, s[98:99]
	s_mov_b32 m0, s61
	s_nop 0
	global_load_lds_dwordx4 v229, s[98:99]
	s_waitcnt vmcnt(8)
	s_waitcnt lgkmcnt(0)
	s_setprio 1
	s_barrier
	v_mfma_f32_16x16x32_bf16 v[126:129], v[156:159], v[172:175], v[126:129]
	v_mfma_f32_16x16x32_bf16 v[122:125], v[164:167], v[172:175], v[122:125]
	v_mfma_f32_16x16x32_bf16 v[114:117], v[164:167], v[180:183], v[114:117]
	v_mfma_f32_16x16x32_bf16 v[118:121], v[156:159], v[180:183], v[118:121]
	v_mfma_f32_16x16x32_bf16 v[110:113], v[156:159], v[188:191], v[110:113]
	v_mfma_f32_16x16x32_bf16 v[106:109], v[164:167], v[188:191], v[106:109]
	v_mfma_f32_16x16x32_bf16 v[98:101], v[164:167], v[196:199], v[98:101]
	v_mfma_f32_16x16x32_bf16 v[102:105], v[156:159], v[196:199], v[102:105]
	v_mfma_f32_16x16x32_bf16 v[126:129], v[160:163], v[176:179], v[126:129]
	v_mfma_f32_16x16x32_bf16 v[122:125], v[168:171], v[176:179], v[122:125]
	v_mfma_f32_16x16x32_bf16 v[114:117], v[168:171], v[184:187], v[114:117]
	v_mfma_f32_16x16x32_bf16 v[118:121], v[160:163], v[184:187], v[118:121]
	v_mfma_f32_16x16x32_bf16 v[110:113], v[160:163], v[192:195], v[110:113]
	v_mfma_f32_16x16x32_bf16 v[106:109], v[168:171], v[192:195], v[106:109]
	v_mfma_f32_16x16x32_bf16 v[98:101], v[168:171], v[200:203], v[98:101]
	v_mfma_f32_16x16x32_bf16 v[102:105], v[160:163], v[200:203], v[102:105]
	v_mfma_f32_16x16x32_bf16 v[86:89], v[204:207], v[172:175], v[86:89]
	v_mfma_f32_16x16x32_bf16 v[70:73], v[212:215], v[172:175], v[70:73]
	v_mfma_f32_16x16x32_bf16 v[50:53], v[212:215], v[180:183], v[50:53]
	v_mfma_f32_16x16x32_bf16 v[54:57], v[204:207], v[180:183], v[54:57]
	v_mfma_f32_16x16x32_bf16 v[46:49], v[204:207], v[188:191], v[46:49]
	v_mfma_f32_16x16x32_bf16 v[42:45], v[212:215], v[188:191], v[42:45]
	v_mfma_f32_16x16x32_bf16 v[34:37], v[212:215], v[196:199], v[34:37]
	v_mfma_f32_16x16x32_bf16 v[38:41], v[204:207], v[196:199], v[38:41]
	v_mfma_f32_16x16x32_bf16 v[86:89], v[208:211], v[176:179], v[86:89]
	v_mfma_f32_16x16x32_bf16 v[70:73], v[216:219], v[176:179], v[70:73]
	v_mfma_f32_16x16x32_bf16 v[50:53], v[216:219], v[184:187], v[50:53]
	v_mfma_f32_16x16x32_bf16 v[54:57], v[208:211], v[184:187], v[54:57]
	v_mfma_f32_16x16x32_bf16 v[46:49], v[208:211], v[192:195], v[46:49]
	v_mfma_f32_16x16x32_bf16 v[42:45], v[216:219], v[192:195], v[42:45]
	v_mfma_f32_16x16x32_bf16 v[34:37], v[216:219], v[200:203], v[34:37]
	v_mfma_f32_16x16x32_bf16 v[38:41], v[208:211], v[200:203], v[38:41]
	s_barrier
	s_setprio 0
	ds_read_b128 v[172:175], v141 offset:49152
	ds_read_b128 v[176:179], v141 offset:50176
	ds_read_b128 v[180:183], v141 offset:51200
	ds_read_b128 v[184:187], v141 offset:52224
	ds_read_b128 v[188:191], v141 offset:53248
	ds_read_b128 v[192:195], v141 offset:54272
	ds_read_b128 v[196:199], v141 offset:55296
	ds_read_b128 v[200:203], v141 offset:56320
	s_mov_b32 m0, s62
	s_nop 0
	global_load_lds_dwordx4 v232, s[100:101]
	s_mov_b32 m0, s63
	s_nop 0
	global_load_lds_dwordx4 v233, s[100:101]
	s_mov_b32 m0, s64
	s_nop 0
	global_load_lds_dwordx4 v234, s[98:99]
	s_mov_b32 m0, s65
	s_nop 0
	global_load_lds_dwordx4 v235, s[98:99]
	s_mov_b32 m0, s68
	s_nop 0
	global_load_lds_dwordx4 v236, s[100:101]
	s_mov_b32 m0, s69
	s_nop 0
	global_load_lds_dwordx4 v237, s[100:101]
	s_add_i32 s54, s54, 2
	s_add_u32 s52, s52, 0x100
	s_addc_u32 s53, s53, 0
	s_add_u32 s98, s98, 0x100
	s_addc_u32 s99, s99, 0
	s_add_u32 s100, s100, 0x100
	s_addc_u32 s101, s101, 0
	s_cmpk_gt_u32 s54, 0x53
	s_waitcnt vmcnt(8)
	s_waitcnt lgkmcnt(0)
	s_setprio 1
	s_barrier
	v_mfma_f32_16x16x32_bf16 v[30:33], v[156:159], v[172:175], v[30:33]
	v_mfma_f32_16x16x32_bf16 v[26:29], v[164:167], v[172:175], v[26:29]
	v_mfma_f32_16x16x32_bf16 v[18:21], v[164:167], v[180:183], v[18:21]
	v_mfma_f32_16x16x32_bf16 v[22:25], v[156:159], v[180:183], v[22:25]
	v_mfma_f32_16x16x32_bf16 v[14:17], v[156:159], v[188:191], v[14:17]
	v_mfma_f32_16x16x32_bf16 v[10:13], v[164:167], v[188:191], v[10:13]
	v_mfma_f32_16x16x32_bf16 v[2:5], v[164:167], v[196:199], v[2:5]
	v_mfma_f32_16x16x32_bf16 v[6:9], v[156:159], v[196:199], v[6:9]
	v_mfma_f32_16x16x32_bf16 v[30:33], v[160:163], v[176:179], v[30:33]
	v_mfma_f32_16x16x32_bf16 v[26:29], v[168:171], v[176:179], v[26:29]
	v_mfma_f32_16x16x32_bf16 v[18:21], v[168:171], v[184:187], v[18:21]
	v_mfma_f32_16x16x32_bf16 v[22:25], v[160:163], v[184:187], v[22:25]
	v_mfma_f32_16x16x32_bf16 v[14:17], v[160:163], v[192:195], v[14:17]
	v_mfma_f32_16x16x32_bf16 v[10:13], v[168:171], v[192:195], v[10:13]
	v_mfma_f32_16x16x32_bf16 v[2:5], v[168:171], v[200:203], v[2:5]
	v_mfma_f32_16x16x32_bf16 v[6:9], v[160:163], v[200:203], v[6:9]
	v_mfma_f32_16x16x32_bf16 v[58:61], v[204:207], v[172:175], v[58:61]
	v_mfma_f32_16x16x32_bf16 v[62:65], v[212:215], v[172:175], v[62:65]
	v_mfma_f32_16x16x32_bf16 v[74:77], v[212:215], v[180:183], v[74:77]
	v_mfma_f32_16x16x32_bf16 v[66:69], v[204:207], v[180:183], v[66:69]
	v_mfma_f32_16x16x32_bf16 v[78:81], v[204:207], v[188:191], v[78:81]
	v_mfma_f32_16x16x32_bf16 v[82:85], v[212:215], v[188:191], v[82:85]
	v_mfma_f32_16x16x32_bf16 v[94:97], v[212:215], v[196:199], v[94:97]
	v_mfma_f32_16x16x32_bf16 v[90:93], v[204:207], v[196:199], v[90:93]
	v_mfma_f32_16x16x32_bf16 v[58:61], v[208:211], v[176:179], v[58:61]
	v_mfma_f32_16x16x32_bf16 v[62:65], v[216:219], v[176:179], v[62:65]
	v_mfma_f32_16x16x32_bf16 v[74:77], v[216:219], v[184:187], v[74:77]
	v_mfma_f32_16x16x32_bf16 v[66:69], v[208:211], v[184:187], v[66:69]
	v_mfma_f32_16x16x32_bf16 v[78:81], v[208:211], v[192:195], v[78:81]
	v_mfma_f32_16x16x32_bf16 v[82:85], v[216:219], v[192:195], v[82:85]
	v_mfma_f32_16x16x32_bf16 v[94:97], v[216:219], v[200:203], v[94:97]
	v_mfma_f32_16x16x32_bf16 v[90:93], v[208:211], v[200:203], v[90:93]
	s_barrier
; #define LDA(dst, b, h)                                                                                     \
;   _Pragma("unroll") for (int m = 0; m < 4; ++m) _Pragma("unroll") for (int k = 0; k < 2; ++k) dst[m][k] = \
;       *reinterpret_cast<const bf16x8*>(shmc + aL + (((b) * 2 + (h)) * 16384 + (m * 2 + k) * 1024))
; #define LDB(dst, b, h)                                                                                     \
;   _Pragma("unroll") for (int n = 0; n < 2; ++n) _Pragma("unroll") for (int k = 0; k < 2; ++k) dst[n][k] = \
;       *reinterpret_cast<const bf16x8*>(shmc + bL + (((b) * 2 + (h)) * 16384 + (n * 2 + k) * 1024))
; #define OPAQ asm volatile("" : "+v"(aL), "+v"(bL))
; #define WAIT_V(n) asm volatile("s_waitcnt vmcnt(" #n ")" ::: "memory")
; #define WAIT_L(n) asm volatile("s_waitcnt lgkmcnt(" #n ")" ::: "memory")
; #define BAR __builtin_amdgcn_s_barrier()
; template <int EPI>
; __device__ __forceinline__ void phase_gemm(const Params& p, const GemmDesc& d, char* shmc) {
;     ...
;     }
;     {
;       OPAQ;
;       LDB(B0, 0, 0); LDA(At, 0, 0); STAGE_A(SA(1, 1), 1, nt - 1);
;       BAR; WAIT_L(0); MMA(0, 0, At, B0); BAR;
;       LDB(B1, 0, 1); BAR; WAIT_L(0); MMA(0, 1, At, B1); BAR;
;       LDA(At, 0, 1); WAIT_V(4); BAR; WAIT_L(0); MMA(1, 0, At, B0); MMA(1, 1, At, B1); BAR;
	s_cbranch_scc0 .LBB0_455
	s_setprio 0
	s_add_u32 s48, s48, 0x162b80
	s_addc_u32 s49, s49, 0
	v_add_u32_e32 v130, 0, v153
	v_add_u32_e32 v141, 0, v152
	s_mov_b32 m0, s70
	ds_read_b128 v[144:147], v130
	ds_read_b128 v[148:151], v130 offset:1024
	ds_read_b128 v[156:159], v130 offset:2048
	ds_read_b128 v[160:163], v130 offset:3072
	ds_read_b128 v[164:167], v141
	ds_read_b128 v[168:171], v141 offset:1024
	ds_read_b128 v[172:175], v141 offset:2048
	ds_read_b128 v[176:179], v141 offset:3072
	ds_read_b128 v[180:183], v141 offset:4096
	ds_read_b128 v[184:187], v141 offset:5120
	ds_read_b128 v[188:191], v141 offset:6144
	ds_read_b128 v[192:195], v141 offset:7168
	global_load_lds_dwordx4 v140, s[48:49]
	s_mov_b32 m0, s71
	s_nop 0
	global_load_lds_dwordx4 v142, s[48:49]
	s_waitcnt vmcnt(8)
	s_barrier
	s_waitcnt lgkmcnt(0)
	s_setprio 1
	s_waitcnt lgkmcnt(0)
	v_mfma_f32_16x16x32_bf16 v[126:129], v[144:147], v[164:167], v[126:129]
	v_mfma_f32_16x16x32_bf16 v[122:125], v[156:159], v[164:167], v[122:125]
	v_mfma_f32_16x16x32_bf16 v[114:117], v[156:159], v[172:175], v[114:117]
	v_mfma_f32_16x16x32_bf16 v[110:113], v[144:147], v[180:183], v[110:113]
	v_mfma_f32_16x16x32_bf16 v[102:105], v[144:147], v[188:191], v[102:105]
	v_mfma_f32_16x16x32_bf16 v[126:129], v[148:151], v[168:171], v[126:129]
	v_mfma_f32_16x16x32_bf16 v[122:125], v[160:163], v[168:171], v[122:125]
	v_mfma_f32_16x16x32_bf16 v[118:121], v[144:147], v[172:175], v[118:121]
	v_mfma_f32_16x16x32_bf16 v[114:117], v[160:163], v[176:179], v[114:117]
	v_mfma_f32_16x16x32_bf16 v[110:113], v[148:151], v[184:187], v[110:113]
	v_mfma_f32_16x16x32_bf16 v[106:109], v[156:159], v[180:183], v[106:109]
	v_mfma_f32_16x16x32_bf16 v[102:105], v[148:151], v[192:195], v[102:105]
	v_mfma_f32_16x16x32_bf16 v[98:101], v[156:159], v[188:191], v[98:101]
	v_mfma_f32_16x16x32_bf16 v[196:199], v[148:151], v[176:179], v[118:121]
	v_mfma_f32_16x16x32_bf16 v[200:203], v[160:163], v[184:187], v[106:109]
	v_mfma_f32_16x16x32_bf16 v[204:207], v[160:163], v[192:195], v[98:101]
	s_setprio 0
	s_barrier
	s_nop 2
	ds_read_b128 v[98:101], v130 offset:16384
	ds_read_b128 v[106:109], v130 offset:17408
	ds_read_b128 v[118:121], v130 offset:18432
	ds_read_b128 v[208:211], v130 offset:19456
	s_barrier
	s_waitcnt lgkmcnt(0)
	s_setprio 1
	s_waitcnt lgkmcnt(0)
	v_mfma_f32_16x16x32_bf16 v[86:89], v[98:101], v[164:167], v[86:89]
	v_mfma_f32_16x16x32_bf16 v[70:73], v[118:121], v[164:167], v[70:73]
	v_mfma_f32_16x16x32_bf16 v[54:57], v[98:101], v[172:175], v[54:57]
	v_mfma_f32_16x16x32_bf16 v[50:53], v[118:121], v[172:175], v[50:53]
	v_mfma_f32_16x16x32_bf16 v[46:49], v[98:101], v[180:183], v[46:49]
	v_mfma_f32_16x16x32_bf16 v[42:45], v[118:121], v[180:183], v[42:45]
	v_mfma_f32_16x16x32_bf16 v[38:41], v[98:101], v[188:191], v[38:41]
	v_mfma_f32_16x16x32_bf16 v[34:37], v[118:121], v[188:191], v[34:37]
	v_mfma_f32_16x16x32_bf16 v[86:89], v[106:109], v[168:171], v[86:89]
	v_mfma_f32_16x16x32_bf16 v[70:73], v[208:211], v[168:171], v[70:73]
	v_mfma_f32_16x16x32_bf16 v[54:57], v[106:109], v[176:179], v[54:57]
	v_mfma_f32_16x16x32_bf16 v[50:53], v[208:211], v[176:179], v[50:53]
	v_mfma_f32_16x16x32_bf16 v[46:49], v[106:109], v[184:187], v[46:49]
	v_mfma_f32_16x16x32_bf16 v[42:45], v[208:211], v[184:187], v[42:45]
	v_mfma_f32_16x16x32_bf16 v[38:41], v[106:109], v[192:195], v[38:41]
	v_mfma_f32_16x16x32_bf16 v[34:37], v[208:211], v[192:195], v[34:37]
	s_setprio 0
	s_barrier
	ds_read_b128 v[164:167], v141 offset:16384
	ds_read_b128 v[168:171], v141 offset:17408
	ds_read_b128 v[172:175], v141 offset:18432
	ds_read_b128 v[176:179], v141 offset:19456
	ds_read_b128 v[180:183], v141 offset:20480
	ds_read_b128 v[184:187], v141 offset:21504
	ds_read_b128 v[188:191], v141 offset:22528
	ds_read_b128 v[192:195], v141 offset:23552
	s_waitcnt vmcnt(4)
	s_barrier
	s_waitcnt lgkmcnt(0)
	s_setprio 1
	s_waitcnt lgkmcnt(0)
	v_mfma_f32_16x16x32_bf16 v[30:33], v[144:147], v[164:167], v[30:33]
	v_mfma_f32_16x16x32_bf16 v[26:29], v[156:159], v[164:167], v[26:29]
	v_mfma_f32_16x16x32_bf16 v[22:25], v[144:147], v[172:175], v[22:25]
	v_mfma_f32_16x16x32_bf16 v[18:21], v[156:159], v[172:175], v[18:21]
	v_mfma_f32_16x16x32_bf16 v[14:17], v[144:147], v[180:183], v[14:17]
	v_mfma_f32_16x16x32_bf16 v[10:13], v[156:159], v[180:183], v[10:13]
	v_mfma_f32_16x16x32_bf16 v[6:9], v[144:147], v[188:191], v[6:9]
	v_mfma_f32_16x16x32_bf16 v[2:5], v[156:159], v[188:191], v[2:5]
	v_mfma_f32_16x16x32_bf16 v[30:33], v[148:151], v[168:171], v[30:33]
	v_mfma_f32_16x16x32_bf16 v[26:29], v[160:163], v[168:171], v[26:29]
	v_mfma_f32_16x16x32_bf16 v[22:25], v[148:151], v[176:179], v[22:25]
	v_mfma_f32_16x16x32_bf16 v[18:21], v[160:163], v[176:179], v[18:21]
	v_mfma_f32_16x16x32_bf16 v[14:17], v[148:151], v[184:187], v[14:17]
	v_mfma_f32_16x16x32_bf16 v[10:13], v[160:163], v[184:187], v[10:13]
	v_mfma_f32_16x16x32_bf16 v[6:9], v[148:151], v[192:195], v[6:9]
	v_mfma_f32_16x16x32_bf16 v[2:5], v[160:163], v[192:195], v[2:5]
	s_setprio 0
	s_setprio 1
	v_mfma_f32_16x16x32_bf16 v[62:65], v[118:121], v[164:167], v[62:65]
	v_mfma_f32_16x16x32_bf16 v[144:147], v[208:211], v[168:171], v[62:65]
	v_mfma_f32_16x16x32_bf16 v[62:65], v[98:101], v[172:175], v[66:69]
	v_mfma_f32_16x16x32_bf16 v[148:151], v[106:109], v[176:179], v[62:65]
	v_mfma_f32_16x16x32_bf16 v[62:65], v[118:121], v[172:175], v[74:77]
	v_mfma_f32_16x16x32_bf16 v[156:159], v[208:211], v[176:179], v[62:65]
	v_mfma_f32_16x16x32_bf16 v[62:65], v[98:101], v[180:183], v[78:81]
	v_mfma_f32_16x16x32_bf16 v[160:163], v[106:109], v[184:187], v[62:65]
	v_mfma_f32_16x16x32_bf16 v[62:65], v[118:121], v[180:183], v[82:85]
	v_mfma_f32_16x16x32_bf16 v[58:61], v[98:101], v[164:167], v[58:61]
	v_mfma_f32_16x16x32_bf16 v[164:167], v[208:211], v[184:187], v[62:65]
	v_mfma_f32_16x16x32_bf16 v[62:65], v[98:101], v[188:191], v[90:93]
	v_mfma_f32_16x16x32_bf16 v[58:61], v[106:109], v[168:171], v[58:61]
	v_mfma_f32_16x16x32_bf16 v[168:171], v[106:109], v[192:195], v[62:65]
	v_mfma_f32_16x16x32_bf16 v[62:65], v[118:121], v[188:191], v[94:97]
	v_mfma_f32_16x16x32_bf16 v[172:175], v[208:211], v[192:195], v[62:65]
	s_setprio 0
	s_barrier
; #define LDA(dst, b, h)                                                                                     \
;   _Pragma("unroll") for (int m = 0; m < 4; ++m) _Pragma("unroll") for (int k = 0; k < 2; ++k) dst[m][k] = \
;       *reinterpret_cast<const bf16x8*>(shmc + aL + (((b) * 2 + (h)) * 16384 + (m * 2 + k) * 1024))
; #define LDB(dst, b, h)                                                                                     \
;   _Pragma("unroll") for (int n = 0; n < 2; ++n) _Pragma("unroll") for (int k = 0; k < 2; ++k) dst[n][k] = \
;       *reinterpret_cast<const bf16x8*>(shmc + bL + (((b) * 2 + (h)) * 16384 + (n * 2 + k) * 1024))
; #define WAIT_V(n) asm volatile("s_waitcnt vmcnt(" #n ")" ::: "memory")
; #define WAIT_L(n) asm volatile("s_waitcnt lgkmcnt(" #n ")" ::: "memory")
; #define BAR __builtin_amdgcn_s_barrier()
; template <int EPI>
; __device__ __forceinline__ void phase_gemm(const Params& p, const GemmDesc& d, char* shmc) {
;     ...
;     {
;       LDB(B0, 1, 0); LDA(At, 1, 0); WAIT_V(2); BAR; WAIT_L(0); MMA(0, 0, At, B0); BAR;
;       LDB(B1, 1, 1); WAIT_V(0); BAR; WAIT_L(0); MMA(0, 1, At, B1); BAR;
;       LDA(At, 1, 1); BAR; WAIT_L(0); MMA(1, 0, At, B0); MMA(1, 1, At, B1); BAR;
;     }
;     if (wr == 0) BAR;
	ds_read_b128 v[176:179], v130 offset:32768
	ds_read_b128 v[180:183], v130 offset:33792
	ds_read_b128 v[184:187], v130 offset:34816
	ds_read_b128 v[188:191], v130 offset:35840
	s_nop 0
	ds_read_b128 v[62:65], v141 offset:32768
	ds_read_b128 v[78:81], v141 offset:33792
	ds_read_b128 v[94:97], v141 offset:34816
	ds_read_b128 v[192:195], v141 offset:35840
	ds_read_b128 v[208:211], v141 offset:36864
	ds_read_b128 v[212:215], v141 offset:37888
	ds_read_b128 v[216:219], v141 offset:38912
	ds_read_b128 v[220:223], v141 offset:39936
	s_waitcnt vmcnt(2)
	s_barrier
	s_waitcnt lgkmcnt(0)
	s_setprio 1
	s_waitcnt lgkmcnt(0)
	v_mfma_f32_16x16x32_bf16 v[66:69], v[176:179], v[62:65], v[126:129]
	v_mfma_f32_16x16x32_bf16 v[126:129], v[180:183], v[78:81], v[66:69]
	v_mfma_f32_16x16x32_bf16 v[66:69], v[184:187], v[62:65], v[122:125]
	v_mfma_f32_16x16x32_bf16 v[118:121], v[188:191], v[78:81], v[66:69]
	v_mfma_f32_16x16x32_bf16 v[66:69], v[176:179], v[94:97], v[196:199]
	v_mfma_f32_16x16x32_bf16 v[106:109], v[180:183], v[192:195], v[66:69]
	v_mfma_f32_16x16x32_bf16 v[66:69], v[184:187], v[94:97], v[114:117]
	v_mfma_f32_16x16x32_bf16 v[98:101], v[188:191], v[192:195], v[66:69]
	v_mfma_f32_16x16x32_bf16 v[66:69], v[176:179], v[208:211], v[110:113]
	v_mfma_f32_16x16x32_bf16 v[90:93], v[180:183], v[212:215], v[66:69]
	v_mfma_f32_16x16x32_bf16 v[66:69], v[184:187], v[208:211], v[200:203]
	v_mfma_f32_16x16x32_bf16 v[82:85], v[188:191], v[212:215], v[66:69]
	v_mfma_f32_16x16x32_bf16 v[66:69], v[176:179], v[216:219], v[102:105]
	v_mfma_f32_16x16x32_bf16 v[74:77], v[180:183], v[220:223], v[66:69]
	v_mfma_f32_16x16x32_bf16 v[66:69], v[184:187], v[216:219], v[204:207]
	v_mfma_f32_16x16x32_bf16 v[66:69], v[188:191], v[220:223], v[66:69]
	s_setprio 0
	s_barrier
	ds_read_b128 v[196:199], v130 offset:49152
	ds_read_b128 v[200:203], v130 offset:50176
	ds_read_b128 v[204:207], v130 offset:51200
	ds_read_b128 v[224:227], v130 offset:52224
	s_waitcnt vmcnt(0)
	s_barrier
	s_waitcnt lgkmcnt(0)
	s_setprio 1
	s_waitcnt lgkmcnt(0)
	v_mfma_f32_16x16x32_bf16 v[86:89], v[196:199], v[62:65], v[86:89]
	v_mfma_f32_16x16x32_bf16 v[62:65], v[204:207], v[62:65], v[70:73]
	v_mfma_f32_16x16x32_bf16 v[54:57], v[196:199], v[94:97], v[54:57]
	v_mfma_f32_16x16x32_bf16 v[50:53], v[204:207], v[94:97], v[50:53]
	v_mfma_f32_16x16x32_bf16 v[46:49], v[196:199], v[208:211], v[46:49]
	v_mfma_f32_16x16x32_bf16 v[42:45], v[204:207], v[208:211], v[42:45]
	v_mfma_f32_16x16x32_bf16 v[38:41], v[196:199], v[216:219], v[38:41]
	v_mfma_f32_16x16x32_bf16 v[34:37], v[204:207], v[216:219], v[34:37]
	v_mfma_f32_16x16x32_bf16 v[122:125], v[200:203], v[78:81], v[86:89]
	v_mfma_f32_16x16x32_bf16 v[114:117], v[224:227], v[78:81], v[62:65]
	v_mfma_f32_16x16x32_bf16 v[110:113], v[200:203], v[192:195], v[54:57]
	v_mfma_f32_16x16x32_bf16 v[102:105], v[224:227], v[192:195], v[50:53]
	v_mfma_f32_16x16x32_bf16 v[94:97], v[200:203], v[212:215], v[46:49]
	v_mfma_f32_16x16x32_bf16 v[86:89], v[224:227], v[212:215], v[42:45]
	v_mfma_f32_16x16x32_bf16 v[78:81], v[200:203], v[220:223], v[38:41]
	v_mfma_f32_16x16x32_bf16 v[70:73], v[224:227], v[220:223], v[34:37]
	s_setprio 0
	s_barrier
	s_nop 0
	ds_read_b128 v[34:37], v141 offset:49152
	ds_read_b128 v[42:45], v141 offset:50176
	ds_read_b128 v[192:195], v141 offset:51200
	ds_read_b128 v[208:211], v141 offset:52224
	ds_read_b128 v[212:215], v141 offset:53248
	ds_read_b128 v[216:219], v141 offset:54272
	ds_read_b128 v[220:223], v141 offset:55296
	ds_read_b128 v[228:231], v141 offset:56320
	s_barrier
	s_waitcnt lgkmcnt(0)
	s_setprio 1
	s_waitcnt lgkmcnt(0)
	v_mfma_f32_16x16x32_bf16 v[30:33], v[176:179], v[34:37], v[30:33]
	v_mfma_f32_16x16x32_bf16 v[26:29], v[184:187], v[34:37], v[26:29]
	v_mfma_f32_16x16x32_bf16 v[22:25], v[176:179], v[192:195], v[22:25]
	v_mfma_f32_16x16x32_bf16 v[18:21], v[184:187], v[192:195], v[18:21]
	v_mfma_f32_16x16x32_bf16 v[14:17], v[176:179], v[212:215], v[14:17]
	v_mfma_f32_16x16x32_bf16 v[10:13], v[184:187], v[212:215], v[10:13]
	v_mfma_f32_16x16x32_bf16 v[6:9], v[176:179], v[220:223], v[6:9]
	v_mfma_f32_16x16x32_bf16 v[2:5], v[184:187], v[220:223], v[2:5]
	v_mfma_f32_16x16x32_bf16 v[62:65], v[180:183], v[42:45], v[30:33]
	v_mfma_f32_16x16x32_bf16 v[54:57], v[188:191], v[42:45], v[26:29]
	v_mfma_f32_16x16x32_bf16 v[46:49], v[180:183], v[208:211], v[22:25]
	v_mfma_f32_16x16x32_bf16 v[38:41], v[188:191], v[208:211], v[18:21]
	v_mfma_f32_16x16x32_bf16 v[30:33], v[180:183], v[216:219], v[14:17]
	v_mfma_f32_16x16x32_bf16 v[22:25], v[188:191], v[216:219], v[10:13]
	v_mfma_f32_16x16x32_bf16 v[14:17], v[180:183], v[228:231], v[6:9]
	v_mfma_f32_16x16x32_bf16 v[6:9], v[188:191], v[228:231], v[2:5]
	s_setprio 0
	s_setprio 1
	v_mfma_f32_16x16x32_bf16 v[2:5], v[196:199], v[34:37], v[58:61]
	v_mfma_f32_16x16x32_bf16 v[58:61], v[200:203], v[42:45], v[2:5]
	v_mfma_f32_16x16x32_bf16 v[2:5], v[204:207], v[34:37], v[144:147]
	v_mfma_f32_16x16x32_bf16 v[50:53], v[224:227], v[42:45], v[2:5]
	v_mfma_f32_16x16x32_bf16 v[2:5], v[196:199], v[192:195], v[148:151]
	v_mfma_f32_16x16x32_bf16 v[42:45], v[200:203], v[208:211], v[2:5]
	v_mfma_f32_16x16x32_bf16 v[2:5], v[204:207], v[192:195], v[156:159]
	v_mfma_f32_16x16x32_bf16 v[34:37], v[224:227], v[208:211], v[2:5]
	v_mfma_f32_16x16x32_bf16 v[2:5], v[196:199], v[212:215], v[160:163]
	v_mfma_f32_16x16x32_bf16 v[26:29], v[200:203], v[216:219], v[2:5]
	v_mfma_f32_16x16x32_bf16 v[2:5], v[204:207], v[212:215], v[164:167]
	v_mfma_f32_16x16x32_bf16 v[18:21], v[224:227], v[216:219], v[2:5]
	v_mfma_f32_16x16x32_bf16 v[2:5], v[196:199], v[220:223], v[168:171]
	v_mfma_f32_16x16x32_bf16 v[10:13], v[200:203], v[228:231], v[2:5]
	v_mfma_f32_16x16x32_bf16 v[2:5], v[204:207], v[220:223], v[172:175]
	v_mfma_f32_16x16x32_bf16 v[2:5], v[224:227], v[228:231], v[2:5]
	s_setprio 0
	s_barrier
	s_and_saveexec_b64 s[48:49], s[4:5]
	s_cbranch_execz .LBB0_458
	s_barrier

; #define LDA(dst, b, h)                                                                                     \
;   _Pragma("unroll") for (int m = 0; m < 4; ++m) _Pragma("unroll") for (int k = 0; k < 2; ++k) dst[m][k] = \
;       *reinterpret_cast<const bf16x8*>(shmc + aL + (((b) * 2 + (h)) * 16384 + (m * 2 + k) * 1024))
; #define LDB(dst, b, h)                                                                                     \
;   _Pragma("unroll") for (int n = 0; n < 2; ++n) _Pragma("unroll") for (int k = 0; k < 2; ++k) dst[n][k] = \
;       *reinterpret_cast<const bf16x8*>(shmc + bL + (((b) * 2 + (h)) * 16384 + (n * 2 + k) * 1024))
; #define OPAQ asm volatile("" : "+v"(aL), "+v"(bL))
; #define WAIT_V(n) asm volatile("s_waitcnt vmcnt(" #n ")" ::: "memory")
; #define WAIT_L(n) asm volatile("s_waitcnt lgkmcnt(" #n ")" ::: "memory")
; #define BAR __builtin_amdgcn_s_barrier()
; #define SCHED __builtin_amdgcn_sched_barrier(0)
; template <int EPI>
; __device__ __forceinline__ void phase_gemm(const Params& p, const GemmDesc& d, char* shmc) {
;     ...
;     for (int t = 0; t < nt - 2; t += 2) {
;       OPAQ;
;       LDB(B0, 0, 0); SCHED; LDA(At, 0, 0); STAGE_A(SA(1, 1), 1, t + 1);
;       WAIT_L(8); BAR; WAIT_L(0); MMA(0, 0, At, B0); BAR; SCHED;
;       LDB(B1, 0, 1); STAGE_B(SB(0, 0), 0, t + 2);
;       BAR; WAIT_L(0); MMA(0, 1, At, B1); BAR;
;       LDA(At, 0, 1); STAGE_A(SA(0, 0), 0, t + 2);
;       BAR; WAIT_L(0); MMA(1, 0, At, B0); BAR; SCHED;
;       STAGE_B(SB(0, 1), 1, t + 2);
;       WAIT_V(6); BAR; MMA(1, 1, At, B1); BAR;
.LBB0_598:
	s_nop 0
	v_add_u32_e32 v175, 0, v179
	v_add_u32_e32 v176, 0, v177
	s_setprio 0
	ds_read_b128 v[138:141], v175
	ds_read_b128 v[142:145], v175 offset:1024
	ds_read_b128 v[146:149], v175 offset:2048
	ds_read_b128 v[150:153], v175 offset:3072
	ds_read_b128 v[206:209], v175 offset:16384
	ds_read_b128 v[210:213], v175 offset:17408
	ds_read_b128 v[214:217], v175 offset:18432
	ds_read_b128 v[218:221], v175 offset:19456
	ds_read_b128 v[154:157], v176
	ds_read_b128 v[158:161], v176 offset:1024
	ds_read_b128 v[182:185], v176 offset:2048
	ds_read_b128 v[186:189], v176 offset:3072
	ds_read_b128 v[190:193], v176 offset:4096
	ds_read_b128 v[194:197], v176 offset:5120
	ds_read_b128 v[198:201], v176 offset:6144
	ds_read_b128 v[202:205], v176 offset:7168
	s_add_i32 s88, s68, 0xc000
	s_mov_b32 m0, s88
	s_nop 0
	global_load_lds_dwordx4 v222, s[98:99]
	s_add_i32 s89, s68, 0xe000
	s_mov_b32 m0, s89
	s_nop 0
	global_load_lds_dwordx4 v223, s[98:99]
	s_waitcnt vmcnt(8)
	s_waitcnt lgkmcnt(0)
	s_setprio 1
	s_barrier
	v_mfma_f32_16x16x32_bf16 v[126:129], v[154:157], v[138:141], v[126:129]
	v_mfma_f32_16x16x32_bf16 v[122:125], v[154:157], v[146:149], v[122:125]
	v_mfma_f32_16x16x32_bf16 v[114:117], v[182:185], v[146:149], v[114:117]
	v_mfma_f32_16x16x32_bf16 v[118:121], v[182:185], v[138:141], v[118:121]
	v_mfma_f32_16x16x32_bf16 v[110:113], v[190:193], v[138:141], v[110:113]
	v_mfma_f32_16x16x32_bf16 v[106:109], v[190:193], v[146:149], v[106:109]
	v_mfma_f32_16x16x32_bf16 v[94:97], v[198:201], v[146:149], v[94:97]
	v_mfma_f32_16x16x32_bf16 v[102:105], v[198:201], v[138:141], v[102:105]
	v_mfma_f32_16x16x32_bf16 v[126:129], v[158:161], v[142:145], v[126:129]
	v_mfma_f32_16x16x32_bf16 v[122:125], v[158:161], v[150:153], v[122:125]
	v_mfma_f32_16x16x32_bf16 v[114:117], v[186:189], v[150:153], v[114:117]
	v_mfma_f32_16x16x32_bf16 v[118:121], v[186:189], v[142:145], v[118:121]
	v_mfma_f32_16x16x32_bf16 v[110:113], v[194:197], v[142:145], v[110:113]
	v_mfma_f32_16x16x32_bf16 v[106:109], v[194:197], v[150:153], v[106:109]
	v_mfma_f32_16x16x32_bf16 v[94:97], v[202:205], v[150:153], v[94:97]
	v_mfma_f32_16x16x32_bf16 v[102:105], v[202:205], v[142:145], v[102:105]
	v_mfma_f32_16x16x32_bf16 v[50:53], v[154:157], v[206:209], v[50:53]
	v_mfma_f32_16x16x32_bf16 v[42:45], v[154:157], v[214:217], v[42:45]
	v_mfma_f32_16x16x32_bf16 v[34:37], v[182:185], v[214:217], v[34:37]
	v_mfma_f32_16x16x32_bf16 v[38:41], v[182:185], v[206:209], v[38:41]
	v_mfma_f32_16x16x32_bf16 v[30:33], v[190:193], v[206:209], v[30:33]
	v_mfma_f32_16x16x32_bf16 v[26:29], v[190:193], v[214:217], v[26:29]
	v_mfma_f32_16x16x32_bf16 v[18:21], v[198:201], v[214:217], v[18:21]
	v_mfma_f32_16x16x32_bf16 v[22:25], v[198:201], v[206:209], v[22:25]
	v_mfma_f32_16x16x32_bf16 v[50:53], v[158:161], v[210:213], v[50:53]
	v_mfma_f32_16x16x32_bf16 v[42:45], v[158:161], v[218:221], v[42:45]
	v_mfma_f32_16x16x32_bf16 v[34:37], v[186:189], v[218:221], v[34:37]
	v_mfma_f32_16x16x32_bf16 v[38:41], v[186:189], v[210:213], v[38:41]
	v_mfma_f32_16x16x32_bf16 v[30:33], v[194:197], v[210:213], v[30:33]
	v_mfma_f32_16x16x32_bf16 v[26:29], v[194:197], v[218:221], v[26:29]
	v_mfma_f32_16x16x32_bf16 v[18:21], v[202:205], v[218:221], v[18:21]
	v_mfma_f32_16x16x32_bf16 v[22:25], v[202:205], v[210:213], v[22:25]
	s_barrier
	s_setprio 0
	ds_read_b128 v[154:157], v176 offset:16384
	ds_read_b128 v[158:161], v176 offset:17408
	ds_read_b128 v[182:185], v176 offset:18432
	ds_read_b128 v[186:189], v176 offset:19456
	ds_read_b128 v[190:193], v176 offset:20480
	ds_read_b128 v[194:197], v176 offset:21504
	ds_read_b128 v[198:201], v176 offset:22528
	ds_read_b128 v[202:205], v176 offset:23552
	s_mov_b32 m0, s69
	s_nop 0
	global_load_lds_dwordx4 v224, s[100:101]
	s_mov_b32 m0, s70
	s_nop 0
	global_load_lds_dwordx4 v225, s[100:101]
	s_mov_b32 m0, s68
	s_nop 0
	global_load_lds_dwordx4 v226, s[98:99]
	s_mov_b32 m0, s71
	s_nop 0
	global_load_lds_dwordx4 v227, s[98:99]
	s_mov_b32 m0, s76
	s_nop 0
	global_load_lds_dwordx4 v228, s[100:101]
	s_mov_b32 m0, s77
	s_nop 0
	global_load_lds_dwordx4 v229, s[100:101]
	s_waitcnt vmcnt(8)
	s_waitcnt lgkmcnt(0)
	s_setprio 1
	s_barrier
	v_mfma_f32_16x16x32_bf16 v[14:17], v[154:157], v[138:141], v[14:17]
	v_mfma_f32_16x16x32_bf16 v[10:13], v[154:157], v[146:149], v[10:13]
	v_mfma_f32_16x16x32_bf16 v[2:5], v[182:185], v[146:149], v[2:5]
	v_mfma_f32_16x16x32_bf16 v[6:9], v[182:185], v[138:141], v[6:9]
	v_mfma_f32_16x16x32_bf16 v[46:49], v[190:193], v[138:141], v[46:49]
	v_mfma_f32_16x16x32_bf16 v[54:57], v[190:193], v[146:149], v[54:57]
	v_mfma_f32_16x16x32_bf16 v[62:65], v[198:201], v[146:149], v[62:65]
	v_mfma_f32_16x16x32_bf16 v[58:61], v[198:201], v[138:141], v[58:61]
	v_mfma_f32_16x16x32_bf16 v[14:17], v[158:161], v[142:145], v[14:17]
	v_mfma_f32_16x16x32_bf16 v[10:13], v[158:161], v[150:153], v[10:13]
	v_mfma_f32_16x16x32_bf16 v[2:5], v[186:189], v[150:153], v[2:5]
	v_mfma_f32_16x16x32_bf16 v[6:9], v[186:189], v[142:145], v[6:9]
	v_mfma_f32_16x16x32_bf16 v[46:49], v[194:197], v[142:145], v[46:49]
	v_mfma_f32_16x16x32_bf16 v[54:57], v[194:197], v[150:153], v[54:57]
	v_mfma_f32_16x16x32_bf16 v[62:65], v[202:205], v[150:153], v[62:65]
	v_mfma_f32_16x16x32_bf16 v[58:61], v[202:205], v[142:145], v[58:61]
	v_mfma_f32_16x16x32_bf16 v[66:69], v[154:157], v[206:209], v[66:69]
	v_mfma_f32_16x16x32_bf16 v[70:73], v[154:157], v[214:217], v[70:73]
	v_mfma_f32_16x16x32_bf16 v[78:81], v[182:185], v[214:217], v[78:81]
	v_mfma_f32_16x16x32_bf16 v[74:77], v[182:185], v[206:209], v[74:77]
	v_mfma_f32_16x16x32_bf16 v[82:85], v[190:193], v[206:209], v[82:85]
	v_mfma_f32_16x16x32_bf16 v[86:89], v[190:193], v[214:217], v[86:89]
	v_mfma_f32_16x16x32_bf16 v[98:101], v[198:201], v[214:217], v[98:101]
	v_mfma_f32_16x16x32_bf16 v[90:93], v[198:201], v[206:209], v[90:93]
	v_mfma_f32_16x16x32_bf16 v[66:69], v[158:161], v[210:213], v[66:69]
	v_mfma_f32_16x16x32_bf16 v[70:73], v[158:161], v[218:221], v[70:73]
	v_mfma_f32_16x16x32_bf16 v[78:81], v[186:189], v[218:221], v[78:81]
	v_mfma_f32_16x16x32_bf16 v[74:77], v[186:189], v[210:213], v[74:77]
	v_mfma_f32_16x16x32_bf16 v[82:85], v[194:197], v[210:213], v[82:85]
	v_mfma_f32_16x16x32_bf16 v[86:89], v[194:197], v[218:221], v[86:89]
	v_mfma_f32_16x16x32_bf16 v[98:101], v[202:205], v[218:221], v[98:101]
	v_mfma_f32_16x16x32_bf16 v[90:93], v[202:205], v[210:213], v[90:93]
	s_barrier
; #define LDA(dst, b, h)                                                                                     \
;   _Pragma("unroll") for (int m = 0; m < 4; ++m) _Pragma("unroll") for (int k = 0; k < 2; ++k) dst[m][k] = \
;       *reinterpret_cast<const bf16x8*>(shmc + aL + (((b) * 2 + (h)) * 16384 + (m * 2 + k) * 1024))
; #define LDB(dst, b, h)                                                                                     \
;   _Pragma("unroll") for (int n = 0; n < 2; ++n) _Pragma("unroll") for (int k = 0; k < 2; ++k) dst[n][k] = \
;       *reinterpret_cast<const bf16x8*>(shmc + bL + (((b) * 2 + (h)) * 16384 + (n * 2 + k) * 1024))
; #define WAIT_V(n) asm volatile("s_waitcnt vmcnt(" #n ")" ::: "memory")
; #define WAIT_L(n) asm volatile("s_waitcnt lgkmcnt(" #n ")" ::: "memory")
; #define BAR __builtin_amdgcn_s_barrier()
; #define SCHED __builtin_amdgcn_sched_barrier(0)
; template <int EPI>
; __device__ __forceinline__ void phase_gemm(const Params& p, const GemmDesc& d, char* shmc) {
;     ...
;       LDB(B0, 1, 0); SCHED; LDA(At, 1, 0); STAGE_A(SA(0, 1), 1, t + 2);
;       WAIT_L(8); BAR; WAIT_L(0); MMA(0, 0, At, B0); BAR; SCHED;
;       LDB(B1, 1, 1); STAGE_B(SB(1, 0), 0, t + 3);
;       BAR; WAIT_L(0); MMA(0, 1, At, B1); BAR;
;       LDA(At, 1, 1); STAGE_A(SA(1, 0), 0, t + 3);
;       BAR; WAIT_L(0); MMA(1, 0, At, B0); BAR; SCHED;
;       STAGE_B(SB(1, 1), 1, t + 3);
;       WAIT_V(6); BAR; MMA(1, 1, At, B1); BAR;
;     }
	s_setprio 0
	ds_read_b128 v[138:141], v175 offset:32768
	ds_read_b128 v[142:145], v175 offset:33792
	ds_read_b128 v[146:149], v175 offset:34816
	ds_read_b128 v[150:153], v175 offset:35840
	ds_read_b128 v[206:209], v175 offset:49152
	ds_read_b128 v[210:213], v175 offset:50176
	ds_read_b128 v[214:217], v175 offset:51200
	ds_read_b128 v[218:221], v175 offset:52224
	ds_read_b128 v[154:157], v176 offset:32768
	ds_read_b128 v[158:161], v176 offset:33792
	ds_read_b128 v[182:185], v176 offset:34816
	ds_read_b128 v[186:189], v176 offset:35840
	ds_read_b128 v[190:193], v176 offset:36864
	ds_read_b128 v[194:197], v176 offset:37888
	ds_read_b128 v[198:201], v176 offset:38912
	ds_read_b128 v[202:205], v176 offset:39936
	s_mov_b32 m0, s80
	s_nop 0
	global_load_lds_dwordx4 v230, s[98:99]
	s_mov_b32 m0, s81
	s_nop 0
	global_load_lds_dwordx4 v231, s[98:99]
	s_waitcnt vmcnt(8)
	s_waitcnt lgkmcnt(0)
	s_setprio 1
	s_barrier
	v_mfma_f32_16x16x32_bf16 v[126:129], v[154:157], v[138:141], v[126:129]
	v_mfma_f32_16x16x32_bf16 v[122:125], v[154:157], v[146:149], v[122:125]
	v_mfma_f32_16x16x32_bf16 v[114:117], v[182:185], v[146:149], v[114:117]
	v_mfma_f32_16x16x32_bf16 v[118:121], v[182:185], v[138:141], v[118:121]
	v_mfma_f32_16x16x32_bf16 v[110:113], v[190:193], v[138:141], v[110:113]
	v_mfma_f32_16x16x32_bf16 v[106:109], v[190:193], v[146:149], v[106:109]
	v_mfma_f32_16x16x32_bf16 v[94:97], v[198:201], v[146:149], v[94:97]
	v_mfma_f32_16x16x32_bf16 v[102:105], v[198:201], v[138:141], v[102:105]
	v_mfma_f32_16x16x32_bf16 v[126:129], v[158:161], v[142:145], v[126:129]
	v_mfma_f32_16x16x32_bf16 v[122:125], v[158:161], v[150:153], v[122:125]
	v_mfma_f32_16x16x32_bf16 v[114:117], v[186:189], v[150:153], v[114:117]
	v_mfma_f32_16x16x32_bf16 v[118:121], v[186:189], v[142:145], v[118:121]
	v_mfma_f32_16x16x32_bf16 v[110:113], v[194:197], v[142:145], v[110:113]
	v_mfma_f32_16x16x32_bf16 v[106:109], v[194:197], v[150:153], v[106:109]
	v_mfma_f32_16x16x32_bf16 v[94:97], v[202:205], v[150:153], v[94:97]
	v_mfma_f32_16x16x32_bf16 v[102:105], v[202:205], v[142:145], v[102:105]
	v_mfma_f32_16x16x32_bf16 v[50:53], v[154:157], v[206:209], v[50:53]
	v_mfma_f32_16x16x32_bf16 v[42:45], v[154:157], v[214:217], v[42:45]
	v_mfma_f32_16x16x32_bf16 v[34:37], v[182:185], v[214:217], v[34:37]
	v_mfma_f32_16x16x32_bf16 v[38:41], v[182:185], v[206:209], v[38:41]
	v_mfma_f32_16x16x32_bf16 v[30:33], v[190:193], v[206:209], v[30:33]
	v_mfma_f32_16x16x32_bf16 v[26:29], v[190:193], v[214:217], v[26:29]
	v_mfma_f32_16x16x32_bf16 v[18:21], v[198:201], v[214:217], v[18:21]
	v_mfma_f32_16x16x32_bf16 v[22:25], v[198:201], v[206:209], v[22:25]
	v_mfma_f32_16x16x32_bf16 v[50:53], v[158:161], v[210:213], v[50:53]
	v_mfma_f32_16x16x32_bf16 v[42:45], v[158:161], v[218:221], v[42:45]
	v_mfma_f32_16x16x32_bf16 v[34:37], v[186:189], v[218:221], v[34:37]
	v_mfma_f32_16x16x32_bf16 v[38:41], v[186:189], v[210:213], v[38:41]
	v_mfma_f32_16x16x32_bf16 v[30:33], v[194:197], v[210:213], v[30:33]
	v_mfma_f32_16x16x32_bf16 v[26:29], v[194:197], v[218:221], v[26:29]
	v_mfma_f32_16x16x32_bf16 v[18:21], v[202:205], v[218:221], v[18:21]
	v_mfma_f32_16x16x32_bf16 v[22:25], v[202:205], v[210:213], v[22:25]
	s_barrier
	s_setprio 0
	ds_read_b128 v[154:157], v176 offset:49152
	ds_read_b128 v[158:161], v176 offset:50176
	ds_read_b128 v[182:185], v176 offset:51200
	ds_read_b128 v[186:189], v176 offset:52224
	ds_read_b128 v[190:193], v176 offset:53248
	ds_read_b128 v[194:197], v176 offset:54272
	ds_read_b128 v[198:201], v176 offset:55296
	ds_read_b128 v[202:205], v176 offset:56320
	s_mov_b32 m0, s61
	s_nop 0
	global_load_lds_dwordx4 v232, s[100:101]
	s_mov_b32 m0, s78
	s_nop 0
	global_load_lds_dwordx4 v233, s[100:101]
	s_mov_b32 m0, s79
	s_nop 0
	global_load_lds_dwordx4 v234, s[98:99]
	s_mov_b32 m0, s86
	s_nop 0
	global_load_lds_dwordx4 v235, s[98:99]
	s_mov_b32 m0, s64
	s_nop 0
	global_load_lds_dwordx4 v236, s[100:101]
	s_mov_b32 m0, s65
	s_nop 0
	global_load_lds_dwordx4 v237, s[100:101]
	s_add_i32 s87, s87, 2
	s_add_u32 s62, s62, 0x100
	s_addc_u32 s63, s63, 0
	s_add_u32 s98, s98, 0x100
	s_addc_u32 s99, s99, 0
	s_add_u32 s100, s100, 0x100
	s_addc_u32 s101, s101, 0
	s_cmp_gt_u32 s87, 27
	s_waitcnt vmcnt(8)
	s_waitcnt lgkmcnt(0)
	s_setprio 1
	s_barrier
	v_mfma_f32_16x16x32_bf16 v[14:17], v[154:157], v[138:141], v[14:17]
	v_mfma_f32_16x16x32_bf16 v[10:13], v[154:157], v[146:149], v[10:13]
	v_mfma_f32_16x16x32_bf16 v[2:5], v[182:185], v[146:149], v[2:5]
	v_mfma_f32_16x16x32_bf16 v[6:9], v[182:185], v[138:141], v[6:9]
	v_mfma_f32_16x16x32_bf16 v[46:49], v[190:193], v[138:141], v[46:49]
	v_mfma_f32_16x16x32_bf16 v[54:57], v[190:193], v[146:149], v[54:57]
	v_mfma_f32_16x16x32_bf16 v[62:65], v[198:201], v[146:149], v[62:65]
	v_mfma_f32_16x16x32_bf16 v[58:61], v[198:201], v[138:141], v[58:61]
	v_mfma_f32_16x16x32_bf16 v[14:17], v[158:161], v[142:145], v[14:17]
	v_mfma_f32_16x16x32_bf16 v[10:13], v[158:161], v[150:153], v[10:13]
	v_mfma_f32_16x16x32_bf16 v[2:5], v[186:189], v[150:153], v[2:5]
	v_mfma_f32_16x16x32_bf16 v[6:9], v[186:189], v[142:145], v[6:9]
	v_mfma_f32_16x16x32_bf16 v[46:49], v[194:197], v[142:145], v[46:49]
	v_mfma_f32_16x16x32_bf16 v[54:57], v[194:197], v[150:153], v[54:57]
	v_mfma_f32_16x16x32_bf16 v[62:65], v[202:205], v[150:153], v[62:65]
	v_mfma_f32_16x16x32_bf16 v[58:61], v[202:205], v[142:145], v[58:61]
	v_mfma_f32_16x16x32_bf16 v[66:69], v[154:157], v[206:209], v[66:69]
	v_mfma_f32_16x16x32_bf16 v[70:73], v[154:157], v[214:217], v[70:73]
	v_mfma_f32_16x16x32_bf16 v[78:81], v[182:185], v[214:217], v[78:81]
	v_mfma_f32_16x16x32_bf16 v[74:77], v[182:185], v[206:209], v[74:77]
	v_mfma_f32_16x16x32_bf16 v[82:85], v[190:193], v[206:209], v[82:85]
	v_mfma_f32_16x16x32_bf16 v[86:89], v[190:193], v[214:217], v[86:89]
	v_mfma_f32_16x16x32_bf16 v[98:101], v[198:201], v[214:217], v[98:101]
	v_mfma_f32_16x16x32_bf16 v[90:93], v[198:201], v[206:209], v[90:93]
	v_mfma_f32_16x16x32_bf16 v[66:69], v[158:161], v[210:213], v[66:69]
	v_mfma_f32_16x16x32_bf16 v[70:73], v[158:161], v[218:221], v[70:73]
	v_mfma_f32_16x16x32_bf16 v[78:81], v[186:189], v[218:221], v[78:81]
	v_mfma_f32_16x16x32_bf16 v[74:77], v[186:189], v[210:213], v[74:77]
	v_mfma_f32_16x16x32_bf16 v[82:85], v[194:197], v[210:213], v[82:85]
	v_mfma_f32_16x16x32_bf16 v[86:89], v[194:197], v[218:221], v[86:89]
	v_mfma_f32_16x16x32_bf16 v[98:101], v[202:205], v[218:221], v[98:101]
	v_mfma_f32_16x16x32_bf16 v[90:93], v[202:205], v[210:213], v[90:93]
	s_barrier
; #define LDA(dst, b, h)                                                                                     \
;   _Pragma("unroll") for (int m = 0; m < 4; ++m) _Pragma("unroll") for (int k = 0; k < 2; ++k) dst[m][k] = \
;       *reinterpret_cast<const bf16x8*>(shmc + aL + (((b) * 2 + (h)) * 16384 + (m * 2 + k) * 1024))
; #define LDB(dst, b, h)                                                                                     \
;   _Pragma("unroll") for (int n = 0; n < 2; ++n) _Pragma("unroll") for (int k = 0; k < 2; ++k) dst[n][k] = \
;       *reinterpret_cast<const bf16x8*>(shmc + bL + (((b) * 2 + (h)) * 16384 + (n * 2 + k) * 1024))
; #define OPAQ asm volatile("" : "+v"(aL), "+v"(bL))
; #define WAIT_V(n) asm volatile("s_waitcnt vmcnt(" #n ")" ::: "memory")
; #define WAIT_L(n) asm volatile("s_waitcnt lgkmcnt(" #n ")" ::: "memory")
; #define BAR __builtin_amdgcn_s_barrier()
; template <int EPI>
; __device__ __forceinline__ void phase_gemm(const Params& p, const GemmDesc& d, char* shmc) {
;     ...
;     }
;     {
;       OPAQ;
;       LDB(B0, 0, 0); LDA(At, 0, 0); STAGE_A(SA(1, 1), 1, nt - 1);
;       BAR; WAIT_L(0); MMA(0, 0, At, B0); BAR;
;       LDB(B1, 0, 1); BAR; WAIT_L(0); MMA(0, 1, At, B1); BAR;
;       LDA(At, 0, 1); WAIT_V(4); BAR; WAIT_L(0); MMA(1, 0, At, B0); MMA(1, 1, At, B1); BAR;
	s_cbranch_scc0 .LBB0_598
	s_setprio 0
	s_add_u32 s8, s8, 0x80f80
	s_addc_u32 s9, s9, 0
	v_add_u32_e32 v175, 0, v179
	v_add_u32_e32 v176, 0, v177
	s_mov_b32 m0, s88
	ds_read_b128 v[130:133], v175
	ds_read_b128 v[134:137], v175 offset:1024
	ds_read_b128 v[138:141], v175 offset:2048
	ds_read_b128 v[142:145], v175 offset:3072
	ds_read_b128 v[146:149], v176
	ds_read_b128 v[150:153], v176 offset:1024
	ds_read_b128 v[154:157], v176 offset:2048
	ds_read_b128 v[158:161], v176 offset:3072
	ds_read_b128 v[182:185], v176 offset:4096
	ds_read_b128 v[186:189], v176 offset:5120
	ds_read_b128 v[190:193], v176 offset:6144
	ds_read_b128 v[194:197], v176 offset:7168
	global_load_lds_dwordx4 v162, s[8:9]
	s_mov_b32 m0, s89
	s_nop 0
	global_load_lds_dwordx4 v174, s[8:9]
	s_waitcnt vmcnt(8)
	s_barrier
	s_waitcnt lgkmcnt(0)
	s_setprio 1
	s_waitcnt lgkmcnt(0)
	v_mfma_f32_16x16x32_bf16 v[126:129], v[146:149], v[130:133], v[126:129]
	v_mfma_f32_16x16x32_bf16 v[122:125], v[146:149], v[138:141], v[122:125]
	v_mfma_f32_16x16x32_bf16 v[114:117], v[154:157], v[138:141], v[114:117]
	v_mfma_f32_16x16x32_bf16 v[110:113], v[182:185], v[130:133], v[110:113]
	v_mfma_f32_16x16x32_bf16 v[126:129], v[150:153], v[134:137], v[126:129]
	v_mfma_f32_16x16x32_bf16 v[122:125], v[150:153], v[142:145], v[122:125]
	v_mfma_f32_16x16x32_bf16 v[118:121], v[154:157], v[130:133], v[118:121]
	v_mfma_f32_16x16x32_bf16 v[114:117], v[158:161], v[142:145], v[114:117]
	v_mfma_f32_16x16x32_bf16 v[110:113], v[186:189], v[134:137], v[110:113]
	v_mfma_f32_16x16x32_bf16 v[106:109], v[182:185], v[138:141], v[106:109]
	v_mfma_f32_16x16x32_bf16 v[102:105], v[190:193], v[130:133], v[102:105]
	v_mfma_f32_16x16x32_bf16 v[94:97], v[190:193], v[138:141], v[94:97]
	v_mfma_f32_16x16x32_bf16 v[118:121], v[158:161], v[134:137], v[118:121]
	v_mfma_f32_16x16x32_bf16 v[106:109], v[186:189], v[142:145], v[106:109]
	v_mfma_f32_16x16x32_bf16 v[102:105], v[194:197], v[134:137], v[102:105]
	v_mfma_f32_16x16x32_bf16 v[94:97], v[194:197], v[142:145], v[94:97]
	s_setprio 0
	s_barrier
	ds_read_b128 v[198:201], v175 offset:16384
	ds_read_b128 v[202:205], v175 offset:17408
	ds_read_b128 v[206:209], v175 offset:18432
	ds_read_b128 v[210:213], v175 offset:19456
	s_barrier
	s_waitcnt lgkmcnt(0)
	s_setprio 1
	s_waitcnt lgkmcnt(0)
	v_mfma_f32_16x16x32_bf16 v[50:53], v[146:149], v[198:201], v[50:53]
	v_mfma_f32_16x16x32_bf16 v[42:45], v[146:149], v[206:209], v[42:45]
	v_mfma_f32_16x16x32_bf16 v[38:41], v[154:157], v[198:201], v[38:41]
	v_mfma_f32_16x16x32_bf16 v[30:33], v[182:185], v[198:201], v[30:33]
	v_mfma_f32_16x16x32_bf16 v[22:25], v[190:193], v[198:201], v[22:25]
	v_mfma_f32_16x16x32_bf16 v[50:53], v[150:153], v[202:205], v[50:53]
	v_mfma_f32_16x16x32_bf16 v[42:45], v[150:153], v[210:213], v[42:45]
	v_mfma_f32_16x16x32_bf16 v[38:41], v[158:161], v[202:205], v[38:41]
	v_mfma_f32_16x16x32_bf16 v[34:37], v[154:157], v[206:209], v[34:37]
	v_mfma_f32_16x16x32_bf16 v[30:33], v[186:189], v[202:205], v[30:33]
	v_mfma_f32_16x16x32_bf16 v[26:29], v[182:185], v[206:209], v[26:29]
	v_mfma_f32_16x16x32_bf16 v[22:25], v[194:197], v[202:205], v[22:25]
	v_mfma_f32_16x16x32_bf16 v[18:21], v[190:193], v[206:209], v[18:21]
	v_mfma_f32_16x16x32_bf16 v[34:37], v[158:161], v[210:213], v[34:37]
	v_mfma_f32_16x16x32_bf16 v[26:29], v[186:189], v[210:213], v[26:29]
	v_mfma_f32_16x16x32_bf16 v[18:21], v[194:197], v[210:213], v[18:21]
	s_setprio 0
	s_barrier
	ds_read_b128 v[146:149], v176 offset:16384
	ds_read_b128 v[150:153], v176 offset:17408
	ds_read_b128 v[154:157], v176 offset:18432
	ds_read_b128 v[158:161], v176 offset:19456
	ds_read_b128 v[182:185], v176 offset:20480
	ds_read_b128 v[186:189], v176 offset:21504
	ds_read_b128 v[190:193], v176 offset:22528
	ds_read_b128 v[194:197], v176 offset:23552
	s_waitcnt vmcnt(4)
	s_barrier
	s_waitcnt lgkmcnt(0)
	s_setprio 1
	s_waitcnt lgkmcnt(0)
	v_mfma_f32_16x16x32_bf16 v[14:17], v[146:149], v[130:133], v[14:17]
	v_mfma_f32_16x16x32_bf16 v[6:9], v[154:157], v[130:133], v[6:9]
	v_mfma_f32_16x16x32_bf16 v[2:5], v[154:157], v[138:141], v[2:5]
	v_mfma_f32_16x16x32_bf16 v[46:49], v[182:185], v[130:133], v[46:49]
	v_mfma_f32_16x16x32_bf16 v[54:57], v[182:185], v[138:141], v[54:57]
	v_mfma_f32_16x16x32_bf16 v[58:61], v[190:193], v[130:133], v[58:61]
	v_mfma_f32_16x16x32_bf16 v[14:17], v[150:153], v[134:137], v[14:17]
	v_mfma_f32_16x16x32_bf16 v[10:13], v[146:149], v[138:141], v[10:13]
	v_mfma_f32_16x16x32_bf16 v[6:9], v[158:161], v[134:137], v[6:9]
	v_mfma_f32_16x16x32_bf16 v[2:5], v[158:161], v[142:145], v[2:5]
	v_mfma_f32_16x16x32_bf16 v[46:49], v[186:189], v[134:137], v[46:49]
	v_mfma_f32_16x16x32_bf16 v[54:57], v[186:189], v[142:145], v[54:57]
	v_mfma_f32_16x16x32_bf16 v[214:217], v[194:197], v[134:137], v[58:61]
	v_mfma_f32_16x16x32_bf16 v[58:61], v[190:193], v[138:141], v[62:65]
	v_mfma_f32_16x16x32_bf16 v[10:13], v[150:153], v[142:145], v[10:13]
	v_mfma_f32_16x16x32_bf16 v[218:221], v[194:197], v[142:145], v[58:61]
	s_setprio 0
	s_setprio 1
	v_mfma_f32_16x16x32_bf16 v[58:61], v[146:149], v[198:201], v[66:69]
	v_mfma_f32_16x16x32_bf16 v[222:225], v[150:153], v[202:205], v[58:61]
	v_mfma_f32_16x16x32_bf16 v[58:61], v[146:149], v[206:209], v[70:73]
	v_mfma_f32_16x16x32_bf16 v[226:229], v[150:153], v[210:213], v[58:61]
	v_mfma_f32_16x16x32_bf16 v[58:61], v[154:157], v[198:201], v[74:77]
	v_mfma_f32_16x16x32_bf16 v[230:233], v[158:161], v[202:205], v[58:61]
	v_mfma_f32_16x16x32_bf16 v[58:61], v[154:157], v[206:209], v[78:81]
	v_mfma_f32_16x16x32_bf16 v[234:237], v[158:161], v[210:213], v[58:61]
	v_mfma_f32_16x16x32_bf16 v[58:61], v[182:185], v[198:201], v[82:85]
	v_mfma_f32_16x16x32_bf16 v[238:241], v[186:189], v[202:205], v[58:61]
	v_mfma_f32_16x16x32_bf16 v[58:61], v[182:185], v[206:209], v[86:89]
	v_mfma_f32_16x16x32_bf16 v[182:185], v[186:189], v[210:213], v[58:61]
	v_mfma_f32_16x16x32_bf16 v[58:61], v[190:193], v[198:201], v[90:93]
	v_mfma_f32_16x16x32_bf16 v[186:189], v[194:197], v[202:205], v[58:61]
	v_mfma_f32_16x16x32_bf16 v[58:61], v[190:193], v[206:209], v[98:101]
	v_mfma_f32_16x16x32_bf16 v[190:193], v[194:197], v[210:213], v[58:61]
	s_setprio 0
	s_barrier
; #define LDA(dst, b, h)                                                                                     \
;   _Pragma("unroll") for (int m = 0; m < 4; ++m) _Pragma("unroll") for (int k = 0; k < 2; ++k) dst[m][k] = \
;       *reinterpret_cast<const bf16x8*>(shmc + aL + (((b) * 2 + (h)) * 16384 + (m * 2 + k) * 1024))
; #define LDB(dst, b, h)                                                                                     \
;   _Pragma("unroll") for (int n = 0; n < 2; ++n) _Pragma("unroll") for (int k = 0; k < 2; ++k) dst[n][k] = \
;       *reinterpret_cast<const bf16x8*>(shmc + bL + (((b) * 2 + (h)) * 16384 + (n * 2 + k) * 1024))
; #define WAIT_V(n) asm volatile("s_waitcnt vmcnt(" #n ")" ::: "memory")
; #define WAIT_L(n) asm volatile("s_waitcnt lgkmcnt(" #n ")" ::: "memory")
; #define BAR __builtin_amdgcn_s_barrier()
; template <int EPI>
; __device__ __forceinline__ void phase_gemm(const Params& p, const GemmDesc& d, char* shmc) {
;     ...
;     {
;       LDB(B0, 1, 0); LDA(At, 1, 0); WAIT_V(2); BAR; WAIT_L(0); MMA(0, 0, At, B0); BAR;
;       LDB(B1, 1, 1); WAIT_V(0); BAR; WAIT_L(0); MMA(0, 1, At, B1); BAR;
;       LDA(At, 1, 1); BAR; WAIT_L(0); MMA(1, 0, At, B0); MMA(1, 1, At, B1); BAR;
;     }
;     if (wr == 0) BAR;
	ds_read_b128 v[66:69], v175 offset:32768
	ds_read_b128 v[194:197], v175 offset:33792
	ds_read_b128 v[198:201], v175 offset:34816
	ds_read_b128 v[202:205], v175 offset:35840
	s_nop 0
	ds_read_b128 v[58:61], v176 offset:32768
	ds_read_b128 v[62:65], v176 offset:33792
	ds_read_b128 v[70:73], v176 offset:34816
	ds_read_b128 v[74:77], v176 offset:35840
	ds_read_b128 v[78:81], v176 offset:36864
	ds_read_b128 v[82:85], v176 offset:37888
	ds_read_b128 v[206:209], v176 offset:38912
	ds_read_b128 v[210:213], v176 offset:39936
	s_waitcnt vmcnt(2)
	s_barrier
	s_waitcnt lgkmcnt(0)
	s_setprio 1
	s_waitcnt lgkmcnt(0)
	v_mfma_f32_16x16x32_bf16 v[86:89], v[58:61], v[66:69], v[126:129]
	v_mfma_f32_16x16x32_bf16 v[158:161], v[62:65], v[194:197], v[86:89]
	v_mfma_f32_16x16x32_bf16 v[86:89], v[58:61], v[198:201], v[122:125]
	v_mfma_f32_16x16x32_bf16 v[142:145], v[62:65], v[202:205], v[86:89]
	v_mfma_f32_16x16x32_bf16 v[86:89], v[70:73], v[66:69], v[118:121]
	v_mfma_f32_16x16x32_bf16 v[154:157], v[74:77], v[194:197], v[86:89]
	v_mfma_f32_16x16x32_bf16 v[86:89], v[70:73], v[198:201], v[114:117]
	v_mfma_f32_16x16x32_bf16 v[138:141], v[74:77], v[202:205], v[86:89]
	v_mfma_f32_16x16x32_bf16 v[86:89], v[78:81], v[66:69], v[110:113]
	v_mfma_f32_16x16x32_bf16 v[150:153], v[82:85], v[194:197], v[86:89]
	v_mfma_f32_16x16x32_bf16 v[86:89], v[78:81], v[198:201], v[106:109]
	v_mfma_f32_16x16x32_bf16 v[134:137], v[82:85], v[202:205], v[86:89]
	v_mfma_f32_16x16x32_bf16 v[86:89], v[206:209], v[66:69], v[102:105]
	v_mfma_f32_16x16x32_bf16 v[146:149], v[210:213], v[194:197], v[86:89]
	v_mfma_f32_16x16x32_bf16 v[86:89], v[206:209], v[198:201], v[94:97]
	v_mfma_f32_16x16x32_bf16 v[130:133], v[210:213], v[202:205], v[86:89]
	s_setprio 0
	s_barrier
	ds_read_b128 v[94:97], v175 offset:49152
	ds_read_b128 v[102:105], v175 offset:50176
	ds_read_b128 v[106:109], v175 offset:51200
	ds_read_b128 v[118:121], v175 offset:52224
	s_waitcnt vmcnt(0)
	s_barrier
	s_waitcnt lgkmcnt(0)
	s_setprio 1
	s_waitcnt lgkmcnt(0)
	v_mfma_f32_16x16x32_bf16 v[50:53], v[58:61], v[94:97], v[50:53]
	v_mfma_f32_16x16x32_bf16 v[42:45], v[58:61], v[106:109], v[42:45]
	v_mfma_f32_16x16x32_bf16 v[38:41], v[70:73], v[94:97], v[38:41]
	v_mfma_f32_16x16x32_bf16 v[34:37], v[70:73], v[106:109], v[34:37]
	v_mfma_f32_16x16x32_bf16 v[30:33], v[78:81], v[94:97], v[30:33]
	v_mfma_f32_16x16x32_bf16 v[26:29], v[78:81], v[106:109], v[26:29]
	v_mfma_f32_16x16x32_bf16 v[22:25], v[206:209], v[94:97], v[22:25]
	v_mfma_f32_16x16x32_bf16 v[18:21], v[206:209], v[106:109], v[18:21]
	v_mfma_f32_16x16x32_bf16 v[126:129], v[62:65], v[102:105], v[50:53]
	v_mfma_f32_16x16x32_bf16 v[98:101], v[62:65], v[118:121], v[42:45]
	v_mfma_f32_16x16x32_bf16 v[122:125], v[74:77], v[102:105], v[38:41]
	v_mfma_f32_16x16x32_bf16 v[90:93], v[74:77], v[118:121], v[34:37]
	v_mfma_f32_16x16x32_bf16 v[114:117], v[82:85], v[102:105], v[30:33]
	v_mfma_f32_16x16x32_bf16 v[86:89], v[82:85], v[118:121], v[26:29]
	v_mfma_f32_16x16x32_bf16 v[110:113], v[210:213], v[102:105], v[22:25]
	v_mfma_f32_16x16x32_bf16 v[82:85], v[210:213], v[118:121], v[18:21]
	s_setprio 0
	s_barrier
	s_nop 0
	ds_read_b128 v[18:21], v176 offset:49152
	ds_read_b128 v[22:25], v176 offset:50176
	ds_read_b128 v[26:29], v176 offset:51200
	ds_read_b128 v[30:33], v176 offset:52224
	ds_read_b128 v[34:37], v176 offset:53248
	ds_read_b128 v[206:209], v176 offset:54272
	ds_read_b128 v[210:213], v176 offset:55296
	ds_read_b128 v[242:245], v176 offset:56320
	s_barrier
	s_waitcnt lgkmcnt(0)
	s_setprio 1
	s_waitcnt lgkmcnt(0)
	v_mfma_f32_16x16x32_bf16 v[2:5], v[26:29], v[198:201], v[2:5]
	v_mfma_f32_16x16x32_bf16 v[58:61], v[30:33], v[202:205], v[2:5]
	v_mfma_f32_16x16x32_bf16 v[2:5], v[34:37], v[66:69], v[46:49]
	v_mfma_f32_16x16x32_bf16 v[70:73], v[206:209], v[194:197], v[2:5]
	v_mfma_f32_16x16x32_bf16 v[2:5], v[34:37], v[198:201], v[54:57]
	v_mfma_f32_16x16x32_bf16 v[54:57], v[206:209], v[202:205], v[2:5]
	v_mfma_f32_16x16x32_bf16 v[2:5], v[210:213], v[66:69], v[214:217]
	v_mfma_f32_16x16x32_bf16 v[14:17], v[18:21], v[66:69], v[14:17]
	v_mfma_f32_16x16x32_bf16 v[10:13], v[18:21], v[198:201], v[10:13]
	v_mfma_f32_16x16x32_bf16 v[6:9], v[26:29], v[66:69], v[6:9]
	v_mfma_f32_16x16x32_bf16 v[66:69], v[242:245], v[194:197], v[2:5]
	v_mfma_f32_16x16x32_bf16 v[2:5], v[210:213], v[198:201], v[218:221]
	v_mfma_f32_16x16x32_bf16 v[78:81], v[22:25], v[194:197], v[14:17]
	v_mfma_f32_16x16x32_bf16 v[62:65], v[22:25], v[202:205], v[10:13]
	v_mfma_f32_16x16x32_bf16 v[74:77], v[30:33], v[194:197], v[6:9]
	v_mfma_f32_16x16x32_bf16 v[50:53], v[242:245], v[202:205], v[2:5]
	s_setprio 0
	s_setprio 1
	v_mfma_f32_16x16x32_bf16 v[2:5], v[18:21], v[94:97], v[222:225]
	v_mfma_f32_16x16x32_bf16 v[46:49], v[22:25], v[102:105], v[2:5]
	v_mfma_f32_16x16x32_bf16 v[2:5], v[18:21], v[106:109], v[226:229]
	v_mfma_f32_16x16x32_bf16 v[22:25], v[22:25], v[118:121], v[2:5]
	v_mfma_f32_16x16x32_bf16 v[2:5], v[26:29], v[94:97], v[230:233]
	v_mfma_f32_16x16x32_bf16 v[42:45], v[30:33], v[102:105], v[2:5]
	v_mfma_f32_16x16x32_bf16 v[2:5], v[26:29], v[106:109], v[234:237]
	v_mfma_f32_16x16x32_bf16 v[14:17], v[30:33], v[118:121], v[2:5]
	v_mfma_f32_16x16x32_bf16 v[2:5], v[34:37], v[94:97], v[238:241]
	v_mfma_f32_16x16x32_bf16 v[38:41], v[206:209], v[102:105], v[2:5]
	v_mfma_f32_16x16x32_bf16 v[2:5], v[34:37], v[106:109], v[182:185]
	v_mfma_f32_16x16x32_bf16 v[6:9], v[206:209], v[118:121], v[2:5]
	v_mfma_f32_16x16x32_bf16 v[2:5], v[210:213], v[94:97], v[186:189]
	v_mfma_f32_16x16x32_bf16 v[30:33], v[242:245], v[102:105], v[2:5]
	v_mfma_f32_16x16x32_bf16 v[2:5], v[210:213], v[106:109], v[190:193]
	v_mfma_f32_16x16x32_bf16 v[2:5], v[242:245], v[118:121], v[2:5]
	s_setprio 0
	s_barrier
	s_and_saveexec_b64 s[8:9], s[6:7]
	s_cbranch_execz .LBB0_601
	s_barrier

; #define LDA(dst, b, h)                                                                                     \
;   _Pragma("unroll") for (int m = 0; m < 4; ++m) _Pragma("unroll") for (int k = 0; k < 2; ++k) dst[m][k] = \
;       *reinterpret_cast<const bf16x8*>(shmc + aL + (((b) * 2 + (h)) * 16384 + (m * 2 + k) * 1024))
; #define LDB(dst, b, h)                                                                                     \
;   _Pragma("unroll") for (int n = 0; n < 2; ++n) _Pragma("unroll") for (int k = 0; k < 2; ++k) dst[n][k] = \
;       *reinterpret_cast<const bf16x8*>(shmc + bL + (((b) * 2 + (h)) * 16384 + (n * 2 + k) * 1024))
; #define OPAQ asm volatile("" : "+v"(aL), "+v"(bL))
; #define WAIT_V(n) asm volatile("s_waitcnt vmcnt(" #n ")" ::: "memory")
; #define WAIT_L(n) asm volatile("s_waitcnt lgkmcnt(" #n ")" ::: "memory")
; #define BAR __builtin_amdgcn_s_barrier()
; #define SCHED __builtin_amdgcn_sched_barrier(0)
; template <int EPI>
; __device__ __forceinline__ void phase_gemm(const Params& p, const GemmDesc& d, char* shmc) {
;     ...
;     for (int t = 0; t < nt - 2; t += 2) {
;       OPAQ;
;       LDB(B0, 0, 0); SCHED; LDA(At, 0, 0); STAGE_A(SA(1, 1), 1, t + 1);
;       WAIT_L(8); BAR; WAIT_L(0); MMA(0, 0, At, B0); BAR; SCHED;
;       LDB(B1, 0, 1); STAGE_B(SB(0, 0), 0, t + 2);
;       BAR; WAIT_L(0); MMA(0, 1, At, B1); BAR;
;       LDA(At, 0, 1); STAGE_A(SA(0, 0), 0, t + 2);
;       BAR; WAIT_L(0); MMA(1, 0, At, B0); BAR; SCHED;
;       STAGE_B(SB(0, 1), 1, t + 2);
;       WAIT_V(6); BAR; MMA(1, 1, At, B1); BAR;
.LBB0_1010:
	s_nop 0
	v_add_u32_e32 v130, 0, v153
	v_add_u32_e32 v141, 0, v152
	s_setprio 0
	ds_read_b128 v[156:159], v130
	ds_read_b128 v[160:163], v130 offset:1024
	ds_read_b128 v[164:167], v130 offset:2048
	ds_read_b128 v[168:171], v130 offset:3072
	ds_read_b128 v[204:207], v130 offset:16384
	ds_read_b128 v[208:211], v130 offset:17408
	ds_read_b128 v[212:215], v130 offset:18432
	ds_read_b128 v[216:219], v130 offset:19456
	ds_read_b128 v[172:175], v141
	ds_read_b128 v[176:179], v141 offset:1024
	ds_read_b128 v[180:183], v141 offset:2048
	ds_read_b128 v[184:187], v141 offset:3072
	ds_read_b128 v[188:191], v141 offset:4096
	ds_read_b128 v[192:195], v141 offset:5120
	ds_read_b128 v[196:199], v141 offset:6144
	ds_read_b128 v[200:203], v141 offset:7168
	s_mov_b32 m0, s80
	s_nop 0
	global_load_lds_dwordx4 v220, s[98:99]
	s_mov_b32 m0, s81
	s_nop 0
	global_load_lds_dwordx4 v221, s[98:99]
	s_waitcnt vmcnt(8)
	s_waitcnt lgkmcnt(0)
	s_setprio 1
	s_barrier
	v_mfma_f32_16x16x32_bf16 v[126:129], v[156:159], v[172:175], v[126:129]
	v_mfma_f32_16x16x32_bf16 v[122:125], v[164:167], v[172:175], v[122:125]
	v_mfma_f32_16x16x32_bf16 v[114:117], v[164:167], v[180:183], v[114:117]
	v_mfma_f32_16x16x32_bf16 v[118:121], v[156:159], v[180:183], v[118:121]
	v_mfma_f32_16x16x32_bf16 v[110:113], v[156:159], v[188:191], v[110:113]
	v_mfma_f32_16x16x32_bf16 v[106:109], v[164:167], v[188:191], v[106:109]
	v_mfma_f32_16x16x32_bf16 v[98:101], v[164:167], v[196:199], v[98:101]
	v_mfma_f32_16x16x32_bf16 v[102:105], v[156:159], v[196:199], v[102:105]
	v_mfma_f32_16x16x32_bf16 v[126:129], v[160:163], v[176:179], v[126:129]
	v_mfma_f32_16x16x32_bf16 v[122:125], v[168:171], v[176:179], v[122:125]
	v_mfma_f32_16x16x32_bf16 v[114:117], v[168:171], v[184:187], v[114:117]
	v_mfma_f32_16x16x32_bf16 v[118:121], v[160:163], v[184:187], v[118:121]
	v_mfma_f32_16x16x32_bf16 v[110:113], v[160:163], v[192:195], v[110:113]
	v_mfma_f32_16x16x32_bf16 v[106:109], v[168:171], v[192:195], v[106:109]
	v_mfma_f32_16x16x32_bf16 v[98:101], v[168:171], v[200:203], v[98:101]
	v_mfma_f32_16x16x32_bf16 v[102:105], v[160:163], v[200:203], v[102:105]
	v_mfma_f32_16x16x32_bf16 v[86:89], v[204:207], v[172:175], v[86:89]
	v_mfma_f32_16x16x32_bf16 v[70:73], v[212:215], v[172:175], v[70:73]
	v_mfma_f32_16x16x32_bf16 v[50:53], v[212:215], v[180:183], v[50:53]
	v_mfma_f32_16x16x32_bf16 v[54:57], v[204:207], v[180:183], v[54:57]
	v_mfma_f32_16x16x32_bf16 v[46:49], v[204:207], v[188:191], v[46:49]
	v_mfma_f32_16x16x32_bf16 v[42:45], v[212:215], v[188:191], v[42:45]
	v_mfma_f32_16x16x32_bf16 v[34:37], v[212:215], v[196:199], v[34:37]
	v_mfma_f32_16x16x32_bf16 v[38:41], v[204:207], v[196:199], v[38:41]
	v_mfma_f32_16x16x32_bf16 v[86:89], v[208:211], v[176:179], v[86:89]
	v_mfma_f32_16x16x32_bf16 v[70:73], v[216:219], v[176:179], v[70:73]
	v_mfma_f32_16x16x32_bf16 v[50:53], v[216:219], v[184:187], v[50:53]
	v_mfma_f32_16x16x32_bf16 v[54:57], v[208:211], v[184:187], v[54:57]
	v_mfma_f32_16x16x32_bf16 v[46:49], v[208:211], v[192:195], v[46:49]
	v_mfma_f32_16x16x32_bf16 v[42:45], v[216:219], v[192:195], v[42:45]
	v_mfma_f32_16x16x32_bf16 v[34:37], v[216:219], v[200:203], v[34:37]
	v_mfma_f32_16x16x32_bf16 v[38:41], v[208:211], v[200:203], v[38:41]
	s_barrier
	s_setprio 0
	ds_read_b128 v[172:175], v141 offset:16384
	ds_read_b128 v[176:179], v141 offset:17408
	ds_read_b128 v[180:183], v141 offset:18432
	ds_read_b128 v[184:187], v141 offset:19456
	ds_read_b128 v[188:191], v141 offset:20480
	ds_read_b128 v[192:195], v141 offset:21504
	ds_read_b128 v[196:199], v141 offset:22528
	ds_read_b128 v[200:203], v141 offset:23552
	s_mov_b32 m0, s35
	s_nop 0
	global_load_lds_dwordx4 v222, s[100:101]
	s_mov_b32 m0, s64
	s_nop 0
	global_load_lds_dwordx4 v223, s[100:101]
	s_mov_b32 m0, s34
	s_nop 0
	global_load_lds_dwordx4 v224, s[98:99]
	s_mov_b32 m0, s65
	s_nop 0
	global_load_lds_dwordx4 v225, s[98:99]
	s_mov_b32 m0, s66
	s_nop 0
	global_load_lds_dwordx4 v226, s[100:101]
	s_mov_b32 m0, s67
	s_nop 0
	global_load_lds_dwordx4 v227, s[100:101]
	s_waitcnt vmcnt(8)
	s_waitcnt lgkmcnt(0)
	s_setprio 1
	s_barrier
	v_mfma_f32_16x16x32_bf16 v[30:33], v[156:159], v[172:175], v[30:33]
	v_mfma_f32_16x16x32_bf16 v[26:29], v[164:167], v[172:175], v[26:29]
	v_mfma_f32_16x16x32_bf16 v[18:21], v[164:167], v[180:183], v[18:21]
	v_mfma_f32_16x16x32_bf16 v[22:25], v[156:159], v[180:183], v[22:25]
	v_mfma_f32_16x16x32_bf16 v[14:17], v[156:159], v[188:191], v[14:17]
	v_mfma_f32_16x16x32_bf16 v[10:13], v[164:167], v[188:191], v[10:13]
	v_mfma_f32_16x16x32_bf16 v[2:5], v[164:167], v[196:199], v[2:5]
	v_mfma_f32_16x16x32_bf16 v[6:9], v[156:159], v[196:199], v[6:9]
	v_mfma_f32_16x16x32_bf16 v[30:33], v[160:163], v[176:179], v[30:33]
	v_mfma_f32_16x16x32_bf16 v[26:29], v[168:171], v[176:179], v[26:29]
	v_mfma_f32_16x16x32_bf16 v[18:21], v[168:171], v[184:187], v[18:21]
	v_mfma_f32_16x16x32_bf16 v[22:25], v[160:163], v[184:187], v[22:25]
	v_mfma_f32_16x16x32_bf16 v[14:17], v[160:163], v[192:195], v[14:17]
	v_mfma_f32_16x16x32_bf16 v[10:13], v[168:171], v[192:195], v[10:13]
	v_mfma_f32_16x16x32_bf16 v[2:5], v[168:171], v[200:203], v[2:5]
	v_mfma_f32_16x16x32_bf16 v[6:9], v[160:163], v[200:203], v[6:9]
	v_mfma_f32_16x16x32_bf16 v[58:61], v[204:207], v[172:175], v[58:61]
	v_mfma_f32_16x16x32_bf16 v[62:65], v[212:215], v[172:175], v[62:65]
	v_mfma_f32_16x16x32_bf16 v[74:77], v[212:215], v[180:183], v[74:77]
	v_mfma_f32_16x16x32_bf16 v[66:69], v[204:207], v[180:183], v[66:69]
	v_mfma_f32_16x16x32_bf16 v[78:81], v[204:207], v[188:191], v[78:81]
	v_mfma_f32_16x16x32_bf16 v[82:85], v[212:215], v[188:191], v[82:85]
	v_mfma_f32_16x16x32_bf16 v[94:97], v[212:215], v[196:199], v[94:97]
	v_mfma_f32_16x16x32_bf16 v[90:93], v[204:207], v[196:199], v[90:93]
	v_mfma_f32_16x16x32_bf16 v[58:61], v[208:211], v[176:179], v[58:61]
	v_mfma_f32_16x16x32_bf16 v[62:65], v[216:219], v[176:179], v[62:65]
	v_mfma_f32_16x16x32_bf16 v[74:77], v[216:219], v[184:187], v[74:77]
	v_mfma_f32_16x16x32_bf16 v[66:69], v[208:211], v[184:187], v[66:69]
	v_mfma_f32_16x16x32_bf16 v[78:81], v[208:211], v[192:195], v[78:81]
	v_mfma_f32_16x16x32_bf16 v[82:85], v[216:219], v[192:195], v[82:85]
	v_mfma_f32_16x16x32_bf16 v[94:97], v[216:219], v[200:203], v[94:97]
	v_mfma_f32_16x16x32_bf16 v[90:93], v[208:211], v[200:203], v[90:93]
	s_barrier
; #define LDA(dst, b, h)                                                                                     \
;   _Pragma("unroll") for (int m = 0; m < 4; ++m) _Pragma("unroll") for (int k = 0; k < 2; ++k) dst[m][k] = \
;       *reinterpret_cast<const bf16x8*>(shmc + aL + (((b) * 2 + (h)) * 16384 + (m * 2 + k) * 1024))
; #define LDB(dst, b, h)                                                                                     \
;   _Pragma("unroll") for (int n = 0; n < 2; ++n) _Pragma("unroll") for (int k = 0; k < 2; ++k) dst[n][k] = \
;       *reinterpret_cast<const bf16x8*>(shmc + bL + (((b) * 2 + (h)) * 16384 + (n * 2 + k) * 1024))
; #define WAIT_V(n) asm volatile("s_waitcnt vmcnt(" #n ")" ::: "memory")
; #define WAIT_L(n) asm volatile("s_waitcnt lgkmcnt(" #n ")" ::: "memory")
; #define BAR __builtin_amdgcn_s_barrier()
; #define SCHED __builtin_amdgcn_sched_barrier(0)
; template <int EPI>
; __device__ __forceinline__ void phase_gemm(const Params& p, const GemmDesc& d, char* shmc) {
;     ...
;       LDB(B0, 1, 0); SCHED; LDA(At, 1, 0); STAGE_A(SA(0, 1), 1, t + 2);
;       WAIT_L(8); BAR; WAIT_L(0); MMA(0, 0, At, B0); BAR; SCHED;
;       LDB(B1, 1, 1); STAGE_B(SB(1, 0), 0, t + 3);
;       BAR; WAIT_L(0); MMA(0, 1, At, B1); BAR;
;       LDA(At, 1, 1); STAGE_A(SA(1, 0), 0, t + 3);
;       BAR; WAIT_L(0); MMA(1, 0, At, B0); BAR; SCHED;
;       STAGE_B(SB(1, 1), 1, t + 3);
;       WAIT_V(6); BAR; MMA(1, 1, At, B1); BAR;
;     }
	s_setprio 0
	ds_read_b128 v[156:159], v130 offset:32768
	ds_read_b128 v[160:163], v130 offset:33792
	ds_read_b128 v[164:167], v130 offset:34816
	ds_read_b128 v[168:171], v130 offset:35840
	ds_read_b128 v[204:207], v130 offset:49152
	ds_read_b128 v[208:211], v130 offset:50176
	ds_read_b128 v[212:215], v130 offset:51200
	ds_read_b128 v[216:219], v130 offset:52224
	ds_read_b128 v[172:175], v141 offset:32768
	ds_read_b128 v[176:179], v141 offset:33792
	ds_read_b128 v[180:183], v141 offset:34816
	ds_read_b128 v[184:187], v141 offset:35840
	ds_read_b128 v[188:191], v141 offset:36864
	ds_read_b128 v[192:195], v141 offset:37888
	ds_read_b128 v[196:199], v141 offset:38912
	ds_read_b128 v[200:203], v141 offset:39936
	s_mov_b32 m0, s68
	s_nop 0
	global_load_lds_dwordx4 v228, s[98:99]
	s_mov_b32 m0, s69
	s_nop 0
	global_load_lds_dwordx4 v229, s[98:99]
	s_waitcnt vmcnt(8)
	s_waitcnt lgkmcnt(0)
	s_setprio 1
	s_barrier
	v_mfma_f32_16x16x32_bf16 v[126:129], v[156:159], v[172:175], v[126:129]
	v_mfma_f32_16x16x32_bf16 v[122:125], v[164:167], v[172:175], v[122:125]
	v_mfma_f32_16x16x32_bf16 v[114:117], v[164:167], v[180:183], v[114:117]
	v_mfma_f32_16x16x32_bf16 v[118:121], v[156:159], v[180:183], v[118:121]
	v_mfma_f32_16x16x32_bf16 v[110:113], v[156:159], v[188:191], v[110:113]
	v_mfma_f32_16x16x32_bf16 v[106:109], v[164:167], v[188:191], v[106:109]
	v_mfma_f32_16x16x32_bf16 v[98:101], v[164:167], v[196:199], v[98:101]
	v_mfma_f32_16x16x32_bf16 v[102:105], v[156:159], v[196:199], v[102:105]
	v_mfma_f32_16x16x32_bf16 v[126:129], v[160:163], v[176:179], v[126:129]
	v_mfma_f32_16x16x32_bf16 v[122:125], v[168:171], v[176:179], v[122:125]
	v_mfma_f32_16x16x32_bf16 v[114:117], v[168:171], v[184:187], v[114:117]
	v_mfma_f32_16x16x32_bf16 v[118:121], v[160:163], v[184:187], v[118:121]
	v_mfma_f32_16x16x32_bf16 v[110:113], v[160:163], v[192:195], v[110:113]
	v_mfma_f32_16x16x32_bf16 v[106:109], v[168:171], v[192:195], v[106:109]
	v_mfma_f32_16x16x32_bf16 v[98:101], v[168:171], v[200:203], v[98:101]
	v_mfma_f32_16x16x32_bf16 v[102:105], v[160:163], v[200:203], v[102:105]
	v_mfma_f32_16x16x32_bf16 v[86:89], v[204:207], v[172:175], v[86:89]
	v_mfma_f32_16x16x32_bf16 v[70:73], v[212:215], v[172:175], v[70:73]
	v_mfma_f32_16x16x32_bf16 v[50:53], v[212:215], v[180:183], v[50:53]
	v_mfma_f32_16x16x32_bf16 v[54:57], v[204:207], v[180:183], v[54:57]
	v_mfma_f32_16x16x32_bf16 v[46:49], v[204:207], v[188:191], v[46:49]
	v_mfma_f32_16x16x32_bf16 v[42:45], v[212:215], v[188:191], v[42:45]
	v_mfma_f32_16x16x32_bf16 v[34:37], v[212:215], v[196:199], v[34:37]
	v_mfma_f32_16x16x32_bf16 v[38:41], v[204:207], v[196:199], v[38:41]
	v_mfma_f32_16x16x32_bf16 v[86:89], v[208:211], v[176:179], v[86:89]
	v_mfma_f32_16x16x32_bf16 v[70:73], v[216:219], v[176:179], v[70:73]
	v_mfma_f32_16x16x32_bf16 v[50:53], v[216:219], v[184:187], v[50:53]
	v_mfma_f32_16x16x32_bf16 v[54:57], v[208:211], v[184:187], v[54:57]
	v_mfma_f32_16x16x32_bf16 v[46:49], v[208:211], v[192:195], v[46:49]
	v_mfma_f32_16x16x32_bf16 v[42:45], v[216:219], v[192:195], v[42:45]
	v_mfma_f32_16x16x32_bf16 v[34:37], v[216:219], v[200:203], v[34:37]
	v_mfma_f32_16x16x32_bf16 v[38:41], v[208:211], v[200:203], v[38:41]
	s_barrier
	s_setprio 0
	ds_read_b128 v[172:175], v141 offset:49152
	ds_read_b128 v[176:179], v141 offset:50176
	ds_read_b128 v[180:183], v141 offset:51200
	ds_read_b128 v[184:187], v141 offset:52224
	ds_read_b128 v[188:191], v141 offset:53248
	ds_read_b128 v[192:195], v141 offset:54272
	ds_read_b128 v[196:199], v141 offset:55296
	ds_read_b128 v[200:203], v141 offset:56320
	s_mov_b32 m0, s70
	s_nop 0
	global_load_lds_dwordx4 v232, s[100:101]
	s_mov_b32 m0, s71
	s_nop 0
	global_load_lds_dwordx4 v233, s[100:101]
	s_mov_b32 m0, s76
	s_nop 0
	global_load_lds_dwordx4 v234, s[98:99]
	s_mov_b32 m0, s77
	s_nop 0
	global_load_lds_dwordx4 v235, s[98:99]
	s_mov_b32 m0, s78
	s_nop 0
	global_load_lds_dwordx4 v236, s[100:101]
	s_mov_b32 m0, s79
	s_nop 0
	global_load_lds_dwordx4 v237, s[100:101]
	s_add_i32 s53, s53, 2
	s_add_u32 s58, s58, 0x100
	s_addc_u32 s59, s59, 0
	s_add_u32 s98, s98, 0x100
	s_addc_u32 s99, s99, 0
	s_add_u32 s100, s100, 0x100
	s_addc_u32 s101, s101, 0
	s_cmp_gt_u32 s53, 27
	s_waitcnt vmcnt(8)
	s_waitcnt lgkmcnt(0)
	s_setprio 1
	s_barrier
	v_mfma_f32_16x16x32_bf16 v[30:33], v[156:159], v[172:175], v[30:33]
	v_mfma_f32_16x16x32_bf16 v[26:29], v[164:167], v[172:175], v[26:29]
	v_mfma_f32_16x16x32_bf16 v[18:21], v[164:167], v[180:183], v[18:21]
	v_mfma_f32_16x16x32_bf16 v[22:25], v[156:159], v[180:183], v[22:25]
	v_mfma_f32_16x16x32_bf16 v[14:17], v[156:159], v[188:191], v[14:17]
	v_mfma_f32_16x16x32_bf16 v[10:13], v[164:167], v[188:191], v[10:13]
	v_mfma_f32_16x16x32_bf16 v[2:5], v[164:167], v[196:199], v[2:5]
	v_mfma_f32_16x16x32_bf16 v[6:9], v[156:159], v[196:199], v[6:9]
	v_mfma_f32_16x16x32_bf16 v[30:33], v[160:163], v[176:179], v[30:33]
	v_mfma_f32_16x16x32_bf16 v[26:29], v[168:171], v[176:179], v[26:29]
	v_mfma_f32_16x16x32_bf16 v[18:21], v[168:171], v[184:187], v[18:21]
	v_mfma_f32_16x16x32_bf16 v[22:25], v[160:163], v[184:187], v[22:25]
	v_mfma_f32_16x16x32_bf16 v[14:17], v[160:163], v[192:195], v[14:17]
	v_mfma_f32_16x16x32_bf16 v[10:13], v[168:171], v[192:195], v[10:13]
	v_mfma_f32_16x16x32_bf16 v[2:5], v[168:171], v[200:203], v[2:5]
	v_mfma_f32_16x16x32_bf16 v[6:9], v[160:163], v[200:203], v[6:9]
	v_mfma_f32_16x16x32_bf16 v[58:61], v[204:207], v[172:175], v[58:61]
	v_mfma_f32_16x16x32_bf16 v[62:65], v[212:215], v[172:175], v[62:65]
	v_mfma_f32_16x16x32_bf16 v[74:77], v[212:215], v[180:183], v[74:77]
	v_mfma_f32_16x16x32_bf16 v[66:69], v[204:207], v[180:183], v[66:69]
	v_mfma_f32_16x16x32_bf16 v[78:81], v[204:207], v[188:191], v[78:81]
	v_mfma_f32_16x16x32_bf16 v[82:85], v[212:215], v[188:191], v[82:85]
	v_mfma_f32_16x16x32_bf16 v[94:97], v[212:215], v[196:199], v[94:97]
	v_mfma_f32_16x16x32_bf16 v[90:93], v[204:207], v[196:199], v[90:93]
	v_mfma_f32_16x16x32_bf16 v[58:61], v[208:211], v[176:179], v[58:61]
	v_mfma_f32_16x16x32_bf16 v[62:65], v[216:219], v[176:179], v[62:65]
	v_mfma_f32_16x16x32_bf16 v[74:77], v[216:219], v[184:187], v[74:77]
	v_mfma_f32_16x16x32_bf16 v[66:69], v[208:211], v[184:187], v[66:69]
	v_mfma_f32_16x16x32_bf16 v[78:81], v[208:211], v[192:195], v[78:81]
	v_mfma_f32_16x16x32_bf16 v[82:85], v[216:219], v[192:195], v[82:85]
	v_mfma_f32_16x16x32_bf16 v[94:97], v[216:219], v[200:203], v[94:97]
	v_mfma_f32_16x16x32_bf16 v[90:93], v[208:211], v[200:203], v[90:93]
	s_barrier
; #define LDA(dst, b, h)                                                                                     \
;   _Pragma("unroll") for (int m = 0; m < 4; ++m) _Pragma("unroll") for (int k = 0; k < 2; ++k) dst[m][k] = \
;       *reinterpret_cast<const bf16x8*>(shmc + aL + (((b) * 2 + (h)) * 16384 + (m * 2 + k) * 1024))
; #define LDB(dst, b, h)                                                                                     \
;   _Pragma("unroll") for (int n = 0; n < 2; ++n) _Pragma("unroll") for (int k = 0; k < 2; ++k) dst[n][k] = \
;       *reinterpret_cast<const bf16x8*>(shmc + bL + (((b) * 2 + (h)) * 16384 + (n * 2 + k) * 1024))
; #define OPAQ asm volatile("" : "+v"(aL), "+v"(bL))
; #define WAIT_V(n) asm volatile("s_waitcnt vmcnt(" #n ")" ::: "memory")
; #define WAIT_L(n) asm volatile("s_waitcnt lgkmcnt(" #n ")" ::: "memory")
; #define BAR __builtin_amdgcn_s_barrier()
; template <int EPI>
; __device__ __forceinline__ void phase_gemm(const Params& p, const GemmDesc& d, char* shmc) {
;     ...
;     }
;     {
;       OPAQ;
;       LDB(B0, 0, 0); LDA(At, 0, 0); STAGE_A(SA(1, 1), 1, nt - 1);
;       BAR; WAIT_L(0); MMA(0, 0, At, B0); BAR;
;       LDB(B1, 0, 1); BAR; WAIT_L(0); MMA(0, 1, At, B1); BAR;
;       LDA(At, 0, 1); WAIT_V(4); BAR; WAIT_L(0); MMA(1, 0, At, B0); MMA(1, 1, At, B1); BAR;
	s_cbranch_scc0 .LBB0_1010
	s_setprio 0
	s_add_u32 s56, s56, 0x80f80
	s_addc_u32 s57, s57, 0
	v_add_u32_e32 v130, 0, v153
	v_add_u32_e32 v141, 0, v152
	s_mov_b32 m0, s80
	ds_read_b128 v[144:147], v130
	ds_read_b128 v[148:151], v130 offset:1024
	ds_read_b128 v[156:159], v130 offset:2048
	ds_read_b128 v[160:163], v130 offset:3072
	ds_read_b128 v[164:167], v141
	ds_read_b128 v[168:171], v141 offset:1024
	ds_read_b128 v[172:175], v141 offset:2048
	ds_read_b128 v[176:179], v141 offset:3072
	ds_read_b128 v[180:183], v141 offset:4096
	ds_read_b128 v[184:187], v141 offset:5120
	ds_read_b128 v[188:191], v141 offset:6144
	ds_read_b128 v[192:195], v141 offset:7168
	global_load_lds_dwordx4 v140, s[56:57]
	s_mov_b32 m0, s81
	s_nop 0
	global_load_lds_dwordx4 v142, s[56:57]
	s_waitcnt vmcnt(8)
	s_barrier
	s_waitcnt lgkmcnt(0)
	s_setprio 1
	s_waitcnt lgkmcnt(0)
	v_mfma_f32_16x16x32_bf16 v[126:129], v[144:147], v[164:167], v[126:129]
	v_mfma_f32_16x16x32_bf16 v[122:125], v[156:159], v[164:167], v[122:125]
	v_mfma_f32_16x16x32_bf16 v[114:117], v[156:159], v[172:175], v[114:117]
	v_mfma_f32_16x16x32_bf16 v[110:113], v[144:147], v[180:183], v[110:113]
	v_mfma_f32_16x16x32_bf16 v[102:105], v[144:147], v[188:191], v[102:105]
	v_mfma_f32_16x16x32_bf16 v[126:129], v[148:151], v[168:171], v[126:129]
	v_mfma_f32_16x16x32_bf16 v[122:125], v[160:163], v[168:171], v[122:125]
	v_mfma_f32_16x16x32_bf16 v[118:121], v[144:147], v[172:175], v[118:121]
	v_mfma_f32_16x16x32_bf16 v[114:117], v[160:163], v[176:179], v[114:117]
	v_mfma_f32_16x16x32_bf16 v[110:113], v[148:151], v[184:187], v[110:113]
	v_mfma_f32_16x16x32_bf16 v[106:109], v[156:159], v[180:183], v[106:109]
	v_mfma_f32_16x16x32_bf16 v[102:105], v[148:151], v[192:195], v[102:105]
	v_mfma_f32_16x16x32_bf16 v[98:101], v[156:159], v[188:191], v[98:101]
	v_mfma_f32_16x16x32_bf16 v[196:199], v[148:151], v[176:179], v[118:121]
	v_mfma_f32_16x16x32_bf16 v[200:203], v[160:163], v[184:187], v[106:109]
	v_mfma_f32_16x16x32_bf16 v[204:207], v[160:163], v[192:195], v[98:101]
	s_setprio 0
	s_barrier
	s_nop 2
	ds_read_b128 v[98:101], v130 offset:16384
	ds_read_b128 v[106:109], v130 offset:17408
	ds_read_b128 v[118:121], v130 offset:18432
	ds_read_b128 v[208:211], v130 offset:19456
	s_barrier
	s_waitcnt lgkmcnt(0)
	s_setprio 1
	s_waitcnt lgkmcnt(0)
	v_mfma_f32_16x16x32_bf16 v[86:89], v[98:101], v[164:167], v[86:89]
	v_mfma_f32_16x16x32_bf16 v[70:73], v[118:121], v[164:167], v[70:73]
	v_mfma_f32_16x16x32_bf16 v[54:57], v[98:101], v[172:175], v[54:57]
	v_mfma_f32_16x16x32_bf16 v[50:53], v[118:121], v[172:175], v[50:53]
	v_mfma_f32_16x16x32_bf16 v[46:49], v[98:101], v[180:183], v[46:49]
	v_mfma_f32_16x16x32_bf16 v[42:45], v[118:121], v[180:183], v[42:45]
	v_mfma_f32_16x16x32_bf16 v[38:41], v[98:101], v[188:191], v[38:41]
	v_mfma_f32_16x16x32_bf16 v[34:37], v[118:121], v[188:191], v[34:37]
	v_mfma_f32_16x16x32_bf16 v[86:89], v[106:109], v[168:171], v[86:89]
	v_mfma_f32_16x16x32_bf16 v[70:73], v[208:211], v[168:171], v[70:73]
	v_mfma_f32_16x16x32_bf16 v[54:57], v[106:109], v[176:179], v[54:57]
	v_mfma_f32_16x16x32_bf16 v[50:53], v[208:211], v[176:179], v[50:53]
	v_mfma_f32_16x16x32_bf16 v[46:49], v[106:109], v[184:187], v[46:49]
	v_mfma_f32_16x16x32_bf16 v[42:45], v[208:211], v[184:187], v[42:45]
	v_mfma_f32_16x16x32_bf16 v[38:41], v[106:109], v[192:195], v[38:41]
	v_mfma_f32_16x16x32_bf16 v[34:37], v[208:211], v[192:195], v[34:37]
	s_setprio 0
	s_barrier
	ds_read_b128 v[164:167], v141 offset:16384
	ds_read_b128 v[168:171], v141 offset:17408
	ds_read_b128 v[172:175], v141 offset:18432
	ds_read_b128 v[176:179], v141 offset:19456
	ds_read_b128 v[180:183], v141 offset:20480
	ds_read_b128 v[184:187], v141 offset:21504
	ds_read_b128 v[188:191], v141 offset:22528
	ds_read_b128 v[192:195], v141 offset:23552
	s_waitcnt vmcnt(4)
	s_barrier
	s_waitcnt lgkmcnt(0)
	s_setprio 1
	s_waitcnt lgkmcnt(0)
	v_mfma_f32_16x16x32_bf16 v[30:33], v[144:147], v[164:167], v[30:33]
	v_mfma_f32_16x16x32_bf16 v[26:29], v[156:159], v[164:167], v[26:29]
	v_mfma_f32_16x16x32_bf16 v[22:25], v[144:147], v[172:175], v[22:25]
	v_mfma_f32_16x16x32_bf16 v[18:21], v[156:159], v[172:175], v[18:21]
	v_mfma_f32_16x16x32_bf16 v[14:17], v[144:147], v[180:183], v[14:17]
	v_mfma_f32_16x16x32_bf16 v[10:13], v[156:159], v[180:183], v[10:13]
	v_mfma_f32_16x16x32_bf16 v[6:9], v[144:147], v[188:191], v[6:9]
	v_mfma_f32_16x16x32_bf16 v[2:5], v[156:159], v[188:191], v[2:5]
	v_mfma_f32_16x16x32_bf16 v[30:33], v[148:151], v[168:171], v[30:33]
	v_mfma_f32_16x16x32_bf16 v[26:29], v[160:163], v[168:171], v[26:29]
	v_mfma_f32_16x16x32_bf16 v[22:25], v[148:151], v[176:179], v[22:25]
	v_mfma_f32_16x16x32_bf16 v[18:21], v[160:163], v[176:179], v[18:21]
	v_mfma_f32_16x16x32_bf16 v[14:17], v[148:151], v[184:187], v[14:17]
	v_mfma_f32_16x16x32_bf16 v[10:13], v[160:163], v[184:187], v[10:13]
	v_mfma_f32_16x16x32_bf16 v[6:9], v[148:151], v[192:195], v[6:9]
	v_mfma_f32_16x16x32_bf16 v[2:5], v[160:163], v[192:195], v[2:5]
	s_setprio 0
	s_setprio 1
	v_mfma_f32_16x16x32_bf16 v[62:65], v[118:121], v[164:167], v[62:65]
	v_mfma_f32_16x16x32_bf16 v[144:147], v[208:211], v[168:171], v[62:65]
	v_mfma_f32_16x16x32_bf16 v[62:65], v[98:101], v[172:175], v[66:69]
	v_mfma_f32_16x16x32_bf16 v[148:151], v[106:109], v[176:179], v[62:65]
	v_mfma_f32_16x16x32_bf16 v[62:65], v[118:121], v[172:175], v[74:77]
	v_mfma_f32_16x16x32_bf16 v[156:159], v[208:211], v[176:179], v[62:65]
	v_mfma_f32_16x16x32_bf16 v[62:65], v[98:101], v[180:183], v[78:81]
	v_mfma_f32_16x16x32_bf16 v[160:163], v[106:109], v[184:187], v[62:65]
	v_mfma_f32_16x16x32_bf16 v[62:65], v[118:121], v[180:183], v[82:85]
	v_mfma_f32_16x16x32_bf16 v[58:61], v[98:101], v[164:167], v[58:61]
	v_mfma_f32_16x16x32_bf16 v[164:167], v[208:211], v[184:187], v[62:65]
	v_mfma_f32_16x16x32_bf16 v[62:65], v[98:101], v[188:191], v[90:93]
	v_mfma_f32_16x16x32_bf16 v[58:61], v[106:109], v[168:171], v[58:61]
	v_mfma_f32_16x16x32_bf16 v[168:171], v[106:109], v[192:195], v[62:65]
	v_mfma_f32_16x16x32_bf16 v[62:65], v[118:121], v[188:191], v[94:97]
	v_mfma_f32_16x16x32_bf16 v[172:175], v[208:211], v[192:195], v[62:65]
	s_setprio 0
	s_barrier
; #define LDA(dst, b, h)                                                                                     \
;   _Pragma("unroll") for (int m = 0; m < 4; ++m) _Pragma("unroll") for (int k = 0; k < 2; ++k) dst[m][k] = \
;       *reinterpret_cast<const bf16x8*>(shmc + aL + (((b) * 2 + (h)) * 16384 + (m * 2 + k) * 1024))
; #define LDB(dst, b, h)                                                                                     \
;   _Pragma("unroll") for (int n = 0; n < 2; ++n) _Pragma("unroll") for (int k = 0; k < 2; ++k) dst[n][k] = \
;       *reinterpret_cast<const bf16x8*>(shmc + bL + (((b) * 2 + (h)) * 16384 + (n * 2 + k) * 1024))
; #define WAIT_V(n) asm volatile("s_waitcnt vmcnt(" #n ")" ::: "memory")
; #define WAIT_L(n) asm volatile("s_waitcnt lgkmcnt(" #n ")" ::: "memory")
; #define BAR __builtin_amdgcn_s_barrier()
; template <int EPI>
; __device__ __forceinline__ void phase_gemm(const Params& p, const GemmDesc& d, char* shmc) {
;     ...
;     {
;       LDB(B0, 1, 0); LDA(At, 1, 0); WAIT_V(2); BAR; WAIT_L(0); MMA(0, 0, At, B0); BAR;
;       LDB(B1, 1, 1); WAIT_V(0); BAR; WAIT_L(0); MMA(0, 1, At, B1); BAR;
;       LDA(At, 1, 1); BAR; WAIT_L(0); MMA(1, 0, At, B0); MMA(1, 1, At, B1); BAR;
;     }
;     if (wr == 0) BAR;
	ds_read_b128 v[176:179], v130 offset:32768
	ds_read_b128 v[180:183], v130 offset:33792
	ds_read_b128 v[184:187], v130 offset:34816
	ds_read_b128 v[188:191], v130 offset:35840
	s_nop 0
	ds_read_b128 v[62:65], v141 offset:32768
	ds_read_b128 v[78:81], v141 offset:33792
	ds_read_b128 v[94:97], v141 offset:34816
	ds_read_b128 v[192:195], v141 offset:35840
	ds_read_b128 v[208:211], v141 offset:36864
	ds_read_b128 v[212:215], v141 offset:37888
	ds_read_b128 v[216:219], v141 offset:38912
	ds_read_b128 v[220:223], v141 offset:39936
	s_waitcnt vmcnt(2)
	s_barrier
	s_waitcnt lgkmcnt(0)
	s_setprio 1
	s_waitcnt lgkmcnt(0)
	v_mfma_f32_16x16x32_bf16 v[66:69], v[176:179], v[62:65], v[126:129]
	v_mfma_f32_16x16x32_bf16 v[126:129], v[180:183], v[78:81], v[66:69]
	v_mfma_f32_16x16x32_bf16 v[66:69], v[184:187], v[62:65], v[122:125]
	v_mfma_f32_16x16x32_bf16 v[118:121], v[188:191], v[78:81], v[66:69]
	v_mfma_f32_16x16x32_bf16 v[66:69], v[176:179], v[94:97], v[196:199]
	v_mfma_f32_16x16x32_bf16 v[106:109], v[180:183], v[192:195], v[66:69]
	v_mfma_f32_16x16x32_bf16 v[66:69], v[184:187], v[94:97], v[114:117]
	v_mfma_f32_16x16x32_bf16 v[98:101], v[188:191], v[192:195], v[66:69]
	v_mfma_f32_16x16x32_bf16 v[66:69], v[176:179], v[208:211], v[110:113]
	v_mfma_f32_16x16x32_bf16 v[90:93], v[180:183], v[212:215], v[66:69]
	v_mfma_f32_16x16x32_bf16 v[66:69], v[184:187], v[208:211], v[200:203]
	v_mfma_f32_16x16x32_bf16 v[82:85], v[188:191], v[212:215], v[66:69]
	v_mfma_f32_16x16x32_bf16 v[66:69], v[176:179], v[216:219], v[102:105]
	v_mfma_f32_16x16x32_bf16 v[74:77], v[180:183], v[220:223], v[66:69]
	v_mfma_f32_16x16x32_bf16 v[66:69], v[184:187], v[216:219], v[204:207]
	v_mfma_f32_16x16x32_bf16 v[66:69], v[188:191], v[220:223], v[66:69]
	s_setprio 0
	s_barrier
	ds_read_b128 v[196:199], v130 offset:49152
	ds_read_b128 v[200:203], v130 offset:50176
	ds_read_b128 v[204:207], v130 offset:51200
	ds_read_b128 v[224:227], v130 offset:52224
	s_waitcnt vmcnt(0)
	s_barrier
	s_waitcnt lgkmcnt(0)
	s_setprio 1
	s_waitcnt lgkmcnt(0)
	v_mfma_f32_16x16x32_bf16 v[86:89], v[196:199], v[62:65], v[86:89]
	v_mfma_f32_16x16x32_bf16 v[62:65], v[204:207], v[62:65], v[70:73]
	v_mfma_f32_16x16x32_bf16 v[54:57], v[196:199], v[94:97], v[54:57]
	v_mfma_f32_16x16x32_bf16 v[50:53], v[204:207], v[94:97], v[50:53]
	v_mfma_f32_16x16x32_bf16 v[46:49], v[196:199], v[208:211], v[46:49]
	v_mfma_f32_16x16x32_bf16 v[42:45], v[204:207], v[208:211], v[42:45]
	v_mfma_f32_16x16x32_bf16 v[38:41], v[196:199], v[216:219], v[38:41]
	v_mfma_f32_16x16x32_bf16 v[34:37], v[204:207], v[216:219], v[34:37]
	v_mfma_f32_16x16x32_bf16 v[122:125], v[200:203], v[78:81], v[86:89]
	v_mfma_f32_16x16x32_bf16 v[114:117], v[224:227], v[78:81], v[62:65]
	v_mfma_f32_16x16x32_bf16 v[110:113], v[200:203], v[192:195], v[54:57]
	v_mfma_f32_16x16x32_bf16 v[102:105], v[224:227], v[192:195], v[50:53]
	v_mfma_f32_16x16x32_bf16 v[94:97], v[200:203], v[212:215], v[46:49]
	v_mfma_f32_16x16x32_bf16 v[86:89], v[224:227], v[212:215], v[42:45]
	v_mfma_f32_16x16x32_bf16 v[78:81], v[200:203], v[220:223], v[38:41]
	v_mfma_f32_16x16x32_bf16 v[70:73], v[224:227], v[220:223], v[34:37]
	s_setprio 0
	s_barrier
	s_nop 0
	ds_read_b128 v[34:37], v141 offset:49152
	ds_read_b128 v[42:45], v141 offset:50176
	ds_read_b128 v[192:195], v141 offset:51200
	ds_read_b128 v[208:211], v141 offset:52224
	ds_read_b128 v[212:215], v141 offset:53248
	ds_read_b128 v[216:219], v141 offset:54272
	ds_read_b128 v[220:223], v141 offset:55296
	ds_read_b128 v[228:231], v141 offset:56320
	s_barrier
	s_waitcnt lgkmcnt(0)
	s_setprio 1
	s_waitcnt lgkmcnt(0)
	v_mfma_f32_16x16x32_bf16 v[30:33], v[176:179], v[34:37], v[30:33]
	v_mfma_f32_16x16x32_bf16 v[26:29], v[184:187], v[34:37], v[26:29]
	v_mfma_f32_16x16x32_bf16 v[22:25], v[176:179], v[192:195], v[22:25]
	v_mfma_f32_16x16x32_bf16 v[18:21], v[184:187], v[192:195], v[18:21]
	v_mfma_f32_16x16x32_bf16 v[14:17], v[176:179], v[212:215], v[14:17]
	v_mfma_f32_16x16x32_bf16 v[10:13], v[184:187], v[212:215], v[10:13]
	v_mfma_f32_16x16x32_bf16 v[6:9], v[176:179], v[220:223], v[6:9]
	v_mfma_f32_16x16x32_bf16 v[2:5], v[184:187], v[220:223], v[2:5]
	v_mfma_f32_16x16x32_bf16 v[62:65], v[180:183], v[42:45], v[30:33]
	v_mfma_f32_16x16x32_bf16 v[54:57], v[188:191], v[42:45], v[26:29]
	v_mfma_f32_16x16x32_bf16 v[46:49], v[180:183], v[208:211], v[22:25]
	v_mfma_f32_16x16x32_bf16 v[38:41], v[188:191], v[208:211], v[18:21]
	v_mfma_f32_16x16x32_bf16 v[30:33], v[180:183], v[216:219], v[14:17]
	v_mfma_f32_16x16x32_bf16 v[22:25], v[188:191], v[216:219], v[10:13]
	v_mfma_f32_16x16x32_bf16 v[14:17], v[180:183], v[228:231], v[6:9]
	v_mfma_f32_16x16x32_bf16 v[6:9], v[188:191], v[228:231], v[2:5]
	s_setprio 0
	s_setprio 1
	v_mfma_f32_16x16x32_bf16 v[2:5], v[196:199], v[34:37], v[58:61]
	v_mfma_f32_16x16x32_bf16 v[58:61], v[200:203], v[42:45], v[2:5]
	v_mfma_f32_16x16x32_bf16 v[2:5], v[204:207], v[34:37], v[144:147]
	v_mfma_f32_16x16x32_bf16 v[50:53], v[224:227], v[42:45], v[2:5]
	v_mfma_f32_16x16x32_bf16 v[2:5], v[196:199], v[192:195], v[148:151]
	v_mfma_f32_16x16x32_bf16 v[42:45], v[200:203], v[208:211], v[2:5]
	v_mfma_f32_16x16x32_bf16 v[2:5], v[204:207], v[192:195], v[156:159]
	v_mfma_f32_16x16x32_bf16 v[34:37], v[224:227], v[208:211], v[2:5]
	v_mfma_f32_16x16x32_bf16 v[2:5], v[196:199], v[212:215], v[160:163]
	v_mfma_f32_16x16x32_bf16 v[26:29], v[200:203], v[216:219], v[2:5]
	v_mfma_f32_16x16x32_bf16 v[2:5], v[204:207], v[212:215], v[164:167]
	v_mfma_f32_16x16x32_bf16 v[18:21], v[224:227], v[216:219], v[2:5]
	v_mfma_f32_16x16x32_bf16 v[2:5], v[196:199], v[220:223], v[168:171]
	v_mfma_f32_16x16x32_bf16 v[10:13], v[200:203], v[228:231], v[2:5]
	v_mfma_f32_16x16x32_bf16 v[2:5], v[204:207], v[220:223], v[172:175]
	v_mfma_f32_16x16x32_bf16 v[2:5], v[224:227], v[228:231], v[2:5]
	s_setprio 0
	s_barrier
	s_and_saveexec_b64 s[56:57], s[4:5]
	s_cbranch_execz .LBB0_1013
	s_barrier

; #define LDA(dst, b, h)                                                                                     \
;   _Pragma("unroll") for (int m = 0; m < 4; ++m) _Pragma("unroll") for (int k = 0; k < 2; ++k) dst[m][k] = \
;       *reinterpret_cast<const bf16x8*>(shmc + aL + (((b) * 2 + (h)) * 16384 + (m * 2 + k) * 1024))
; #define LDB(dst, b, h)                                                                                     \
;   _Pragma("unroll") for (int n = 0; n < 2; ++n) _Pragma("unroll") for (int k = 0; k < 2; ++k) dst[n][k] = \
;       *reinterpret_cast<const bf16x8*>(shmc + bL + (((b) * 2 + (h)) * 16384 + (n * 2 + k) * 1024))
; #define OPAQ asm volatile("" : "+v"(aL), "+v"(bL))
; #define WAIT_V(n) asm volatile("s_waitcnt vmcnt(" #n ")" ::: "memory")
; #define WAIT_L(n) asm volatile("s_waitcnt lgkmcnt(" #n ")" ::: "memory")
; #define BAR __builtin_amdgcn_s_barrier()
; #define SCHED __builtin_amdgcn_sched_barrier(0)
; template <int EPI>
; __device__ __forceinline__ void phase_gemm(const Params& p, const GemmDesc& d, char* shmc) {
;     ...
;     for (int t = 0; t < nt - 2; t += 2) {
;       OPAQ;
;       LDB(B0, 0, 0); SCHED; LDA(At, 0, 0); STAGE_A(SA(1, 1), 1, t + 1);
;       WAIT_L(8); BAR; WAIT_L(0); MMA(0, 0, At, B0); BAR; SCHED;
;       LDB(B1, 0, 1); STAGE_B(SB(0, 0), 0, t + 2);
;       BAR; WAIT_L(0); MMA(0, 1, At, B1); BAR;
;       LDA(At, 0, 1); STAGE_A(SA(0, 0), 0, t + 2);
;       BAR; WAIT_L(0); MMA(1, 0, At, B0); BAR; SCHED;
;       STAGE_B(SB(0, 1), 1, t + 2);
;       WAIT_V(6); BAR; MMA(1, 1, At, B1); BAR;
.LBB0_1153:
	s_nop 0
	v_add_u32_e32 v162, 0, v205
	v_add_u32_e32 v175, 0, v204
	s_setprio 0
	ds_read_b128 v[138:141], v162
	ds_read_b128 v[142:145], v162 offset:1024
	ds_read_b128 v[146:149], v162 offset:2048
	ds_read_b128 v[150:153], v162 offset:3072
	ds_read_b128 v[208:211], v162 offset:16384
	ds_read_b128 v[212:215], v162 offset:17408
	ds_read_b128 v[216:219], v162 offset:18432
	ds_read_b128 v[220:223], v162 offset:19456
	ds_read_b128 v[154:157], v175
	ds_read_b128 v[158:161], v175 offset:1024
	ds_read_b128 v[178:181], v175 offset:2048
	ds_read_b128 v[182:185], v175 offset:3072
	ds_read_b128 v[186:189], v175 offset:4096
	ds_read_b128 v[190:193], v175 offset:5120
	ds_read_b128 v[194:197], v175 offset:6144
	ds_read_b128 v[198:201], v175 offset:7168
	s_add_i32 s59, s64, 0xc000
	s_mov_b32 m0, s59
	s_nop 0
	global_load_lds_dwordx4 v202, s[98:99]
	s_add_i32 s68, s64, 0xe000
	s_mov_b32 m0, s68
	s_nop 0
	global_load_lds_dwordx4 v203, s[98:99]
	s_waitcnt vmcnt(8)
	s_waitcnt lgkmcnt(0)
	s_setprio 1
	s_barrier
	v_mfma_f32_16x16x32_bf16 v[2:5], v[154:157], v[138:141], v[2:5]
	v_mfma_f32_16x16x32_bf16 v[6:9], v[154:157], v[146:149], v[6:9]
	v_mfma_f32_16x16x32_bf16 v[18:21], v[178:181], v[146:149], v[18:21]
	v_mfma_f32_16x16x32_bf16 v[10:13], v[178:181], v[138:141], v[10:13]
	v_mfma_f32_16x16x32_bf16 v[30:33], v[186:189], v[138:141], v[30:33]
	v_mfma_f32_16x16x32_bf16 v[42:45], v[186:189], v[146:149], v[42:45]
	v_mfma_f32_16x16x32_bf16 v[66:69], v[194:197], v[146:149], v[66:69]
	v_mfma_f32_16x16x32_bf16 v[54:57], v[194:197], v[138:141], v[54:57]
	v_mfma_f32_16x16x32_bf16 v[2:5], v[158:161], v[142:145], v[2:5]
	v_mfma_f32_16x16x32_bf16 v[6:9], v[158:161], v[150:153], v[6:9]
	v_mfma_f32_16x16x32_bf16 v[18:21], v[182:185], v[150:153], v[18:21]
	v_mfma_f32_16x16x32_bf16 v[10:13], v[182:185], v[142:145], v[10:13]
	v_mfma_f32_16x16x32_bf16 v[30:33], v[190:193], v[142:145], v[30:33]
	v_mfma_f32_16x16x32_bf16 v[42:45], v[190:193], v[150:153], v[42:45]
	v_mfma_f32_16x16x32_bf16 v[66:69], v[198:201], v[150:153], v[66:69]
	v_mfma_f32_16x16x32_bf16 v[54:57], v[198:201], v[142:145], v[54:57]
	v_mfma_f32_16x16x32_bf16 v[14:17], v[154:157], v[208:211], v[14:17]
	v_mfma_f32_16x16x32_bf16 v[22:25], v[154:157], v[216:219], v[22:25]
	v_mfma_f32_16x16x32_bf16 v[46:49], v[178:181], v[216:219], v[46:49]
	v_mfma_f32_16x16x32_bf16 v[34:37], v[178:181], v[208:211], v[34:37]
	v_mfma_f32_16x16x32_bf16 v[58:61], v[186:189], v[208:211], v[58:61]
	v_mfma_f32_16x16x32_bf16 v[70:73], v[186:189], v[216:219], v[70:73]
	v_mfma_f32_16x16x32_bf16 v[86:89], v[194:197], v[216:219], v[86:89]
	v_mfma_f32_16x16x32_bf16 v[78:81], v[194:197], v[208:211], v[78:81]
	v_mfma_f32_16x16x32_bf16 v[14:17], v[158:161], v[212:215], v[14:17]
	v_mfma_f32_16x16x32_bf16 v[22:25], v[158:161], v[220:223], v[22:25]
	v_mfma_f32_16x16x32_bf16 v[46:49], v[182:185], v[220:223], v[46:49]
	v_mfma_f32_16x16x32_bf16 v[34:37], v[182:185], v[212:215], v[34:37]
	v_mfma_f32_16x16x32_bf16 v[58:61], v[190:193], v[212:215], v[58:61]
	v_mfma_f32_16x16x32_bf16 v[70:73], v[190:193], v[220:223], v[70:73]
	v_mfma_f32_16x16x32_bf16 v[86:89], v[198:201], v[220:223], v[86:89]
	v_mfma_f32_16x16x32_bf16 v[78:81], v[198:201], v[212:215], v[78:81]
	s_barrier
	s_setprio 0
	ds_read_b128 v[154:157], v175 offset:16384
	ds_read_b128 v[158:161], v175 offset:17408
	ds_read_b128 v[178:181], v175 offset:18432
	ds_read_b128 v[182:185], v175 offset:19456
	ds_read_b128 v[186:189], v175 offset:20480
	ds_read_b128 v[190:193], v175 offset:21504
	ds_read_b128 v[194:197], v175 offset:22528
	ds_read_b128 v[198:201], v175 offset:23552
	s_mov_b32 m0, s65
	s_nop 0
	global_load_lds_dwordx4 v224, s[100:101]
	s_mov_b32 m0, s66
	s_nop 0
	global_load_lds_dwordx4 v225, s[100:101]
	s_mov_b32 m0, s64
	s_nop 0
	global_load_lds_dwordx4 v226, s[98:99]
	s_mov_b32 m0, s67
	s_nop 0
	global_load_lds_dwordx4 v227, s[98:99]
	s_mov_b32 m0, s71
	s_nop 0
	global_load_lds_dwordx4 v228, s[100:101]
	s_mov_b32 m0, s76
	s_nop 0
	global_load_lds_dwordx4 v229, s[100:101]
	s_waitcnt vmcnt(8)
	s_waitcnt lgkmcnt(0)
	s_setprio 1
	s_barrier
	v_mfma_f32_16x16x32_bf16 v[26:29], v[154:157], v[138:141], v[26:29]
	v_mfma_f32_16x16x32_bf16 v[38:41], v[154:157], v[146:149], v[38:41]
	v_mfma_f32_16x16x32_bf16 v[62:65], v[178:181], v[146:149], v[62:65]
	v_mfma_f32_16x16x32_bf16 v[50:53], v[178:181], v[138:141], v[50:53]
	v_mfma_f32_16x16x32_bf16 v[74:77], v[186:189], v[138:141], v[74:77]
	v_mfma_f32_16x16x32_bf16 v[82:85], v[186:189], v[146:149], v[82:85]
	v_mfma_f32_16x16x32_bf16 v[94:97], v[194:197], v[146:149], v[94:97]
	v_mfma_f32_16x16x32_bf16 v[90:93], v[194:197], v[138:141], v[90:93]
	v_mfma_f32_16x16x32_bf16 v[26:29], v[158:161], v[142:145], v[26:29]
	v_mfma_f32_16x16x32_bf16 v[38:41], v[158:161], v[150:153], v[38:41]
	v_mfma_f32_16x16x32_bf16 v[62:65], v[182:185], v[150:153], v[62:65]
	v_mfma_f32_16x16x32_bf16 v[50:53], v[182:185], v[142:145], v[50:53]
	v_mfma_f32_16x16x32_bf16 v[74:77], v[190:193], v[142:145], v[74:77]
	v_mfma_f32_16x16x32_bf16 v[82:85], v[190:193], v[150:153], v[82:85]
	v_mfma_f32_16x16x32_bf16 v[94:97], v[198:201], v[150:153], v[94:97]
	v_mfma_f32_16x16x32_bf16 v[90:93], v[198:201], v[142:145], v[90:93]
	v_mfma_f32_16x16x32_bf16 v[98:101], v[154:157], v[208:211], v[98:101]
	v_mfma_f32_16x16x32_bf16 v[102:105], v[154:157], v[216:219], v[102:105]
	v_mfma_f32_16x16x32_bf16 v[110:113], v[178:181], v[216:219], v[110:113]
	v_mfma_f32_16x16x32_bf16 v[106:109], v[178:181], v[208:211], v[106:109]
	v_mfma_f32_16x16x32_bf16 v[114:117], v[186:189], v[208:211], v[114:117]
	v_mfma_f32_16x16x32_bf16 v[118:121], v[186:189], v[216:219], v[118:121]
	v_mfma_f32_16x16x32_bf16 v[126:129], v[194:197], v[216:219], v[126:129]
	v_mfma_f32_16x16x32_bf16 v[122:125], v[194:197], v[208:211], v[122:125]
	v_mfma_f32_16x16x32_bf16 v[98:101], v[158:161], v[212:215], v[98:101]
	v_mfma_f32_16x16x32_bf16 v[102:105], v[158:161], v[220:223], v[102:105]
	v_mfma_f32_16x16x32_bf16 v[110:113], v[182:185], v[220:223], v[110:113]
	v_mfma_f32_16x16x32_bf16 v[106:109], v[182:185], v[212:215], v[106:109]
	v_mfma_f32_16x16x32_bf16 v[114:117], v[190:193], v[212:215], v[114:117]
	v_mfma_f32_16x16x32_bf16 v[118:121], v[190:193], v[220:223], v[118:121]
	v_mfma_f32_16x16x32_bf16 v[126:129], v[198:201], v[220:223], v[126:129]
	v_mfma_f32_16x16x32_bf16 v[122:125], v[198:201], v[212:215], v[122:125]
	s_barrier
; #define LDA(dst, b, h)                                                                                     \
;   _Pragma("unroll") for (int m = 0; m < 4; ++m) _Pragma("unroll") for (int k = 0; k < 2; ++k) dst[m][k] = \
;       *reinterpret_cast<const bf16x8*>(shmc + aL + (((b) * 2 + (h)) * 16384 + (m * 2 + k) * 1024))
; #define LDB(dst, b, h)                                                                                     \
;   _Pragma("unroll") for (int n = 0; n < 2; ++n) _Pragma("unroll") for (int k = 0; k < 2; ++k) dst[n][k] = \
;       *reinterpret_cast<const bf16x8*>(shmc + bL + (((b) * 2 + (h)) * 16384 + (n * 2 + k) * 1024))
; #define WAIT_V(n) asm volatile("s_waitcnt vmcnt(" #n ")" ::: "memory")
; #define WAIT_L(n) asm volatile("s_waitcnt lgkmcnt(" #n ")" ::: "memory")
; #define BAR __builtin_amdgcn_s_barrier()
; #define SCHED __builtin_amdgcn_sched_barrier(0)
; template <int EPI>
; __device__ __forceinline__ void phase_gemm(const Params& p, const GemmDesc& d, char* shmc) {
;     ...
;       LDB(B0, 1, 0); SCHED; LDA(At, 1, 0); STAGE_A(SA(0, 1), 1, t + 2);
;       WAIT_L(8); BAR; WAIT_L(0); MMA(0, 0, At, B0); BAR; SCHED;
;       LDB(B1, 1, 1); STAGE_B(SB(1, 0), 0, t + 3);
;       BAR; WAIT_L(0); MMA(0, 1, At, B1); BAR;
;       LDA(At, 1, 1); STAGE_A(SA(1, 0), 0, t + 3);
;       BAR; WAIT_L(0); MMA(1, 0, At, B0); BAR; SCHED;
;       STAGE_B(SB(1, 1), 1, t + 3);
;       WAIT_V(6); BAR; MMA(1, 1, At, B1); BAR;
;     }
	s_setprio 0
	ds_read_b128 v[138:141], v162 offset:32768
	ds_read_b128 v[142:145], v162 offset:33792
	ds_read_b128 v[146:149], v162 offset:34816
	ds_read_b128 v[150:153], v162 offset:35840
	ds_read_b128 v[208:211], v162 offset:49152
	ds_read_b128 v[212:215], v162 offset:50176
	ds_read_b128 v[216:219], v162 offset:51200
	ds_read_b128 v[220:223], v162 offset:52224
	ds_read_b128 v[154:157], v175 offset:32768
	ds_read_b128 v[158:161], v175 offset:33792
	ds_read_b128 v[178:181], v175 offset:34816
	ds_read_b128 v[182:185], v175 offset:35840
	ds_read_b128 v[186:189], v175 offset:36864
	ds_read_b128 v[190:193], v175 offset:37888
	ds_read_b128 v[194:197], v175 offset:38912
	ds_read_b128 v[198:201], v175 offset:39936
	s_mov_b32 m0, s77
	s_nop 0
	global_load_lds_dwordx4 v230, s[98:99]
	s_mov_b32 m0, s78
	s_nop 0
	global_load_lds_dwordx4 v231, s[98:99]
	s_waitcnt vmcnt(8)
	s_waitcnt lgkmcnt(0)
	s_setprio 1
	s_barrier
	v_mfma_f32_16x16x32_bf16 v[2:5], v[154:157], v[138:141], v[2:5]
	v_mfma_f32_16x16x32_bf16 v[6:9], v[154:157], v[146:149], v[6:9]
	v_mfma_f32_16x16x32_bf16 v[18:21], v[178:181], v[146:149], v[18:21]
	v_mfma_f32_16x16x32_bf16 v[10:13], v[178:181], v[138:141], v[10:13]
	v_mfma_f32_16x16x32_bf16 v[30:33], v[186:189], v[138:141], v[30:33]
	v_mfma_f32_16x16x32_bf16 v[42:45], v[186:189], v[146:149], v[42:45]
	v_mfma_f32_16x16x32_bf16 v[66:69], v[194:197], v[146:149], v[66:69]
	v_mfma_f32_16x16x32_bf16 v[54:57], v[194:197], v[138:141], v[54:57]
	v_mfma_f32_16x16x32_bf16 v[2:5], v[158:161], v[142:145], v[2:5]
	v_mfma_f32_16x16x32_bf16 v[6:9], v[158:161], v[150:153], v[6:9]
	v_mfma_f32_16x16x32_bf16 v[18:21], v[182:185], v[150:153], v[18:21]
	v_mfma_f32_16x16x32_bf16 v[10:13], v[182:185], v[142:145], v[10:13]
	v_mfma_f32_16x16x32_bf16 v[30:33], v[190:193], v[142:145], v[30:33]
	v_mfma_f32_16x16x32_bf16 v[42:45], v[190:193], v[150:153], v[42:45]
	v_mfma_f32_16x16x32_bf16 v[66:69], v[198:201], v[150:153], v[66:69]
	v_mfma_f32_16x16x32_bf16 v[54:57], v[198:201], v[142:145], v[54:57]
	v_mfma_f32_16x16x32_bf16 v[14:17], v[154:157], v[208:211], v[14:17]
	v_mfma_f32_16x16x32_bf16 v[22:25], v[154:157], v[216:219], v[22:25]
	v_mfma_f32_16x16x32_bf16 v[46:49], v[178:181], v[216:219], v[46:49]
	v_mfma_f32_16x16x32_bf16 v[34:37], v[178:181], v[208:211], v[34:37]
	v_mfma_f32_16x16x32_bf16 v[58:61], v[186:189], v[208:211], v[58:61]
	v_mfma_f32_16x16x32_bf16 v[70:73], v[186:189], v[216:219], v[70:73]
	v_mfma_f32_16x16x32_bf16 v[86:89], v[194:197], v[216:219], v[86:89]
	v_mfma_f32_16x16x32_bf16 v[78:81], v[194:197], v[208:211], v[78:81]
	v_mfma_f32_16x16x32_bf16 v[14:17], v[158:161], v[212:215], v[14:17]
	v_mfma_f32_16x16x32_bf16 v[22:25], v[158:161], v[220:223], v[22:25]
	v_mfma_f32_16x16x32_bf16 v[46:49], v[182:185], v[220:223], v[46:49]
	v_mfma_f32_16x16x32_bf16 v[34:37], v[182:185], v[212:215], v[34:37]
	v_mfma_f32_16x16x32_bf16 v[58:61], v[190:193], v[212:215], v[58:61]
	v_mfma_f32_16x16x32_bf16 v[70:73], v[190:193], v[220:223], v[70:73]
	v_mfma_f32_16x16x32_bf16 v[86:89], v[198:201], v[220:223], v[86:89]
	v_mfma_f32_16x16x32_bf16 v[78:81], v[198:201], v[212:215], v[78:81]
	s_barrier
	s_setprio 0
	ds_read_b128 v[154:157], v175 offset:49152
	ds_read_b128 v[158:161], v175 offset:50176
	ds_read_b128 v[178:181], v175 offset:51200
	ds_read_b128 v[182:185], v175 offset:52224
	ds_read_b128 v[186:189], v175 offset:53248
	ds_read_b128 v[190:193], v175 offset:54272
	ds_read_b128 v[194:197], v175 offset:55296
	ds_read_b128 v[198:201], v175 offset:56320
	s_mov_b32 m0, s35
	s_nop 0
	global_load_lds_dwordx4 v232, s[100:101]
	s_mov_b32 m0, s53
	s_nop 0
	global_load_lds_dwordx4 v233, s[100:101]
	s_mov_b32 m0, s56
	s_nop 0
	global_load_lds_dwordx4 v234, s[98:99]
	s_mov_b32 m0, s57
	s_nop 0
	global_load_lds_dwordx4 v235, s[98:99]
	s_mov_b32 m0, s54
	s_nop 0
	global_load_lds_dwordx4 v236, s[100:101]
	s_mov_b32 m0, s55
	s_nop 0
	global_load_lds_dwordx4 v237, s[100:101]
	s_add_i32 s58, s58, 2
	s_add_u32 s10, s10, 0x100
	s_addc_u32 s11, s11, 0
	s_add_u32 s98, s98, 0x100
	s_addc_u32 s99, s99, 0
	s_add_u32 s100, s100, 0x100
	s_addc_u32 s101, s101, 0
	s_cmp_gt_u32 s58, 27
	s_waitcnt vmcnt(8)
	s_waitcnt lgkmcnt(0)
	s_setprio 1
	s_barrier
	v_mfma_f32_16x16x32_bf16 v[26:29], v[154:157], v[138:141], v[26:29]
	v_mfma_f32_16x16x32_bf16 v[38:41], v[154:157], v[146:149], v[38:41]
	v_mfma_f32_16x16x32_bf16 v[62:65], v[178:181], v[146:149], v[62:65]
	v_mfma_f32_16x16x32_bf16 v[50:53], v[178:181], v[138:141], v[50:53]
	v_mfma_f32_16x16x32_bf16 v[74:77], v[186:189], v[138:141], v[74:77]
	v_mfma_f32_16x16x32_bf16 v[82:85], v[186:189], v[146:149], v[82:85]
	v_mfma_f32_16x16x32_bf16 v[94:97], v[194:197], v[146:149], v[94:97]
	v_mfma_f32_16x16x32_bf16 v[90:93], v[194:197], v[138:141], v[90:93]
	v_mfma_f32_16x16x32_bf16 v[26:29], v[158:161], v[142:145], v[26:29]
	v_mfma_f32_16x16x32_bf16 v[38:41], v[158:161], v[150:153], v[38:41]
	v_mfma_f32_16x16x32_bf16 v[62:65], v[182:185], v[150:153], v[62:65]
	v_mfma_f32_16x16x32_bf16 v[50:53], v[182:185], v[142:145], v[50:53]
	v_mfma_f32_16x16x32_bf16 v[74:77], v[190:193], v[142:145], v[74:77]
	v_mfma_f32_16x16x32_bf16 v[82:85], v[190:193], v[150:153], v[82:85]
	v_mfma_f32_16x16x32_bf16 v[94:97], v[198:201], v[150:153], v[94:97]
	v_mfma_f32_16x16x32_bf16 v[90:93], v[198:201], v[142:145], v[90:93]
	v_mfma_f32_16x16x32_bf16 v[98:101], v[154:157], v[208:211], v[98:101]
	v_mfma_f32_16x16x32_bf16 v[102:105], v[154:157], v[216:219], v[102:105]
	v_mfma_f32_16x16x32_bf16 v[110:113], v[178:181], v[216:219], v[110:113]
	v_mfma_f32_16x16x32_bf16 v[106:109], v[178:181], v[208:211], v[106:109]
	v_mfma_f32_16x16x32_bf16 v[114:117], v[186:189], v[208:211], v[114:117]
	v_mfma_f32_16x16x32_bf16 v[118:121], v[186:189], v[216:219], v[118:121]
	v_mfma_f32_16x16x32_bf16 v[126:129], v[194:197], v[216:219], v[126:129]
	v_mfma_f32_16x16x32_bf16 v[122:125], v[194:197], v[208:211], v[122:125]
	v_mfma_f32_16x16x32_bf16 v[98:101], v[158:161], v[212:215], v[98:101]
	v_mfma_f32_16x16x32_bf16 v[102:105], v[158:161], v[220:223], v[102:105]
	v_mfma_f32_16x16x32_bf16 v[110:113], v[182:185], v[220:223], v[110:113]
	v_mfma_f32_16x16x32_bf16 v[106:109], v[182:185], v[212:215], v[106:109]
	v_mfma_f32_16x16x32_bf16 v[114:117], v[190:193], v[212:215], v[114:117]
	v_mfma_f32_16x16x32_bf16 v[118:121], v[190:193], v[220:223], v[118:121]
	v_mfma_f32_16x16x32_bf16 v[126:129], v[198:201], v[220:223], v[126:129]
	v_mfma_f32_16x16x32_bf16 v[122:125], v[198:201], v[212:215], v[122:125]
	s_barrier
; #define LDA(dst, b, h)                                                                                     \
;   _Pragma("unroll") for (int m = 0; m < 4; ++m) _Pragma("unroll") for (int k = 0; k < 2; ++k) dst[m][k] = \
;       *reinterpret_cast<const bf16x8*>(shmc + aL + (((b) * 2 + (h)) * 16384 + (m * 2 + k) * 1024))
; #define LDB(dst, b, h)                                                                                     \
;   _Pragma("unroll") for (int n = 0; n < 2; ++n) _Pragma("unroll") for (int k = 0; k < 2; ++k) dst[n][k] = \
;       *reinterpret_cast<const bf16x8*>(shmc + bL + (((b) * 2 + (h)) * 16384 + (n * 2 + k) * 1024))
; #define OPAQ asm volatile("" : "+v"(aL), "+v"(bL))
; #define WAIT_V(n) asm volatile("s_waitcnt vmcnt(" #n ")" ::: "memory")
; #define WAIT_L(n) asm volatile("s_waitcnt lgkmcnt(" #n ")" ::: "memory")
; #define BAR __builtin_amdgcn_s_barrier()
; template <int EPI>
; __device__ __forceinline__ void phase_gemm(const Params& p, const GemmDesc& d, char* shmc) {
;     ...
;     }
;     {
;       OPAQ;
;       LDB(B0, 0, 0); LDA(At, 0, 0); STAGE_A(SA(1, 1), 1, nt - 1);
;       BAR; WAIT_L(0); MMA(0, 0, At, B0); BAR;
;       LDB(B1, 0, 1); BAR; WAIT_L(0); MMA(0, 1, At, B1); BAR;
;       LDA(At, 0, 1); WAIT_V(4); BAR; WAIT_L(0); MMA(1, 0, At, B0); MMA(1, 1, At, B1); BAR;
	s_cbranch_scc0 .LBB0_1153
	s_setprio 0
	s_add_u32 s8, s8, 0x80f80
	s_addc_u32 s9, s9, 0
	v_add_u32_e32 v162, 0, v205
	v_add_u32_e32 v175, 0, v204
	s_mov_b32 m0, s59
	ds_read_b128 v[130:133], v162
	ds_read_b128 v[134:137], v162 offset:1024
	ds_read_b128 v[138:141], v162 offset:2048
	ds_read_b128 v[142:145], v162 offset:3072
	ds_read_b128 v[146:149], v175
	ds_read_b128 v[150:153], v175 offset:1024
	ds_read_b128 v[154:157], v175 offset:2048
	ds_read_b128 v[158:161], v175 offset:3072
	ds_read_b128 v[178:181], v175 offset:4096
	ds_read_b128 v[182:185], v175 offset:5120
	ds_read_b128 v[186:189], v175 offset:6144
	ds_read_b128 v[190:193], v175 offset:7168
	global_load_lds_dwordx4 v174, s[8:9]
	s_mov_b32 m0, s68
	s_nop 0
	global_load_lds_dwordx4 v176, s[8:9]
	s_waitcnt vmcnt(8)
	s_barrier
	s_waitcnt lgkmcnt(0)
	s_setprio 1
	s_waitcnt lgkmcnt(0)
	v_mfma_f32_16x16x32_bf16 v[2:5], v[146:149], v[130:133], v[2:5]
	v_mfma_f32_16x16x32_bf16 v[6:9], v[146:149], v[138:141], v[6:9]
	v_mfma_f32_16x16x32_bf16 v[10:13], v[154:157], v[130:133], v[10:13]
	v_mfma_f32_16x16x32_bf16 v[18:21], v[154:157], v[138:141], v[18:21]
	v_mfma_f32_16x16x32_bf16 v[66:69], v[186:189], v[138:141], v[66:69]
	v_mfma_f32_16x16x32_bf16 v[2:5], v[150:153], v[134:137], v[2:5]
	v_mfma_f32_16x16x32_bf16 v[6:9], v[150:153], v[142:145], v[6:9]
	v_mfma_f32_16x16x32_bf16 v[10:13], v[158:161], v[134:137], v[10:13]
	v_mfma_f32_16x16x32_bf16 v[18:21], v[158:161], v[142:145], v[18:21]
	v_mfma_f32_16x16x32_bf16 v[30:33], v[178:181], v[130:133], v[30:33]
	v_mfma_f32_16x16x32_bf16 v[42:45], v[178:181], v[138:141], v[42:45]
	v_mfma_f32_16x16x32_bf16 v[54:57], v[186:189], v[130:133], v[54:57]
	v_mfma_f32_16x16x32_bf16 v[66:69], v[190:193], v[142:145], v[66:69]
	v_mfma_f32_16x16x32_bf16 v[30:33], v[182:185], v[134:137], v[30:33]
	v_mfma_f32_16x16x32_bf16 v[42:45], v[182:185], v[142:145], v[42:45]
	v_mfma_f32_16x16x32_bf16 v[54:57], v[190:193], v[134:137], v[54:57]
	s_setprio 0
	s_barrier
	ds_read_b128 v[194:197], v162 offset:16384
	ds_read_b128 v[198:201], v162 offset:17408
	ds_read_b128 v[208:211], v162 offset:18432
	ds_read_b128 v[212:215], v162 offset:19456
	s_barrier
	s_waitcnt lgkmcnt(0)
	s_setprio 1
	s_waitcnt lgkmcnt(0)
	v_mfma_f32_16x16x32_bf16 v[14:17], v[146:149], v[194:197], v[14:17]
	v_mfma_f32_16x16x32_bf16 v[22:25], v[146:149], v[208:211], v[22:25]
	v_mfma_f32_16x16x32_bf16 v[58:61], v[178:181], v[194:197], v[58:61]
	v_mfma_f32_16x16x32_bf16 v[14:17], v[150:153], v[198:201], v[14:17]
	v_mfma_f32_16x16x32_bf16 v[22:25], v[150:153], v[212:215], v[22:25]
	v_mfma_f32_16x16x32_bf16 v[150:153], v[182:185], v[198:201], v[58:61]
	v_mfma_f32_16x16x32_bf16 v[58:61], v[178:181], v[208:211], v[70:73]
	v_mfma_f32_16x16x32_bf16 v[34:37], v[154:157], v[194:197], v[34:37]
	v_mfma_f32_16x16x32_bf16 v[46:49], v[154:157], v[208:211], v[46:49]
	v_mfma_f32_16x16x32_bf16 v[154:157], v[182:185], v[212:215], v[58:61]
	v_mfma_f32_16x16x32_bf16 v[58:61], v[186:189], v[194:197], v[78:81]
	v_mfma_f32_16x16x32_bf16 v[78:81], v[190:193], v[198:201], v[58:61]
	v_mfma_f32_16x16x32_bf16 v[58:61], v[186:189], v[208:211], v[86:89]
	v_mfma_f32_16x16x32_bf16 v[86:89], v[190:193], v[212:215], v[58:61]
	v_mfma_f32_16x16x32_bf16 v[34:37], v[158:161], v[198:201], v[34:37]
	v_mfma_f32_16x16x32_bf16 v[46:49], v[158:161], v[212:215], v[46:49]
	s_setprio 0
	s_barrier
	s_nop 2
	ds_read_b128 v[58:61], v175 offset:16384
	ds_read_b128 v[70:73], v175 offset:17408
	ds_read_b128 v[146:149], v175 offset:18432
	ds_read_b128 v[158:161], v175 offset:19456
	ds_read_b128 v[178:181], v175 offset:20480
	ds_read_b128 v[182:185], v175 offset:21504
	ds_read_b128 v[186:189], v175 offset:22528
	ds_read_b128 v[190:193], v175 offset:23552
	s_waitcnt vmcnt(4)
	s_barrier
	s_waitcnt lgkmcnt(0)
	s_setprio 1
	s_waitcnt lgkmcnt(0)
	v_mfma_f32_16x16x32_bf16 v[74:77], v[178:181], v[130:133], v[74:77]
	v_mfma_f32_16x16x32_bf16 v[216:219], v[182:185], v[134:137], v[74:77]
	v_mfma_f32_16x16x32_bf16 v[74:77], v[178:181], v[138:141], v[82:85]
	v_mfma_f32_16x16x32_bf16 v[26:29], v[58:61], v[130:133], v[26:29]
	v_mfma_f32_16x16x32_bf16 v[82:85], v[182:185], v[142:145], v[74:77]
	v_mfma_f32_16x16x32_bf16 v[74:77], v[186:189], v[130:133], v[90:93]
	v_mfma_f32_16x16x32_bf16 v[26:29], v[70:73], v[134:137], v[26:29]
	v_mfma_f32_16x16x32_bf16 v[38:41], v[58:61], v[138:141], v[38:41]
	v_mfma_f32_16x16x32_bf16 v[50:53], v[146:149], v[130:133], v[50:53]
	v_mfma_f32_16x16x32_bf16 v[62:65], v[146:149], v[138:141], v[62:65]
	v_mfma_f32_16x16x32_bf16 v[90:93], v[190:193], v[134:137], v[74:77]
	v_mfma_f32_16x16x32_bf16 v[74:77], v[186:189], v[138:141], v[94:97]
	v_mfma_f32_16x16x32_bf16 v[38:41], v[70:73], v[142:145], v[38:41]
	v_mfma_f32_16x16x32_bf16 v[50:53], v[158:161], v[134:137], v[50:53]
	v_mfma_f32_16x16x32_bf16 v[62:65], v[158:161], v[142:145], v[62:65]
	v_mfma_f32_16x16x32_bf16 v[220:223], v[190:193], v[142:145], v[74:77]
	s_setprio 0
	s_setprio 1
	v_mfma_f32_16x16x32_bf16 v[74:77], v[58:61], v[194:197], v[98:101]
	v_mfma_f32_16x16x32_bf16 v[58:61], v[58:61], v[208:211], v[102:105]
	v_mfma_f32_16x16x32_bf16 v[228:231], v[70:73], v[212:215], v[58:61]
	v_mfma_f32_16x16x32_bf16 v[58:61], v[146:149], v[194:197], v[106:109]
	v_mfma_f32_16x16x32_bf16 v[232:235], v[158:161], v[198:201], v[58:61]
	v_mfma_f32_16x16x32_bf16 v[58:61], v[146:149], v[208:211], v[110:113]
	v_mfma_f32_16x16x32_bf16 v[236:239], v[158:161], v[212:215], v[58:61]
	v_mfma_f32_16x16x32_bf16 v[58:61], v[178:181], v[194:197], v[114:117]
	v_mfma_f32_16x16x32_bf16 v[240:243], v[182:185], v[198:201], v[58:61]
	v_mfma_f32_16x16x32_bf16 v[58:61], v[178:181], v[208:211], v[118:121]
	v_mfma_f32_16x16x32_bf16 v[178:181], v[182:185], v[212:215], v[58:61]
	v_mfma_f32_16x16x32_bf16 v[58:61], v[186:189], v[194:197], v[122:125]
	v_mfma_f32_16x16x32_bf16 v[182:185], v[190:193], v[198:201], v[58:61]
	v_mfma_f32_16x16x32_bf16 v[58:61], v[186:189], v[208:211], v[126:129]
	v_mfma_f32_16x16x32_bf16 v[224:227], v[70:73], v[198:201], v[74:77]
	v_mfma_f32_16x16x32_bf16 v[186:189], v[190:193], v[212:215], v[58:61]
	s_setprio 0
	s_barrier
; #define LDA(dst, b, h)                                                                                     \
;   _Pragma("unroll") for (int m = 0; m < 4; ++m) _Pragma("unroll") for (int k = 0; k < 2; ++k) dst[m][k] = \
;       *reinterpret_cast<const bf16x8*>(shmc + aL + (((b) * 2 + (h)) * 16384 + (m * 2 + k) * 1024))
; #define LDB(dst, b, h)                                                                                     \
;   _Pragma("unroll") for (int n = 0; n < 2; ++n) _Pragma("unroll") for (int k = 0; k < 2; ++k) dst[n][k] = \
;       *reinterpret_cast<const bf16x8*>(shmc + bL + (((b) * 2 + (h)) * 16384 + (n * 2 + k) * 1024))
; #define WAIT_V(n) asm volatile("s_waitcnt vmcnt(" #n ")" ::: "memory")
; #define WAIT_L(n) asm volatile("s_waitcnt lgkmcnt(" #n ")" ::: "memory")
; #define BAR __builtin_amdgcn_s_barrier()
; template <int EPI>
; __device__ __forceinline__ void phase_gemm(const Params& p, const GemmDesc& d, char* shmc) {
;     ...
;     {
;       LDB(B0, 1, 0); LDA(At, 1, 0); WAIT_V(2); BAR; WAIT_L(0); MMA(0, 0, At, B0); BAR;
;       LDB(B1, 1, 1); WAIT_V(0); BAR; WAIT_L(0); MMA(0, 1, At, B1); BAR;
;       LDA(At, 1, 1); BAR; WAIT_L(0); MMA(1, 0, At, B0); MMA(1, 1, At, B1); BAR;
;     }
;     if (wr == 0) BAR;
	ds_read_b128 v[98:101], v162 offset:32768
	ds_read_b128 v[106:109], v162 offset:33792
	ds_read_b128 v[190:193], v162 offset:34816
	ds_read_b128 v[194:197], v162 offset:35840
	ds_read_b128 v[58:61], v175 offset:32768
	ds_read_b128 v[70:73], v175 offset:33792
	ds_read_b128 v[114:117], v175 offset:34816
	ds_read_b128 v[122:125], v175 offset:35840
	ds_read_b128 v[130:133], v175 offset:36864
	ds_read_b128 v[138:141], v175 offset:37888
	ds_read_b128 v[198:201], v175 offset:38912
	ds_read_b128 v[208:211], v175 offset:39936
	s_waitcnt vmcnt(2)
	s_barrier
	s_waitcnt lgkmcnt(0)
	s_setprio 1
	s_waitcnt lgkmcnt(0)
	v_mfma_f32_16x16x32_bf16 v[2:5], v[58:61], v[98:101], v[2:5]
	v_mfma_f32_16x16x32_bf16 v[158:161], v[70:73], v[106:109], v[2:5]
	v_mfma_f32_16x16x32_bf16 v[2:5], v[58:61], v[190:193], v[6:9]
	v_mfma_f32_16x16x32_bf16 v[146:149], v[70:73], v[194:197], v[2:5]
	v_mfma_f32_16x16x32_bf16 v[2:5], v[114:117], v[98:101], v[10:13]
	v_mfma_f32_16x16x32_bf16 v[142:145], v[122:125], v[106:109], v[2:5]
	v_mfma_f32_16x16x32_bf16 v[2:5], v[114:117], v[190:193], v[18:21]
	v_mfma_f32_16x16x32_bf16 v[134:137], v[122:125], v[194:197], v[2:5]
	v_mfma_f32_16x16x32_bf16 v[2:5], v[130:133], v[98:101], v[30:33]
	v_mfma_f32_16x16x32_bf16 v[126:129], v[138:141], v[106:109], v[2:5]
	v_mfma_f32_16x16x32_bf16 v[2:5], v[130:133], v[190:193], v[42:45]
	v_mfma_f32_16x16x32_bf16 v[118:121], v[138:141], v[194:197], v[2:5]
	v_mfma_f32_16x16x32_bf16 v[2:5], v[198:201], v[98:101], v[54:57]
	v_mfma_f32_16x16x32_bf16 v[110:113], v[208:211], v[106:109], v[2:5]
	v_mfma_f32_16x16x32_bf16 v[2:5], v[198:201], v[190:193], v[66:69]
	v_mfma_f32_16x16x32_bf16 v[102:105], v[208:211], v[194:197], v[2:5]
	s_setprio 0
	s_barrier
	ds_read_b128 v[30:33], v162 offset:49152
	ds_read_b128 v[42:45], v162 offset:50176
	ds_read_b128 v[54:57], v162 offset:51200
	ds_read_b128 v[212:215], v162 offset:52224
	s_waitcnt vmcnt(0)
	s_barrier
	s_waitcnt lgkmcnt(0)
	s_setprio 1
	s_waitcnt lgkmcnt(0)
	v_mfma_f32_16x16x32_bf16 v[2:5], v[58:61], v[30:33], v[14:17]
	v_mfma_f32_16x16x32_bf16 v[94:97], v[70:73], v[42:45], v[2:5]
	v_mfma_f32_16x16x32_bf16 v[2:5], v[58:61], v[54:57], v[22:25]
	v_mfma_f32_16x16x32_bf16 v[58:61], v[70:73], v[212:215], v[2:5]
	v_mfma_f32_16x16x32_bf16 v[2:5], v[114:117], v[30:33], v[34:37]
	v_mfma_f32_16x16x32_bf16 v[74:77], v[122:125], v[42:45], v[2:5]
	v_mfma_f32_16x16x32_bf16 v[2:5], v[114:117], v[54:57], v[46:49]
	v_mfma_f32_16x16x32_bf16 v[10:13], v[122:125], v[212:215], v[2:5]
	v_mfma_f32_16x16x32_bf16 v[2:5], v[130:133], v[30:33], v[150:153]
	v_mfma_f32_16x16x32_bf16 v[70:73], v[138:141], v[42:45], v[2:5]
	v_mfma_f32_16x16x32_bf16 v[2:5], v[130:133], v[54:57], v[154:157]
	v_mfma_f32_16x16x32_bf16 v[6:9], v[138:141], v[212:215], v[2:5]
	v_mfma_f32_16x16x32_bf16 v[2:5], v[198:201], v[30:33], v[78:81]
	v_mfma_f32_16x16x32_bf16 v[66:69], v[208:211], v[42:45], v[2:5]
	v_mfma_f32_16x16x32_bf16 v[2:5], v[198:201], v[54:57], v[86:89]
	v_mfma_f32_16x16x32_bf16 v[2:5], v[208:211], v[212:215], v[2:5]
	s_setprio 0
	s_barrier
	ds_read_b128 v[14:17], v175 offset:49152
	ds_read_b128 v[18:21], v175 offset:50176
	ds_read_b128 v[22:25], v175 offset:51200
	ds_read_b128 v[34:37], v175 offset:52224
	ds_read_b128 v[46:49], v175 offset:53248
	ds_read_b128 v[78:81], v175 offset:54272
	ds_read_b128 v[198:201], v175 offset:55296
	ds_read_b128 v[208:211], v175 offset:56320
	s_barrier
	s_waitcnt lgkmcnt(0)
	s_setprio 1
	s_waitcnt lgkmcnt(0)
	v_mfma_f32_16x16x32_bf16 v[26:29], v[14:17], v[98:101], v[26:29]
	v_mfma_f32_16x16x32_bf16 v[154:157], v[18:21], v[106:109], v[26:29]
	v_mfma_f32_16x16x32_bf16 v[26:29], v[14:17], v[190:193], v[38:41]
	v_mfma_f32_16x16x32_bf16 v[150:153], v[18:21], v[194:197], v[26:29]
	v_mfma_f32_16x16x32_bf16 v[26:29], v[22:25], v[98:101], v[50:53]
	v_mfma_f32_16x16x32_bf16 v[138:141], v[34:37], v[106:109], v[26:29]
	v_mfma_f32_16x16x32_bf16 v[26:29], v[22:25], v[190:193], v[62:65]
	v_mfma_f32_16x16x32_bf16 v[130:133], v[34:37], v[194:197], v[26:29]
	v_mfma_f32_16x16x32_bf16 v[26:29], v[46:49], v[98:101], v[216:219]
	v_mfma_f32_16x16x32_bf16 v[122:125], v[78:81], v[106:109], v[26:29]
	v_mfma_f32_16x16x32_bf16 v[26:29], v[46:49], v[190:193], v[82:85]
	v_mfma_f32_16x16x32_bf16 v[114:117], v[78:81], v[194:197], v[26:29]
	v_mfma_f32_16x16x32_bf16 v[26:29], v[198:201], v[98:101], v[90:93]
	v_mfma_f32_16x16x32_bf16 v[106:109], v[208:211], v[106:109], v[26:29]
	v_mfma_f32_16x16x32_bf16 v[26:29], v[198:201], v[190:193], v[220:223]
	v_mfma_f32_16x16x32_bf16 v[98:101], v[208:211], v[194:197], v[26:29]
	s_setprio 0
	s_setprio 1
	v_mfma_f32_16x16x32_bf16 v[26:29], v[14:17], v[30:33], v[224:227]
	v_mfma_f32_16x16x32_bf16 v[14:17], v[14:17], v[54:57], v[228:231]
	v_mfma_f32_16x16x32_bf16 v[90:93], v[18:21], v[42:45], v[26:29]
	v_mfma_f32_16x16x32_bf16 v[26:29], v[18:21], v[212:215], v[14:17]
	v_mfma_f32_16x16x32_bf16 v[14:17], v[22:25], v[30:33], v[232:235]
	v_mfma_f32_16x16x32_bf16 v[86:89], v[34:37], v[42:45], v[14:17]
	v_mfma_f32_16x16x32_bf16 v[14:17], v[22:25], v[54:57], v[236:239]
	v_mfma_f32_16x16x32_bf16 v[22:25], v[34:37], v[212:215], v[14:17]
	v_mfma_f32_16x16x32_bf16 v[14:17], v[46:49], v[30:33], v[240:243]
	v_mfma_f32_16x16x32_bf16 v[82:85], v[78:81], v[42:45], v[14:17]
	v_mfma_f32_16x16x32_bf16 v[14:17], v[46:49], v[54:57], v[178:181]
	v_mfma_f32_16x16x32_bf16 v[18:21], v[78:81], v[212:215], v[14:17]
	v_mfma_f32_16x16x32_bf16 v[14:17], v[198:201], v[30:33], v[182:185]
	v_mfma_f32_16x16x32_bf16 v[78:81], v[208:211], v[42:45], v[14:17]
	v_mfma_f32_16x16x32_bf16 v[14:17], v[198:201], v[54:57], v[186:189]
	v_mfma_f32_16x16x32_bf16 v[14:17], v[208:211], v[212:215], v[14:17]
	s_setprio 0
	s_barrier
	s_and_saveexec_b64 s[8:9], s[6:7]
	s_cbranch_execz .LBB0_1156
	s_barrier

; #define LDA(dst, b, h)                                                                                     \
;   _Pragma("unroll") for (int m = 0; m < 4; ++m) _Pragma("unroll") for (int k = 0; k < 2; ++k) dst[m][k] = \
;       *reinterpret_cast<const bf16x8*>(shmc + aL + (((b) * 2 + (h)) * 16384 + (m * 2 + k) * 1024))
; #define LDB(dst, b, h)                                                                                     \
;   _Pragma("unroll") for (int n = 0; n < 2; ++n) _Pragma("unroll") for (int k = 0; k < 2; ++k) dst[n][k] = \
;       *reinterpret_cast<const bf16x8*>(shmc + bL + (((b) * 2 + (h)) * 16384 + (n * 2 + k) * 1024))
; #define OPAQ asm volatile("" : "+v"(aL), "+v"(bL))
; #define WAIT_V(n) asm volatile("s_waitcnt vmcnt(" #n ")" ::: "memory")
; #define WAIT_L(n) asm volatile("s_waitcnt lgkmcnt(" #n ")" ::: "memory")
; #define BAR __builtin_amdgcn_s_barrier()
; #define SCHED __builtin_amdgcn_sched_barrier(0)
; template <int EPI>
; __device__ __forceinline__ void phase_gemm(const Params& p, const GemmDesc& d, char* shmc) {
;     ...
;     for (int t = 0; t < nt - 2; t += 2) {
;       OPAQ;
;       LDB(B0, 0, 0); SCHED; LDA(At, 0, 0); STAGE_A(SA(1, 1), 1, t + 1);
;       WAIT_L(8); BAR; WAIT_L(0); MMA(0, 0, At, B0); BAR; SCHED;
;       LDB(B1, 0, 1); STAGE_B(SB(0, 0), 0, t + 2);
;       BAR; WAIT_L(0); MMA(0, 1, At, B1); BAR;
;       LDA(At, 0, 1); STAGE_A(SA(0, 0), 0, t + 2);
;       BAR; WAIT_L(0); MMA(1, 0, At, B0); BAR; SCHED;
;       STAGE_B(SB(0, 1), 1, t + 2);
;       WAIT_V(6); BAR; MMA(1, 1, At, B1); BAR;
.LBB0_1312:
	s_nop 0
	v_add_u32_e32 v130, 0, v153
	v_add_u32_e32 v141, 0, v152
	s_setprio 0
	ds_read_b128 v[156:159], v130
	ds_read_b128 v[160:163], v130 offset:1024
	ds_read_b128 v[164:167], v130 offset:2048
	ds_read_b128 v[168:171], v130 offset:3072
	ds_read_b128 v[204:207], v130 offset:16384
	ds_read_b128 v[208:211], v130 offset:17408
	ds_read_b128 v[212:215], v130 offset:18432
	ds_read_b128 v[216:219], v130 offset:19456
	ds_read_b128 v[172:175], v141
	ds_read_b128 v[176:179], v141 offset:1024
	ds_read_b128 v[180:183], v141 offset:2048
	ds_read_b128 v[184:187], v141 offset:3072
	ds_read_b128 v[188:191], v141 offset:4096
	ds_read_b128 v[192:195], v141 offset:5120
	ds_read_b128 v[196:199], v141 offset:6144
	ds_read_b128 v[200:203], v141 offset:7168
	s_mov_b32 m0, s59
	s_nop 0
	global_load_lds_dwordx4 v220, s[98:99]
	s_mov_b32 m0, s60
	s_nop 0
	global_load_lds_dwordx4 v221, s[98:99]
	s_waitcnt vmcnt(8)
	s_waitcnt lgkmcnt(0)
	s_setprio 1
	s_barrier
	v_mfma_f32_16x16x32_bf16 v[126:129], v[156:159], v[172:175], v[126:129]
	v_mfma_f32_16x16x32_bf16 v[122:125], v[164:167], v[172:175], v[122:125]
	v_mfma_f32_16x16x32_bf16 v[114:117], v[164:167], v[180:183], v[114:117]
	v_mfma_f32_16x16x32_bf16 v[118:121], v[156:159], v[180:183], v[118:121]
	v_mfma_f32_16x16x32_bf16 v[110:113], v[156:159], v[188:191], v[110:113]
	v_mfma_f32_16x16x32_bf16 v[106:109], v[164:167], v[188:191], v[106:109]
	v_mfma_f32_16x16x32_bf16 v[98:101], v[164:167], v[196:199], v[98:101]
	v_mfma_f32_16x16x32_bf16 v[102:105], v[156:159], v[196:199], v[102:105]
	v_mfma_f32_16x16x32_bf16 v[126:129], v[160:163], v[176:179], v[126:129]
	v_mfma_f32_16x16x32_bf16 v[122:125], v[168:171], v[176:179], v[122:125]
	v_mfma_f32_16x16x32_bf16 v[114:117], v[168:171], v[184:187], v[114:117]
	v_mfma_f32_16x16x32_bf16 v[118:121], v[160:163], v[184:187], v[118:121]
	v_mfma_f32_16x16x32_bf16 v[110:113], v[160:163], v[192:195], v[110:113]
	v_mfma_f32_16x16x32_bf16 v[106:109], v[168:171], v[192:195], v[106:109]
	v_mfma_f32_16x16x32_bf16 v[98:101], v[168:171], v[200:203], v[98:101]
	v_mfma_f32_16x16x32_bf16 v[102:105], v[160:163], v[200:203], v[102:105]
	v_mfma_f32_16x16x32_bf16 v[86:89], v[204:207], v[172:175], v[86:89]
	v_mfma_f32_16x16x32_bf16 v[70:73], v[212:215], v[172:175], v[70:73]
	v_mfma_f32_16x16x32_bf16 v[50:53], v[212:215], v[180:183], v[50:53]
	v_mfma_f32_16x16x32_bf16 v[54:57], v[204:207], v[180:183], v[54:57]
	v_mfma_f32_16x16x32_bf16 v[46:49], v[204:207], v[188:191], v[46:49]
	v_mfma_f32_16x16x32_bf16 v[42:45], v[212:215], v[188:191], v[42:45]
	v_mfma_f32_16x16x32_bf16 v[34:37], v[212:215], v[196:199], v[34:37]
	v_mfma_f32_16x16x32_bf16 v[38:41], v[204:207], v[196:199], v[38:41]
	v_mfma_f32_16x16x32_bf16 v[86:89], v[208:211], v[176:179], v[86:89]
	v_mfma_f32_16x16x32_bf16 v[70:73], v[216:219], v[176:179], v[70:73]
	v_mfma_f32_16x16x32_bf16 v[50:53], v[216:219], v[184:187], v[50:53]
	v_mfma_f32_16x16x32_bf16 v[54:57], v[208:211], v[184:187], v[54:57]
	v_mfma_f32_16x16x32_bf16 v[46:49], v[208:211], v[192:195], v[46:49]
	v_mfma_f32_16x16x32_bf16 v[42:45], v[216:219], v[192:195], v[42:45]
	v_mfma_f32_16x16x32_bf16 v[34:37], v[216:219], v[200:203], v[34:37]
	v_mfma_f32_16x16x32_bf16 v[38:41], v[208:211], v[200:203], v[38:41]
	s_barrier
	s_setprio 0
	ds_read_b128 v[172:175], v141 offset:16384
	ds_read_b128 v[176:179], v141 offset:17408
	ds_read_b128 v[180:183], v141 offset:18432
	ds_read_b128 v[184:187], v141 offset:19456
	ds_read_b128 v[188:191], v141 offset:20480
	ds_read_b128 v[192:195], v141 offset:21504
	ds_read_b128 v[196:199], v141 offset:22528
	ds_read_b128 v[200:203], v141 offset:23552
	s_mov_b32 m0, s34
	s_nop 0
	global_load_lds_dwordx4 v222, s[100:101]
	s_mov_b32 m0, s35
	s_nop 0
	global_load_lds_dwordx4 v223, s[100:101]
	s_mov_b32 m0, s33
	s_nop 0
	global_load_lds_dwordx4 v224, s[98:99]
	s_mov_b32 m0, s46
	s_nop 0
	global_load_lds_dwordx4 v225, s[98:99]
	s_mov_b32 m0, s47
	s_nop 0
	global_load_lds_dwordx4 v226, s[100:101]
	s_mov_b32 m0, s48
	s_nop 0
	global_load_lds_dwordx4 v227, s[100:101]
	s_waitcnt vmcnt(8)
	s_waitcnt lgkmcnt(0)
	s_setprio 1
	s_barrier
	v_mfma_f32_16x16x32_bf16 v[30:33], v[156:159], v[172:175], v[30:33]
	v_mfma_f32_16x16x32_bf16 v[26:29], v[164:167], v[172:175], v[26:29]
	v_mfma_f32_16x16x32_bf16 v[18:21], v[164:167], v[180:183], v[18:21]
	v_mfma_f32_16x16x32_bf16 v[22:25], v[156:159], v[180:183], v[22:25]
	v_mfma_f32_16x16x32_bf16 v[14:17], v[156:159], v[188:191], v[14:17]
	v_mfma_f32_16x16x32_bf16 v[10:13], v[164:167], v[188:191], v[10:13]
	v_mfma_f32_16x16x32_bf16 v[2:5], v[164:167], v[196:199], v[2:5]
	v_mfma_f32_16x16x32_bf16 v[6:9], v[156:159], v[196:199], v[6:9]
	v_mfma_f32_16x16x32_bf16 v[30:33], v[160:163], v[176:179], v[30:33]
	v_mfma_f32_16x16x32_bf16 v[26:29], v[168:171], v[176:179], v[26:29]
	v_mfma_f32_16x16x32_bf16 v[18:21], v[168:171], v[184:187], v[18:21]
	v_mfma_f32_16x16x32_bf16 v[22:25], v[160:163], v[184:187], v[22:25]
	v_mfma_f32_16x16x32_bf16 v[14:17], v[160:163], v[192:195], v[14:17]
	v_mfma_f32_16x16x32_bf16 v[10:13], v[168:171], v[192:195], v[10:13]
	v_mfma_f32_16x16x32_bf16 v[2:5], v[168:171], v[200:203], v[2:5]
	v_mfma_f32_16x16x32_bf16 v[6:9], v[160:163], v[200:203], v[6:9]
	v_mfma_f32_16x16x32_bf16 v[58:61], v[204:207], v[172:175], v[58:61]
	v_mfma_f32_16x16x32_bf16 v[62:65], v[212:215], v[172:175], v[62:65]
	v_mfma_f32_16x16x32_bf16 v[74:77], v[212:215], v[180:183], v[74:77]
	v_mfma_f32_16x16x32_bf16 v[66:69], v[204:207], v[180:183], v[66:69]
	v_mfma_f32_16x16x32_bf16 v[78:81], v[204:207], v[188:191], v[78:81]
	v_mfma_f32_16x16x32_bf16 v[82:85], v[212:215], v[188:191], v[82:85]
	v_mfma_f32_16x16x32_bf16 v[94:97], v[212:215], v[196:199], v[94:97]
	v_mfma_f32_16x16x32_bf16 v[90:93], v[204:207], v[196:199], v[90:93]
	v_mfma_f32_16x16x32_bf16 v[58:61], v[208:211], v[176:179], v[58:61]
	v_mfma_f32_16x16x32_bf16 v[62:65], v[216:219], v[176:179], v[62:65]
	v_mfma_f32_16x16x32_bf16 v[74:77], v[216:219], v[184:187], v[74:77]
	v_mfma_f32_16x16x32_bf16 v[66:69], v[208:211], v[184:187], v[66:69]
	v_mfma_f32_16x16x32_bf16 v[78:81], v[208:211], v[192:195], v[78:81]
	v_mfma_f32_16x16x32_bf16 v[82:85], v[216:219], v[192:195], v[82:85]
	v_mfma_f32_16x16x32_bf16 v[94:97], v[216:219], v[200:203], v[94:97]
	v_mfma_f32_16x16x32_bf16 v[90:93], v[208:211], v[200:203], v[90:93]
	s_barrier
; #define LDA(dst, b, h)                                                                                     \
;   _Pragma("unroll") for (int m = 0; m < 4; ++m) _Pragma("unroll") for (int k = 0; k < 2; ++k) dst[m][k] = \
;       *reinterpret_cast<const bf16x8*>(shmc + aL + (((b) * 2 + (h)) * 16384 + (m * 2 + k) * 1024))
; #define LDB(dst, b, h)                                                                                     \
;   _Pragma("unroll") for (int n = 0; n < 2; ++n) _Pragma("unroll") for (int k = 0; k < 2; ++k) dst[n][k] = \
;       *reinterpret_cast<const bf16x8*>(shmc + bL + (((b) * 2 + (h)) * 16384 + (n * 2 + k) * 1024))
; #define WAIT_V(n) asm volatile("s_waitcnt vmcnt(" #n ")" ::: "memory")
; #define WAIT_L(n) asm volatile("s_waitcnt lgkmcnt(" #n ")" ::: "memory")
; #define BAR __builtin_amdgcn_s_barrier()
; #define SCHED __builtin_amdgcn_sched_barrier(0)
; template <int EPI>
; __device__ __forceinline__ void phase_gemm(const Params& p, const GemmDesc& d, char* shmc) {
;     ...
;       LDB(B0, 1, 0); SCHED; LDA(At, 1, 0); STAGE_A(SA(0, 1), 1, t + 2);
;       WAIT_L(8); BAR; WAIT_L(0); MMA(0, 0, At, B0); BAR; SCHED;
;       LDB(B1, 1, 1); STAGE_B(SB(1, 0), 0, t + 3);
;       BAR; WAIT_L(0); MMA(0, 1, At, B1); BAR;
;       LDA(At, 1, 1); STAGE_A(SA(1, 0), 0, t + 3);
;       BAR; WAIT_L(0); MMA(1, 0, At, B0); BAR; SCHED;
;       STAGE_B(SB(1, 1), 1, t + 3);
;       WAIT_V(6); BAR; MMA(1, 1, At, B1); BAR;
;     }
	s_setprio 0
	ds_read_b128 v[156:159], v130 offset:32768
	ds_read_b128 v[160:163], v130 offset:33792
	ds_read_b128 v[164:167], v130 offset:34816
	ds_read_b128 v[168:171], v130 offset:35840
	ds_read_b128 v[204:207], v130 offset:49152
	ds_read_b128 v[208:211], v130 offset:50176
	ds_read_b128 v[212:215], v130 offset:51200
	ds_read_b128 v[216:219], v130 offset:52224
	ds_read_b128 v[172:175], v141 offset:32768
	ds_read_b128 v[176:179], v141 offset:33792
	ds_read_b128 v[180:183], v141 offset:34816
	ds_read_b128 v[184:187], v141 offset:35840
	ds_read_b128 v[188:191], v141 offset:36864
	ds_read_b128 v[192:195], v141 offset:37888
	ds_read_b128 v[196:199], v141 offset:38912
	ds_read_b128 v[200:203], v141 offset:39936
	s_mov_b32 m0, s49
	s_nop 0
	global_load_lds_dwordx4 v228, s[98:99]
	s_mov_b32 m0, s52
	s_nop 0
	global_load_lds_dwordx4 v229, s[98:99]
	s_waitcnt vmcnt(8)
	s_waitcnt lgkmcnt(0)
	s_setprio 1
	s_barrier
	v_mfma_f32_16x16x32_bf16 v[126:129], v[156:159], v[172:175], v[126:129]
	v_mfma_f32_16x16x32_bf16 v[122:125], v[164:167], v[172:175], v[122:125]
	v_mfma_f32_16x16x32_bf16 v[114:117], v[164:167], v[180:183], v[114:117]
	v_mfma_f32_16x16x32_bf16 v[118:121], v[156:159], v[180:183], v[118:121]
	v_mfma_f32_16x16x32_bf16 v[110:113], v[156:159], v[188:191], v[110:113]
	v_mfma_f32_16x16x32_bf16 v[106:109], v[164:167], v[188:191], v[106:109]
	v_mfma_f32_16x16x32_bf16 v[98:101], v[164:167], v[196:199], v[98:101]
	v_mfma_f32_16x16x32_bf16 v[102:105], v[156:159], v[196:199], v[102:105]
	v_mfma_f32_16x16x32_bf16 v[126:129], v[160:163], v[176:179], v[126:129]
	v_mfma_f32_16x16x32_bf16 v[122:125], v[168:171], v[176:179], v[122:125]
	v_mfma_f32_16x16x32_bf16 v[114:117], v[168:171], v[184:187], v[114:117]
	v_mfma_f32_16x16x32_bf16 v[118:121], v[160:163], v[184:187], v[118:121]
	v_mfma_f32_16x16x32_bf16 v[110:113], v[160:163], v[192:195], v[110:113]
	v_mfma_f32_16x16x32_bf16 v[106:109], v[168:171], v[192:195], v[106:109]
	v_mfma_f32_16x16x32_bf16 v[98:101], v[168:171], v[200:203], v[98:101]
	v_mfma_f32_16x16x32_bf16 v[102:105], v[160:163], v[200:203], v[102:105]
	v_mfma_f32_16x16x32_bf16 v[86:89], v[204:207], v[172:175], v[86:89]
	v_mfma_f32_16x16x32_bf16 v[70:73], v[212:215], v[172:175], v[70:73]
	v_mfma_f32_16x16x32_bf16 v[50:53], v[212:215], v[180:183], v[50:53]
	v_mfma_f32_16x16x32_bf16 v[54:57], v[204:207], v[180:183], v[54:57]
	v_mfma_f32_16x16x32_bf16 v[46:49], v[204:207], v[188:191], v[46:49]
	v_mfma_f32_16x16x32_bf16 v[42:45], v[212:215], v[188:191], v[42:45]
	v_mfma_f32_16x16x32_bf16 v[34:37], v[212:215], v[196:199], v[34:37]
	v_mfma_f32_16x16x32_bf16 v[38:41], v[204:207], v[196:199], v[38:41]
	v_mfma_f32_16x16x32_bf16 v[86:89], v[208:211], v[176:179], v[86:89]
	v_mfma_f32_16x16x32_bf16 v[70:73], v[216:219], v[176:179], v[70:73]
	v_mfma_f32_16x16x32_bf16 v[50:53], v[216:219], v[184:187], v[50:53]
	v_mfma_f32_16x16x32_bf16 v[54:57], v[208:211], v[184:187], v[54:57]
	v_mfma_f32_16x16x32_bf16 v[46:49], v[208:211], v[192:195], v[46:49]
	v_mfma_f32_16x16x32_bf16 v[42:45], v[216:219], v[192:195], v[42:45]
	v_mfma_f32_16x16x32_bf16 v[34:37], v[216:219], v[200:203], v[34:37]
	v_mfma_f32_16x16x32_bf16 v[38:41], v[208:211], v[200:203], v[38:41]
	s_barrier
	s_setprio 0
	ds_read_b128 v[172:175], v141 offset:49152
	ds_read_b128 v[176:179], v141 offset:50176
	ds_read_b128 v[180:183], v141 offset:51200
	ds_read_b128 v[184:187], v141 offset:52224
	ds_read_b128 v[188:191], v141 offset:53248
	ds_read_b128 v[192:195], v141 offset:54272
	ds_read_b128 v[196:199], v141 offset:55296
	ds_read_b128 v[200:203], v141 offset:56320
	s_mov_b32 m0, s53
	s_nop 0
	global_load_lds_dwordx4 v232, s[100:101]
	s_mov_b32 m0, s54
	s_nop 0
	global_load_lds_dwordx4 v233, s[100:101]
	s_mov_b32 m0, s55
	s_nop 0
	global_load_lds_dwordx4 v234, s[98:99]
	s_mov_b32 m0, s56
	s_nop 0
	global_load_lds_dwordx4 v235, s[98:99]
	s_mov_b32 m0, s57
	s_nop 0
	global_load_lds_dwordx4 v236, s[100:101]
	s_mov_b32 m0, s58
	s_nop 0
	global_load_lds_dwordx4 v237, s[100:101]
	s_add_i32 s42, s42, 2
	s_add_u32 s40, s40, 0x100
	s_addc_u32 s41, s41, 0
	s_add_u32 s98, s98, 0x100
	s_addc_u32 s99, s99, 0
	s_add_u32 s100, s100, 0x100
	s_addc_u32 s101, s101, 0
	s_cmpk_gt_u32 s42, 0x53
	s_waitcnt vmcnt(8)
	s_waitcnt lgkmcnt(0)
	s_setprio 1
	s_barrier
	v_mfma_f32_16x16x32_bf16 v[30:33], v[156:159], v[172:175], v[30:33]
	v_mfma_f32_16x16x32_bf16 v[26:29], v[164:167], v[172:175], v[26:29]
	v_mfma_f32_16x16x32_bf16 v[18:21], v[164:167], v[180:183], v[18:21]
	v_mfma_f32_16x16x32_bf16 v[22:25], v[156:159], v[180:183], v[22:25]
	v_mfma_f32_16x16x32_bf16 v[14:17], v[156:159], v[188:191], v[14:17]
	v_mfma_f32_16x16x32_bf16 v[10:13], v[164:167], v[188:191], v[10:13]
	v_mfma_f32_16x16x32_bf16 v[2:5], v[164:167], v[196:199], v[2:5]
	v_mfma_f32_16x16x32_bf16 v[6:9], v[156:159], v[196:199], v[6:9]
	v_mfma_f32_16x16x32_bf16 v[30:33], v[160:163], v[176:179], v[30:33]
	v_mfma_f32_16x16x32_bf16 v[26:29], v[168:171], v[176:179], v[26:29]
	v_mfma_f32_16x16x32_bf16 v[18:21], v[168:171], v[184:187], v[18:21]
	v_mfma_f32_16x16x32_bf16 v[22:25], v[160:163], v[184:187], v[22:25]
	v_mfma_f32_16x16x32_bf16 v[14:17], v[160:163], v[192:195], v[14:17]
	v_mfma_f32_16x16x32_bf16 v[10:13], v[168:171], v[192:195], v[10:13]
	v_mfma_f32_16x16x32_bf16 v[2:5], v[168:171], v[200:203], v[2:5]
	v_mfma_f32_16x16x32_bf16 v[6:9], v[160:163], v[200:203], v[6:9]
	v_mfma_f32_16x16x32_bf16 v[58:61], v[204:207], v[172:175], v[58:61]
	v_mfma_f32_16x16x32_bf16 v[62:65], v[212:215], v[172:175], v[62:65]
	v_mfma_f32_16x16x32_bf16 v[74:77], v[212:215], v[180:183], v[74:77]
	v_mfma_f32_16x16x32_bf16 v[66:69], v[204:207], v[180:183], v[66:69]
	v_mfma_f32_16x16x32_bf16 v[78:81], v[204:207], v[188:191], v[78:81]
	v_mfma_f32_16x16x32_bf16 v[82:85], v[212:215], v[188:191], v[82:85]
	v_mfma_f32_16x16x32_bf16 v[94:97], v[212:215], v[196:199], v[94:97]
	v_mfma_f32_16x16x32_bf16 v[90:93], v[204:207], v[196:199], v[90:93]
	v_mfma_f32_16x16x32_bf16 v[58:61], v[208:211], v[176:179], v[58:61]
	v_mfma_f32_16x16x32_bf16 v[62:65], v[216:219], v[176:179], v[62:65]
	v_mfma_f32_16x16x32_bf16 v[74:77], v[216:219], v[184:187], v[74:77]
	v_mfma_f32_16x16x32_bf16 v[66:69], v[208:211], v[184:187], v[66:69]
	v_mfma_f32_16x16x32_bf16 v[78:81], v[208:211], v[192:195], v[78:81]
	v_mfma_f32_16x16x32_bf16 v[82:85], v[216:219], v[192:195], v[82:85]
	v_mfma_f32_16x16x32_bf16 v[94:97], v[216:219], v[200:203], v[94:97]
	v_mfma_f32_16x16x32_bf16 v[90:93], v[208:211], v[200:203], v[90:93]
	s_barrier
; #define LDA(dst, b, h)                                                                                     \
;   _Pragma("unroll") for (int m = 0; m < 4; ++m) _Pragma("unroll") for (int k = 0; k < 2; ++k) dst[m][k] = \
;       *reinterpret_cast<const bf16x8*>(shmc + aL + (((b) * 2 + (h)) * 16384 + (m * 2 + k) * 1024))
; #define LDB(dst, b, h)                                                                                     \
;   _Pragma("unroll") for (int n = 0; n < 2; ++n) _Pragma("unroll") for (int k = 0; k < 2; ++k) dst[n][k] = \
;       *reinterpret_cast<const bf16x8*>(shmc + bL + (((b) * 2 + (h)) * 16384 + (n * 2 + k) * 1024))
; #define OPAQ asm volatile("" : "+v"(aL), "+v"(bL))
; #define WAIT_V(n) asm volatile("s_waitcnt vmcnt(" #n ")" ::: "memory")
; #define WAIT_L(n) asm volatile("s_waitcnt lgkmcnt(" #n ")" ::: "memory")
; #define BAR __builtin_amdgcn_s_barrier()
; template <int EPI>
; __device__ __forceinline__ void phase_gemm(const Params& p, const GemmDesc& d, char* shmc) {
;     ...
;     }
;     {
;       OPAQ;
;       LDB(B0, 0, 0); LDA(At, 0, 0); STAGE_A(SA(1, 1), 1, nt - 1);
;       BAR; WAIT_L(0); MMA(0, 0, At, B0); BAR;
;       LDB(B1, 0, 1); BAR; WAIT_L(0); MMA(0, 1, At, B1); BAR;
;       LDA(At, 0, 1); WAIT_V(4); BAR; WAIT_L(0); MMA(1, 0, At, B0); MMA(1, 1, At, B1); BAR;
;     }
	s_cbranch_scc0 .LBB0_1312
	s_setprio 0
	s_add_u32 s38, s38, 0x162b80
	s_addc_u32 s39, s39, 0
	v_add_u32_e32 v130, 0, v153
	v_add_u32_e32 v141, 0, v152
	s_mov_b32 m0, s59
	ds_read_b128 v[144:147], v130
	ds_read_b128 v[148:151], v130 offset:1024
	ds_read_b128 v[156:159], v130 offset:2048
	ds_read_b128 v[160:163], v130 offset:3072
	ds_read_b128 v[164:167], v141
	ds_read_b128 v[168:171], v141 offset:1024
	ds_read_b128 v[172:175], v141 offset:2048
	ds_read_b128 v[176:179], v141 offset:3072
	ds_read_b128 v[180:183], v141 offset:4096
	ds_read_b128 v[184:187], v141 offset:5120
	ds_read_b128 v[188:191], v141 offset:6144
	ds_read_b128 v[192:195], v141 offset:7168
	global_load_lds_dwordx4 v140, s[38:39]
	s_mov_b32 m0, s60
	s_nop 0
	global_load_lds_dwordx4 v142, s[38:39]
	s_waitcnt vmcnt(8)
	s_barrier
	s_waitcnt lgkmcnt(0)
	s_setprio 1
	s_waitcnt lgkmcnt(0)
	v_mfma_f32_16x16x32_bf16 v[126:129], v[144:147], v[164:167], v[126:129]
	v_mfma_f32_16x16x32_bf16 v[122:125], v[156:159], v[164:167], v[122:125]
	v_mfma_f32_16x16x32_bf16 v[114:117], v[156:159], v[172:175], v[114:117]
	v_mfma_f32_16x16x32_bf16 v[110:113], v[144:147], v[180:183], v[110:113]
	v_mfma_f32_16x16x32_bf16 v[102:105], v[144:147], v[188:191], v[102:105]
	v_mfma_f32_16x16x32_bf16 v[126:129], v[148:151], v[168:171], v[126:129]
	v_mfma_f32_16x16x32_bf16 v[122:125], v[160:163], v[168:171], v[122:125]
	v_mfma_f32_16x16x32_bf16 v[118:121], v[144:147], v[172:175], v[118:121]
	v_mfma_f32_16x16x32_bf16 v[114:117], v[160:163], v[176:179], v[114:117]
	v_mfma_f32_16x16x32_bf16 v[110:113], v[148:151], v[184:187], v[110:113]
	v_mfma_f32_16x16x32_bf16 v[106:109], v[156:159], v[180:183], v[106:109]
	v_mfma_f32_16x16x32_bf16 v[102:105], v[148:151], v[192:195], v[102:105]
	v_mfma_f32_16x16x32_bf16 v[98:101], v[156:159], v[188:191], v[98:101]
	v_mfma_f32_16x16x32_bf16 v[196:199], v[148:151], v[176:179], v[118:121]
	v_mfma_f32_16x16x32_bf16 v[200:203], v[160:163], v[184:187], v[106:109]
	v_mfma_f32_16x16x32_bf16 v[204:207], v[160:163], v[192:195], v[98:101]
	s_setprio 0
	s_barrier
	s_nop 2
	ds_read_b128 v[98:101], v130 offset:16384
	ds_read_b128 v[106:109], v130 offset:17408
	ds_read_b128 v[118:121], v130 offset:18432
	ds_read_b128 v[208:211], v130 offset:19456
	s_barrier
	s_waitcnt lgkmcnt(0)
	s_setprio 1
	s_waitcnt lgkmcnt(0)
	v_mfma_f32_16x16x32_bf16 v[86:89], v[98:101], v[164:167], v[86:89]
	v_mfma_f32_16x16x32_bf16 v[70:73], v[118:121], v[164:167], v[70:73]
	v_mfma_f32_16x16x32_bf16 v[54:57], v[98:101], v[172:175], v[54:57]
	v_mfma_f32_16x16x32_bf16 v[50:53], v[118:121], v[172:175], v[50:53]
	v_mfma_f32_16x16x32_bf16 v[46:49], v[98:101], v[180:183], v[46:49]
	v_mfma_f32_16x16x32_bf16 v[42:45], v[118:121], v[180:183], v[42:45]
	v_mfma_f32_16x16x32_bf16 v[38:41], v[98:101], v[188:191], v[38:41]
	v_mfma_f32_16x16x32_bf16 v[34:37], v[118:121], v[188:191], v[34:37]
	v_mfma_f32_16x16x32_bf16 v[86:89], v[106:109], v[168:171], v[86:89]
	v_mfma_f32_16x16x32_bf16 v[70:73], v[208:211], v[168:171], v[70:73]
	v_mfma_f32_16x16x32_bf16 v[54:57], v[106:109], v[176:179], v[54:57]
	v_mfma_f32_16x16x32_bf16 v[50:53], v[208:211], v[176:179], v[50:53]
	v_mfma_f32_16x16x32_bf16 v[46:49], v[106:109], v[184:187], v[46:49]
	v_mfma_f32_16x16x32_bf16 v[42:45], v[208:211], v[184:187], v[42:45]
	v_mfma_f32_16x16x32_bf16 v[38:41], v[106:109], v[192:195], v[38:41]
	v_mfma_f32_16x16x32_bf16 v[34:37], v[208:211], v[192:195], v[34:37]
	s_setprio 0
	s_barrier
	ds_read_b128 v[164:167], v141 offset:16384
	ds_read_b128 v[168:171], v141 offset:17408
	ds_read_b128 v[172:175], v141 offset:18432
	ds_read_b128 v[176:179], v141 offset:19456
	ds_read_b128 v[180:183], v141 offset:20480
	ds_read_b128 v[184:187], v141 offset:21504
	ds_read_b128 v[188:191], v141 offset:22528
	ds_read_b128 v[192:195], v141 offset:23552
	s_waitcnt vmcnt(4)
	s_barrier
	s_waitcnt lgkmcnt(0)
	s_setprio 1
	s_waitcnt lgkmcnt(0)
	v_mfma_f32_16x16x32_bf16 v[30:33], v[144:147], v[164:167], v[30:33]
	v_mfma_f32_16x16x32_bf16 v[26:29], v[156:159], v[164:167], v[26:29]
	v_mfma_f32_16x16x32_bf16 v[22:25], v[144:147], v[172:175], v[22:25]
	v_mfma_f32_16x16x32_bf16 v[18:21], v[156:159], v[172:175], v[18:21]
	v_mfma_f32_16x16x32_bf16 v[14:17], v[144:147], v[180:183], v[14:17]
	v_mfma_f32_16x16x32_bf16 v[10:13], v[156:159], v[180:183], v[10:13]
	v_mfma_f32_16x16x32_bf16 v[6:9], v[144:147], v[188:191], v[6:9]
	v_mfma_f32_16x16x32_bf16 v[2:5], v[156:159], v[188:191], v[2:5]
	v_mfma_f32_16x16x32_bf16 v[30:33], v[148:151], v[168:171], v[30:33]
	v_mfma_f32_16x16x32_bf16 v[26:29], v[160:163], v[168:171], v[26:29]
	v_mfma_f32_16x16x32_bf16 v[22:25], v[148:151], v[176:179], v[22:25]
	v_mfma_f32_16x16x32_bf16 v[18:21], v[160:163], v[176:179], v[18:21]
	v_mfma_f32_16x16x32_bf16 v[14:17], v[148:151], v[184:187], v[14:17]
	v_mfma_f32_16x16x32_bf16 v[10:13], v[160:163], v[184:187], v[10:13]
	v_mfma_f32_16x16x32_bf16 v[6:9], v[148:151], v[192:195], v[6:9]
	v_mfma_f32_16x16x32_bf16 v[2:5], v[160:163], v[192:195], v[2:5]
	s_setprio 0
	s_setprio 1
	v_mfma_f32_16x16x32_bf16 v[62:65], v[118:121], v[164:167], v[62:65]
	v_mfma_f32_16x16x32_bf16 v[144:147], v[208:211], v[168:171], v[62:65]
	v_mfma_f32_16x16x32_bf16 v[62:65], v[98:101], v[172:175], v[66:69]
	v_mfma_f32_16x16x32_bf16 v[148:151], v[106:109], v[176:179], v[62:65]
	v_mfma_f32_16x16x32_bf16 v[62:65], v[118:121], v[172:175], v[74:77]
	v_mfma_f32_16x16x32_bf16 v[156:159], v[208:211], v[176:179], v[62:65]
	v_mfma_f32_16x16x32_bf16 v[62:65], v[98:101], v[180:183], v[78:81]
	v_mfma_f32_16x16x32_bf16 v[160:163], v[106:109], v[184:187], v[62:65]
	v_mfma_f32_16x16x32_bf16 v[62:65], v[118:121], v[180:183], v[82:85]
	v_mfma_f32_16x16x32_bf16 v[58:61], v[98:101], v[164:167], v[58:61]
	v_mfma_f32_16x16x32_bf16 v[164:167], v[208:211], v[184:187], v[62:65]
	v_mfma_f32_16x16x32_bf16 v[62:65], v[98:101], v[188:191], v[90:93]
	v_mfma_f32_16x16x32_bf16 v[58:61], v[106:109], v[168:171], v[58:61]
	v_mfma_f32_16x16x32_bf16 v[168:171], v[106:109], v[192:195], v[62:65]
	v_mfma_f32_16x16x32_bf16 v[62:65], v[118:121], v[188:191], v[94:97]
	v_mfma_f32_16x16x32_bf16 v[172:175], v[208:211], v[192:195], v[62:65]
	s_setprio 0
	s_barrier
; #define LDA(dst, b, h)                                                                                     \
;   _Pragma("unroll") for (int m = 0; m < 4; ++m) _Pragma("unroll") for (int k = 0; k < 2; ++k) dst[m][k] = \
;       *reinterpret_cast<const bf16x8*>(shmc + aL + (((b) * 2 + (h)) * 16384 + (m * 2 + k) * 1024))
; #define LDB(dst, b, h)                                                                                     \
;   _Pragma("unroll") for (int n = 0; n < 2; ++n) _Pragma("unroll") for (int k = 0; k < 2; ++k) dst[n][k] = \
;       *reinterpret_cast<const bf16x8*>(shmc + bL + (((b) * 2 + (h)) * 16384 + (n * 2 + k) * 1024))
; #define WAIT_V(n) asm volatile("s_waitcnt vmcnt(" #n ")" ::: "memory")
; #define WAIT_L(n) asm volatile("s_waitcnt lgkmcnt(" #n ")" ::: "memory")
; #define BAR __builtin_amdgcn_s_barrier()
; template <int EPI>
; __device__ __forceinline__ void phase_gemm(const Params& p, const GemmDesc& d, char* shmc) {
;     ...
;     {
;       LDB(B0, 1, 0); LDA(At, 1, 0); WAIT_V(2); BAR; WAIT_L(0); MMA(0, 0, At, B0); BAR;
;       LDB(B1, 1, 1); WAIT_V(0); BAR; WAIT_L(0); MMA(0, 1, At, B1); BAR;
;       LDA(At, 1, 1); BAR; WAIT_L(0); MMA(1, 0, At, B0); MMA(1, 1, At, B1); BAR;
;     }
;     if (wr == 0) BAR;
	ds_read_b128 v[176:179], v130 offset:32768
	ds_read_b128 v[180:183], v130 offset:33792
	ds_read_b128 v[184:187], v130 offset:34816
	ds_read_b128 v[188:191], v130 offset:35840
	s_nop 0
	ds_read_b128 v[62:65], v141 offset:32768
	ds_read_b128 v[78:81], v141 offset:33792
	ds_read_b128 v[94:97], v141 offset:34816
	ds_read_b128 v[192:195], v141 offset:35840
	ds_read_b128 v[208:211], v141 offset:36864
	ds_read_b128 v[212:215], v141 offset:37888
	ds_read_b128 v[216:219], v141 offset:38912
	ds_read_b128 v[220:223], v141 offset:39936
	s_waitcnt vmcnt(2)
	s_barrier
	s_waitcnt lgkmcnt(0)
	s_setprio 1
	s_waitcnt lgkmcnt(0)
	v_mfma_f32_16x16x32_bf16 v[66:69], v[176:179], v[62:65], v[126:129]
	v_mfma_f32_16x16x32_bf16 v[126:129], v[180:183], v[78:81], v[66:69]
	v_mfma_f32_16x16x32_bf16 v[66:69], v[184:187], v[62:65], v[122:125]
	v_mfma_f32_16x16x32_bf16 v[118:121], v[188:191], v[78:81], v[66:69]
	v_mfma_f32_16x16x32_bf16 v[66:69], v[176:179], v[94:97], v[196:199]
	v_mfma_f32_16x16x32_bf16 v[106:109], v[180:183], v[192:195], v[66:69]
	v_mfma_f32_16x16x32_bf16 v[66:69], v[184:187], v[94:97], v[114:117]
	v_mfma_f32_16x16x32_bf16 v[98:101], v[188:191], v[192:195], v[66:69]
	v_mfma_f32_16x16x32_bf16 v[66:69], v[176:179], v[208:211], v[110:113]
	v_mfma_f32_16x16x32_bf16 v[90:93], v[180:183], v[212:215], v[66:69]
	v_mfma_f32_16x16x32_bf16 v[66:69], v[184:187], v[208:211], v[200:203]
	v_mfma_f32_16x16x32_bf16 v[82:85], v[188:191], v[212:215], v[66:69]
	v_mfma_f32_16x16x32_bf16 v[66:69], v[176:179], v[216:219], v[102:105]
	v_mfma_f32_16x16x32_bf16 v[74:77], v[180:183], v[220:223], v[66:69]
	v_mfma_f32_16x16x32_bf16 v[66:69], v[184:187], v[216:219], v[204:207]
	v_mfma_f32_16x16x32_bf16 v[66:69], v[188:191], v[220:223], v[66:69]
	s_setprio 0
	s_barrier
	ds_read_b128 v[196:199], v130 offset:49152
	ds_read_b128 v[200:203], v130 offset:50176
	ds_read_b128 v[204:207], v130 offset:51200
	ds_read_b128 v[224:227], v130 offset:52224
	s_waitcnt vmcnt(0)
	s_barrier
	s_waitcnt lgkmcnt(0)
	s_setprio 1
	s_waitcnt lgkmcnt(0)
	v_mfma_f32_16x16x32_bf16 v[86:89], v[196:199], v[62:65], v[86:89]
	v_mfma_f32_16x16x32_bf16 v[62:65], v[204:207], v[62:65], v[70:73]
	v_mfma_f32_16x16x32_bf16 v[54:57], v[196:199], v[94:97], v[54:57]
	v_mfma_f32_16x16x32_bf16 v[50:53], v[204:207], v[94:97], v[50:53]
	v_mfma_f32_16x16x32_bf16 v[46:49], v[196:199], v[208:211], v[46:49]
	v_mfma_f32_16x16x32_bf16 v[42:45], v[204:207], v[208:211], v[42:45]
	v_mfma_f32_16x16x32_bf16 v[38:41], v[196:199], v[216:219], v[38:41]
	v_mfma_f32_16x16x32_bf16 v[34:37], v[204:207], v[216:219], v[34:37]
	v_mfma_f32_16x16x32_bf16 v[122:125], v[200:203], v[78:81], v[86:89]
	v_mfma_f32_16x16x32_bf16 v[114:117], v[224:227], v[78:81], v[62:65]
	v_mfma_f32_16x16x32_bf16 v[110:113], v[200:203], v[192:195], v[54:57]
	v_mfma_f32_16x16x32_bf16 v[102:105], v[224:227], v[192:195], v[50:53]
	v_mfma_f32_16x16x32_bf16 v[94:97], v[200:203], v[212:215], v[46:49]
	v_mfma_f32_16x16x32_bf16 v[86:89], v[224:227], v[212:215], v[42:45]
	v_mfma_f32_16x16x32_bf16 v[78:81], v[200:203], v[220:223], v[38:41]
	v_mfma_f32_16x16x32_bf16 v[70:73], v[224:227], v[220:223], v[34:37]
	s_setprio 0
	s_barrier
	s_nop 0
	ds_read_b128 v[34:37], v141 offset:49152
	ds_read_b128 v[42:45], v141 offset:50176
	ds_read_b128 v[192:195], v141 offset:51200
	ds_read_b128 v[208:211], v141 offset:52224
	ds_read_b128 v[212:215], v141 offset:53248
	ds_read_b128 v[216:219], v141 offset:54272
	ds_read_b128 v[220:223], v141 offset:55296
	ds_read_b128 v[228:231], v141 offset:56320
	s_barrier
	s_waitcnt lgkmcnt(0)
	s_setprio 1
	s_waitcnt lgkmcnt(0)
	v_mfma_f32_16x16x32_bf16 v[30:33], v[176:179], v[34:37], v[30:33]
	v_mfma_f32_16x16x32_bf16 v[26:29], v[184:187], v[34:37], v[26:29]
	v_mfma_f32_16x16x32_bf16 v[22:25], v[176:179], v[192:195], v[22:25]
	v_mfma_f32_16x16x32_bf16 v[18:21], v[184:187], v[192:195], v[18:21]
	v_mfma_f32_16x16x32_bf16 v[14:17], v[176:179], v[212:215], v[14:17]
	v_mfma_f32_16x16x32_bf16 v[10:13], v[184:187], v[212:215], v[10:13]
	v_mfma_f32_16x16x32_bf16 v[6:9], v[176:179], v[220:223], v[6:9]
	v_mfma_f32_16x16x32_bf16 v[2:5], v[184:187], v[220:223], v[2:5]
	v_mfma_f32_16x16x32_bf16 v[62:65], v[180:183], v[42:45], v[30:33]
	v_mfma_f32_16x16x32_bf16 v[54:57], v[188:191], v[42:45], v[26:29]
	v_mfma_f32_16x16x32_bf16 v[46:49], v[180:183], v[208:211], v[22:25]
	v_mfma_f32_16x16x32_bf16 v[38:41], v[188:191], v[208:211], v[18:21]
	v_mfma_f32_16x16x32_bf16 v[30:33], v[180:183], v[216:219], v[14:17]
	v_mfma_f32_16x16x32_bf16 v[22:25], v[188:191], v[216:219], v[10:13]
	v_mfma_f32_16x16x32_bf16 v[14:17], v[180:183], v[228:231], v[6:9]
	v_mfma_f32_16x16x32_bf16 v[6:9], v[188:191], v[228:231], v[2:5]
	s_setprio 0
	s_setprio 1
	v_mfma_f32_16x16x32_bf16 v[2:5], v[196:199], v[34:37], v[58:61]
	v_mfma_f32_16x16x32_bf16 v[58:61], v[200:203], v[42:45], v[2:5]
	v_mfma_f32_16x16x32_bf16 v[2:5], v[204:207], v[34:37], v[144:147]
	v_mfma_f32_16x16x32_bf16 v[50:53], v[224:227], v[42:45], v[2:5]
	v_mfma_f32_16x16x32_bf16 v[2:5], v[196:199], v[192:195], v[148:151]
	v_mfma_f32_16x16x32_bf16 v[42:45], v[200:203], v[208:211], v[2:5]
	v_mfma_f32_16x16x32_bf16 v[2:5], v[204:207], v[192:195], v[156:159]
	v_mfma_f32_16x16x32_bf16 v[34:37], v[224:227], v[208:211], v[2:5]
	v_mfma_f32_16x16x32_bf16 v[2:5], v[196:199], v[212:215], v[160:163]
	v_mfma_f32_16x16x32_bf16 v[26:29], v[200:203], v[216:219], v[2:5]
	v_mfma_f32_16x16x32_bf16 v[2:5], v[204:207], v[212:215], v[164:167]
	v_mfma_f32_16x16x32_bf16 v[18:21], v[224:227], v[216:219], v[2:5]
	v_mfma_f32_16x16x32_bf16 v[2:5], v[196:199], v[220:223], v[168:171]
	v_mfma_f32_16x16x32_bf16 v[10:13], v[200:203], v[228:231], v[2:5]
	v_mfma_f32_16x16x32_bf16 v[2:5], v[204:207], v[220:223], v[172:175]
	v_mfma_f32_16x16x32_bf16 v[2:5], v[224:227], v[228:231], v[2:5]
	s_setprio 0
	s_barrier
	s_and_saveexec_b64 s[38:39], s[4:5]
	s_cbranch_execz .LBB0_1315
	s_barrier
